# strategy: deleted hipcc's 28 mid-cluster s_setprio 0/1 flips inside the GEMM MFMA clusters (outer raise/lower kept)
# baseline (speedup 1.0000x reference)
; #define PG8_STAGE(bufoff, gbase, voff) do { _Pragma("unroll") for (int _i = 0; _i < 2; ++_i) \
;         __builtin_amdgcn_global_load_lds((const unsigned*)((const char*)(gbase) + (voff)[_i]), (LAS unsigned*)(lds + (bufoff) + ldsw + _i * 8192), 16, 0, 0); } while (0)
; #define PG8_LDA(dst, b, h) do { _Pragma("unroll") for (int m = 0; m < 4; ++m) _Pragma("unroll") for (int k = 0; k < 2; ++k) dst[m][k] = *(const LAS bf16x8*)(lds + PG8_SA(b, h) + aoff + m * 2048 + k * 1024); } while (0)
; #define PG8_LDB(dst, b, h) do { _Pragma("unroll") for (int n = 0; n < 2; ++n) _Pragma("unroll") for (int k = 0; k < 2; ++k) dst[n][k] = *(const LAS bf16x8*)(lds + PG8_SB(b, h) + boff + n * 2048 + k * 1024); } while (0)
; #define PG8_MMA(ai, bj, At, Bt) do { __builtin_amdgcn_s_setprio(1); _Pragma("unroll") for (int m = 0; m < 4; ++m) _Pragma("unroll") for (int n = 0; n < 2; ++n) _Pragma("unroll") for (int k = 0; k < 2; ++k) \
;         acc[ai][bj][m][n] = __builtin_amdgcn_mfma_f32_16x16x32_bf16(Bt[n][k], At[m][k], acc[ai][bj][m][n], 0, 0, 0); __builtin_amdgcn_s_setprio(0); } while (0)
; #define PG8_WAIT_V(n) asm volatile("s_waitcnt vmcnt(" #n ")" ::: "memory")
; #define PG8_BAR __builtin_amdgcn_s_barrier()
; template <class Epi>
; __device__ __forceinline__ void gemm_phase(LAS unsigned char* lds, const Gemm g, const StaticOrder& S, const Epi& E, const int tid) {
;     ...
;         const char* nA = has_next ? (const char*)g.A + (size_t)nxt.pm * tstep : cA; const char* nB = has_next ? (const char*)g.Bt + (size_t)nxt.pn * tstep : cB;
;         for (int t = 0; t < nt; t += 2) {
;             const bool last = (t == nt - 2);
;             const char* a1 = cA + (size_t)(t + 1) * kstep;
;             const char* a2 = last ? nA : cA + (size_t)(t + 2) * kstep; const char* b2 = last ? nB : cB + (size_t)(t + 2) * kstep;
;             const char* a3 = a2 + kstep; const char* b3 = b2 + kstep;
;             PG8_LDB(B0, 0, 0); PG8_LDB(B1, 0, 1); PG8_SCHED; PG8_LDA(At, 0, 0); PG8_STAGE(PG8_SA(1, 1), a1 + hstep, voffA);
;             PG8_WAIT_V(8); PG8_WAIT_L(0); PG8_BAR; PG8_MMA(0, 0, At, B0); PG8_MMA(0, 1, At, B1); PG8_BAR; PG8_SCHED;
;             PG8_LDA(At, 0, 1); PG8_STAGE(PG8_SB(0, 0), b2, voffB); PG8_STAGE(PG8_SB(0, 1), b2 + hstep, voffB); PG8_STAGE(PG8_SA(0, 0), a2, voffA);
;             PG8_WAIT_V(8); PG8_WAIT_L(0); PG8_BAR; PG8_MMA(1, 0, At, B0); PG8_MMA(1, 1, At, B1); PG8_BAR; PG8_SCHED;
.LBB0_150:
	s_add_u32 s10, s62, 0xfff80080
	s_addc_u32 s11, s63, -1
	s_add_i32 s78, 0, 0x10000
	s_cmp_eq_u32 vcc_hi, 28
	s_cselect_b32 s67, s53, s11
	s_cselect_b32 s66, s95, s10
	v_add_u32_e32 v146, s78, v149
	s_cselect_b32 s65, s29, vcc_lo
	s_cselect_b32 s64, s96, s97
	s_add_i32 s46, 0, 0x14000
	ds_read_b128 v[152:155], v146
	ds_read_b128 v[156:159], v146 offset:1024
	ds_read_b128 v[160:163], v146 offset:2048
	ds_read_b128 v[164:167], v146 offset:3072
	v_add_u32_e32 v146, s46, v149
	ds_read_b128 v[172:175], v146
	ds_read_b128 v[178:181], v146 offset:1024
	ds_read_b128 v[182:185], v146 offset:2048
	ds_read_b128 v[186:189], v146 offset:3072
	v_lshl_add_u64 v[146:147], s[62:63], 0, v[142:143]
	s_add_i32 m0, s88, 0xc000
	ds_read_b128 v[190:193], v151
	ds_read_b128 v[194:197], v151 offset:1024
	ds_read_b128 v[198:201], v151 offset:2048
	ds_read_b128 v[202:205], v151 offset:3072
	ds_read_b128 v[206:209], v151 offset:4096
	ds_read_b128 v[210:213], v151 offset:5120
	ds_read_b128 v[214:217], v151 offset:6144
	ds_read_b128 v[218:221], v151 offset:7168
	global_load_lds_dwordx4 v[146:147], off
	v_lshl_add_u64 v[146:147], s[62:63], 0, v[140:141]
	s_add_i32 m0, s88, 0xe000
	s_nop 0
	global_load_lds_dwordx4 v[146:147], off
	s_waitcnt vmcnt(8)
	s_waitcnt lgkmcnt(0)
	s_barrier
	s_setprio 1
	s_waitcnt lgkmcnt(0)
	v_mfma_f32_16x16x32_bf16 v[124:127], v[152:155], v[190:193], v[124:127]
	v_mfma_f32_16x16x32_bf16 v[116:119], v[160:163], v[190:193], v[116:119]
	v_mfma_f32_16x16x32_bf16 v[108:111], v[152:155], v[198:201], v[108:111]
	v_mfma_f32_16x16x32_bf16 v[100:103], v[160:163], v[198:201], v[100:103]
	v_mfma_f32_16x16x32_bf16 v[92:95], v[152:155], v[206:209], v[92:95]
	v_mfma_f32_16x16x32_bf16 v[84:87], v[160:163], v[206:209], v[84:87]
	v_mfma_f32_16x16x32_bf16 v[76:79], v[152:155], v[214:217], v[76:79]
	v_mfma_f32_16x16x32_bf16 v[68:71], v[160:163], v[214:217], v[68:71]
	v_mfma_f32_16x16x32_bf16 v[124:127], v[156:159], v[194:197], v[124:127]
	v_mfma_f32_16x16x32_bf16 v[116:119], v[164:167], v[194:197], v[116:119]
	v_mfma_f32_16x16x32_bf16 v[108:111], v[156:159], v[202:205], v[108:111]
	v_mfma_f32_16x16x32_bf16 v[100:103], v[164:167], v[202:205], v[100:103]
	v_mfma_f32_16x16x32_bf16 v[92:95], v[156:159], v[210:213], v[92:95]
	v_mfma_f32_16x16x32_bf16 v[84:87], v[164:167], v[210:213], v[84:87]
	v_mfma_f32_16x16x32_bf16 v[76:79], v[156:159], v[218:221], v[76:79]
	v_mfma_f32_16x16x32_bf16 v[68:71], v[164:167], v[218:221], v[68:71]
	v_mfma_f32_16x16x32_bf16 v[120:123], v[172:175], v[190:193], v[120:123]
	v_mfma_f32_16x16x32_bf16 v[112:115], v[182:185], v[190:193], v[112:115]
	v_mfma_f32_16x16x32_bf16 v[104:107], v[172:175], v[198:201], v[104:107]
	v_mfma_f32_16x16x32_bf16 v[96:99], v[182:185], v[198:201], v[96:99]
	v_mfma_f32_16x16x32_bf16 v[88:91], v[172:175], v[206:209], v[88:91]
	v_mfma_f32_16x16x32_bf16 v[80:83], v[182:185], v[206:209], v[80:83]
	v_mfma_f32_16x16x32_bf16 v[72:75], v[172:175], v[214:217], v[72:75]
	v_mfma_f32_16x16x32_bf16 v[64:67], v[182:185], v[214:217], v[64:67]
	v_mfma_f32_16x16x32_bf16 v[120:123], v[178:181], v[194:197], v[120:123]
	v_mfma_f32_16x16x32_bf16 v[112:115], v[186:189], v[194:197], v[112:115]
	v_mfma_f32_16x16x32_bf16 v[104:107], v[178:181], v[202:205], v[104:107]
	v_mfma_f32_16x16x32_bf16 v[96:99], v[186:189], v[202:205], v[96:99]
	v_mfma_f32_16x16x32_bf16 v[88:91], v[178:181], v[210:213], v[88:91]
	v_mfma_f32_16x16x32_bf16 v[80:83], v[186:189], v[210:213], v[80:83]
	v_mfma_f32_16x16x32_bf16 v[72:75], v[178:181], v[218:221], v[72:75]
	v_mfma_f32_16x16x32_bf16 v[64:67], v[186:189], v[218:221], v[64:67]
	s_setprio 0
	s_barrier
	s_add_i32 s10, s78, s87
	v_lshl_add_u64 v[146:147], s[64:65], 0, v[128:129]
	s_mov_b32 m0, s10
	ds_read_b128 v[190:193], v151 offset:16384
	ds_read_b128 v[194:197], v151 offset:17408
	ds_read_b128 v[198:201], v151 offset:18432
	ds_read_b128 v[202:205], v151 offset:19456
	ds_read_b128 v[206:209], v151 offset:20480
	ds_read_b128 v[210:213], v151 offset:21504
	ds_read_b128 v[214:217], v151 offset:22528
	ds_read_b128 v[218:221], v151 offset:23552
	global_load_lds_dwordx4 v[146:147], off
	s_add_i32 m0, s10, 0x2000
	s_add_u32 s10, s64, 0x80000
	v_lshl_add_u64 v[168:169], s[64:65], 0, v[138:139]
	s_addc_u32 s11, s65, 0
	s_add_i32 s46, s46, s87
	global_load_lds_dwordx4 v[168:169], off
	v_lshl_add_u64 v[222:223], s[10:11], 0, v[128:129]
	s_mov_b32 m0, s46
	v_lshl_add_u64 v[226:227], s[66:67], 0, v[136:137]
	global_load_lds_dwordx4 v[222:223], off
	v_lshl_add_u64 v[222:223], s[10:11], 0, v[138:139]
	s_add_i32 m0, s46, 0x2000
	s_nop 0
	global_load_lds_dwordx4 v[222:223], off
	v_lshl_add_u64 v[222:223], s[66:67], 0, v[134:135]
	s_mov_b32 m0, s88
	s_nop 0
	global_load_lds_dwordx4 v[222:223], off
	s_mov_b32 m0, s89
	s_nop 0
	global_load_lds_dwordx4 v[226:227], off
	s_waitcnt vmcnt(8)
	s_waitcnt lgkmcnt(0)
	s_barrier
; #define PG8_STAGE(bufoff, gbase, voff) do { _Pragma("unroll") for (int _i = 0; _i < 2; ++_i) \
;         __builtin_amdgcn_global_load_lds((const unsigned*)((const char*)(gbase) + (voff)[_i]), (LAS unsigned*)(lds + (bufoff) + ldsw + _i * 8192), 16, 0, 0); } while (0)
; #define PG8_LDA(dst, b, h) do { _Pragma("unroll") for (int m = 0; m < 4; ++m) _Pragma("unroll") for (int k = 0; k < 2; ++k) dst[m][k] = *(const LAS bf16x8*)(lds + PG8_SA(b, h) + aoff + m * 2048 + k * 1024); } while (0)
; #define PG8_LDB(dst, b, h) do { _Pragma("unroll") for (int n = 0; n < 2; ++n) _Pragma("unroll") for (int k = 0; k < 2; ++k) dst[n][k] = *(const LAS bf16x8*)(lds + PG8_SB(b, h) + boff + n * 2048 + k * 1024); } while (0)
; #define PG8_MMA(ai, bj, At, Bt) do { __builtin_amdgcn_s_setprio(1); _Pragma("unroll") for (int m = 0; m < 4; ++m) _Pragma("unroll") for (int n = 0; n < 2; ++n) _Pragma("unroll") for (int k = 0; k < 2; ++k) \
;         acc[ai][bj][m][n] = __builtin_amdgcn_mfma_f32_16x16x32_bf16(Bt[n][k], At[m][k], acc[ai][bj][m][n], 0, 0, 0); __builtin_amdgcn_s_setprio(0); } while (0)
; #define PG8_WAIT_V(n) asm volatile("s_waitcnt vmcnt(" #n ")" ::: "memory")
; #define PG8_WAIT_L(n) asm volatile("s_waitcnt lgkmcnt(" #n ")" ::: "memory")
; #define PG8_BAR __builtin_amdgcn_s_barrier()
; #define PG8_SCHED __builtin_amdgcn_sched_barrier(0)
; template <class Epi>
; __device__ __forceinline__ void gemm_phase(LAS unsigned char* lds, const Gemm g, const StaticOrder& S, const Epi& E, const int tid) {
;     ...
;             PG8_WAIT_V(8); PG8_WAIT_L(0); PG8_BAR; PG8_MMA(1, 0, At, B0); PG8_MMA(1, 1, At, B1); PG8_BAR; PG8_SCHED;
;             PG8_LDB(B0, 1, 0); PG8_LDB(B1, 1, 1); PG8_SCHED; PG8_LDA(At, 1, 0); PG8_STAGE(PG8_SA(0, 1), a2 + hstep, voffA);
;             PG8_WAIT_V(8); PG8_WAIT_L(0); PG8_BAR; PG8_MMA(0, 0, At, B0); PG8_MMA(0, 1, At, B1); PG8_BAR; PG8_SCHED;
	s_setprio 1
	s_waitcnt lgkmcnt(0)
	v_mfma_f32_16x16x32_bf16 v[60:63], v[152:155], v[190:193], v[60:63]
	v_mfma_f32_16x16x32_bf16 v[52:55], v[160:163], v[190:193], v[52:55]
	v_mfma_f32_16x16x32_bf16 v[44:47], v[152:155], v[198:201], v[44:47]
	v_mfma_f32_16x16x32_bf16 v[36:39], v[160:163], v[198:201], v[36:39]
	v_mfma_f32_16x16x32_bf16 v[28:31], v[152:155], v[206:209], v[28:31]
	v_mfma_f32_16x16x32_bf16 v[20:23], v[160:163], v[206:209], v[20:23]
	v_mfma_f32_16x16x32_bf16 v[12:15], v[152:155], v[214:217], v[12:15]
	v_mfma_f32_16x16x32_bf16 v[4:7], v[160:163], v[214:217], v[4:7]
	v_mfma_f32_16x16x32_bf16 v[60:63], v[156:159], v[194:197], v[60:63]
	v_mfma_f32_16x16x32_bf16 v[52:55], v[164:167], v[194:197], v[52:55]
	v_mfma_f32_16x16x32_bf16 v[44:47], v[156:159], v[202:205], v[44:47]
	v_mfma_f32_16x16x32_bf16 v[36:39], v[164:167], v[202:205], v[36:39]
	v_mfma_f32_16x16x32_bf16 v[28:31], v[156:159], v[210:213], v[28:31]
	v_mfma_f32_16x16x32_bf16 v[20:23], v[164:167], v[210:213], v[20:23]
	v_mfma_f32_16x16x32_bf16 v[12:15], v[156:159], v[218:221], v[12:15]
	v_mfma_f32_16x16x32_bf16 v[4:7], v[164:167], v[218:221], v[4:7]
	v_mfma_f32_16x16x32_bf16 v[56:59], v[172:175], v[190:193], v[56:59]
	v_mfma_f32_16x16x32_bf16 v[48:51], v[182:185], v[190:193], v[48:51]
	v_mfma_f32_16x16x32_bf16 v[40:43], v[172:175], v[198:201], v[40:43]
	v_mfma_f32_16x16x32_bf16 v[32:35], v[182:185], v[198:201], v[32:35]
	v_mfma_f32_16x16x32_bf16 v[24:27], v[172:175], v[206:209], v[24:27]
	v_mfma_f32_16x16x32_bf16 v[16:19], v[182:185], v[206:209], v[16:19]
	v_mfma_f32_16x16x32_bf16 v[8:11], v[172:175], v[214:217], v[8:11]
	v_mfma_f32_16x16x32_bf16 v[0:3], v[182:185], v[214:217], v[0:3]
	v_mfma_f32_16x16x32_bf16 v[56:59], v[178:181], v[194:197], v[56:59]
	v_mfma_f32_16x16x32_bf16 v[48:51], v[186:189], v[194:197], v[48:51]
	v_mfma_f32_16x16x32_bf16 v[40:43], v[178:181], v[202:205], v[40:43]
	v_mfma_f32_16x16x32_bf16 v[32:35], v[186:189], v[202:205], v[32:35]
	v_mfma_f32_16x16x32_bf16 v[24:27], v[178:181], v[210:213], v[24:27]
	v_mfma_f32_16x16x32_bf16 v[16:19], v[186:189], v[210:213], v[16:19]
	v_mfma_f32_16x16x32_bf16 v[8:11], v[178:181], v[218:221], v[8:11]
	v_mfma_f32_16x16x32_bf16 v[0:3], v[186:189], v[218:221], v[0:3]
	s_setprio 0
	s_barrier
	s_add_i32 s46, 0, 0x18000
	s_add_i32 s47, 0, 0x1c000
	v_add_u32_e32 v164, s46, v149
	v_add_u32_e32 v170, s47, v149
	ds_read_b128 v[152:155], v164
	ds_read_b128 v[156:159], v164 offset:1024
	ds_read_b128 v[160:163], v164 offset:2048
	ds_read_b128 v[164:167], v164 offset:3072
	ds_read_b128 v[172:175], v170
	ds_read_b128 v[178:181], v170 offset:1024
	ds_read_b128 v[182:185], v170 offset:2048
	ds_read_b128 v[186:189], v170 offset:3072
	s_add_u32 s10, s66, 0x80000
	s_addc_u32 s11, s67, 0
	s_mov_b32 m0, s90
	v_lshl_add_u64 v[228:229], s[10:11], 0, v[134:135]
	ds_read_b128 v[190:193], v151 offset:32768
	ds_read_b128 v[194:197], v151 offset:33792
	ds_read_b128 v[198:201], v151 offset:34816
	ds_read_b128 v[202:205], v151 offset:35840
	ds_read_b128 v[206:209], v151 offset:36864
	ds_read_b128 v[210:213], v151 offset:37888
	ds_read_b128 v[214:217], v151 offset:38912
	ds_read_b128 v[218:221], v151 offset:39936
	global_load_lds_dwordx4 v[228:229], off
	v_lshl_add_u64 v[228:229], s[10:11], 0, v[136:137]
	s_mov_b32 m0, s91
	s_nop 0
	global_load_lds_dwordx4 v[228:229], off
	s_waitcnt vmcnt(8)
	s_waitcnt lgkmcnt(0)
	s_barrier
	s_setprio 1
	s_waitcnt lgkmcnt(0)
	v_mfma_f32_16x16x32_bf16 v[124:127], v[152:155], v[190:193], v[124:127]
	v_mfma_f32_16x16x32_bf16 v[116:119], v[160:163], v[190:193], v[116:119]
	v_mfma_f32_16x16x32_bf16 v[108:111], v[152:155], v[198:201], v[108:111]
	v_mfma_f32_16x16x32_bf16 v[100:103], v[160:163], v[198:201], v[100:103]
	v_mfma_f32_16x16x32_bf16 v[92:95], v[152:155], v[206:209], v[92:95]
	v_mfma_f32_16x16x32_bf16 v[84:87], v[160:163], v[206:209], v[84:87]
	v_mfma_f32_16x16x32_bf16 v[76:79], v[152:155], v[214:217], v[76:79]
	v_mfma_f32_16x16x32_bf16 v[68:71], v[160:163], v[214:217], v[68:71]
	v_mfma_f32_16x16x32_bf16 v[124:127], v[156:159], v[194:197], v[124:127]
	v_mfma_f32_16x16x32_bf16 v[116:119], v[164:167], v[194:197], v[116:119]
	v_mfma_f32_16x16x32_bf16 v[108:111], v[156:159], v[202:205], v[108:111]
	v_mfma_f32_16x16x32_bf16 v[100:103], v[164:167], v[202:205], v[100:103]
	v_mfma_f32_16x16x32_bf16 v[92:95], v[156:159], v[210:213], v[92:95]
	v_mfma_f32_16x16x32_bf16 v[84:87], v[164:167], v[210:213], v[84:87]
	v_mfma_f32_16x16x32_bf16 v[76:79], v[156:159], v[218:221], v[76:79]
	v_mfma_f32_16x16x32_bf16 v[68:71], v[164:167], v[218:221], v[68:71]
	v_mfma_f32_16x16x32_bf16 v[120:123], v[172:175], v[190:193], v[120:123]
	v_mfma_f32_16x16x32_bf16 v[112:115], v[182:185], v[190:193], v[112:115]
	v_mfma_f32_16x16x32_bf16 v[104:107], v[172:175], v[198:201], v[104:107]
	v_mfma_f32_16x16x32_bf16 v[96:99], v[182:185], v[198:201], v[96:99]
	v_mfma_f32_16x16x32_bf16 v[88:91], v[172:175], v[206:209], v[88:91]
	v_mfma_f32_16x16x32_bf16 v[80:83], v[182:185], v[206:209], v[80:83]
	v_mfma_f32_16x16x32_bf16 v[72:75], v[172:175], v[214:217], v[72:75]
	v_mfma_f32_16x16x32_bf16 v[64:67], v[182:185], v[214:217], v[64:67]
	v_mfma_f32_16x16x32_bf16 v[120:123], v[178:181], v[194:197], v[120:123]
	v_mfma_f32_16x16x32_bf16 v[112:115], v[186:189], v[194:197], v[112:115]
	v_mfma_f32_16x16x32_bf16 v[104:107], v[178:181], v[202:205], v[104:107]
	v_mfma_f32_16x16x32_bf16 v[96:99], v[186:189], v[202:205], v[96:99]
	v_mfma_f32_16x16x32_bf16 v[88:91], v[178:181], v[210:213], v[88:91]
	v_mfma_f32_16x16x32_bf16 v[80:83], v[186:189], v[210:213], v[80:83]
	v_mfma_f32_16x16x32_bf16 v[72:75], v[178:181], v[218:221], v[72:75]
	v_mfma_f32_16x16x32_bf16 v[64:67], v[186:189], v[218:221], v[64:67]
	s_setprio 0
	s_barrier
; #define PG8_STAGE(bufoff, gbase, voff) do { _Pragma("unroll") for (int _i = 0; _i < 2; ++_i) \
;         __builtin_amdgcn_global_load_lds((const unsigned*)((const char*)(gbase) + (voff)[_i]), (LAS unsigned*)(lds + (bufoff) + ldsw + _i * 8192), 16, 0, 0); } while (0)
; #define PG8_LDA(dst, b, h) do { _Pragma("unroll") for (int m = 0; m < 4; ++m) _Pragma("unroll") for (int k = 0; k < 2; ++k) dst[m][k] = *(const LAS bf16x8*)(lds + PG8_SA(b, h) + aoff + m * 2048 + k * 1024); } while (0)
; #define PG8_MMA(ai, bj, At, Bt) do { __builtin_amdgcn_s_setprio(1); _Pragma("unroll") for (int m = 0; m < 4; ++m) _Pragma("unroll") for (int n = 0; n < 2; ++n) _Pragma("unroll") for (int k = 0; k < 2; ++k) \
;         acc[ai][bj][m][n] = __builtin_amdgcn_mfma_f32_16x16x32_bf16(Bt[n][k], At[m][k], acc[ai][bj][m][n], 0, 0, 0); __builtin_amdgcn_s_setprio(0); } while (0)
; #define PG8_WAIT_V(n) asm volatile("s_waitcnt vmcnt(" #n ")" ::: "memory")
; #define PG8_WAIT_L(n) asm volatile("s_waitcnt lgkmcnt(" #n ")" ::: "memory")
; #define PG8_BAR __builtin_amdgcn_s_barrier()
; #define PG8_SCHED __builtin_amdgcn_sched_barrier(0)
; template <class Epi>
; __device__ __forceinline__ void gemm_phase(LAS unsigned char* lds, const Gemm g, const StaticOrder& S, const Epi& E, const int tid) {
;     ...
;             PG8_LDA(At, 1, 1); PG8_STAGE(PG8_SB(1, 0), b3, voffB); PG8_STAGE(PG8_SB(1, 1), b3 + hstep, voffB); PG8_STAGE(PG8_SA(1, 0), a3, voffA);
;             PG8_WAIT_V(8); PG8_WAIT_L(0); PG8_BAR; PG8_MMA(1, 0, At, B0); PG8_MMA(1, 1, At, B1); PG8_BAR; PG8_SCHED;
;         }
;         if (wr == 0) PG8_BAR;
	s_add_i32 s10, s46, s87
	v_lshl_add_u64 v[146:147], v[146:147], 0, s[8:9]
	s_mov_b32 m0, s10
	ds_read_b128 v[190:193], v151 offset:49152
	ds_read_b128 v[194:197], v151 offset:50176
	ds_read_b128 v[198:201], v151 offset:51200
	ds_read_b128 v[202:205], v151 offset:52224
	ds_read_b128 v[206:209], v151 offset:53248
	ds_read_b128 v[210:213], v151 offset:54272
	ds_read_b128 v[214:217], v151 offset:55296
	ds_read_b128 v[218:221], v151 offset:56320
	global_load_lds_dwordx4 v[146:147], off
	s_add_i32 m0, s10, 0x2000
	s_add_u32 s10, s64, 0x80080
	v_lshl_add_u64 v[146:147], v[168:169], 0, s[8:9]
	s_addc_u32 s11, s65, 0
	s_add_i32 s46, s47, s87
	global_load_lds_dwordx4 v[146:147], off
	v_lshl_add_u64 v[146:147], s[10:11], 0, v[128:129]
	s_mov_b32 m0, s46
	s_nop 0
	global_load_lds_dwordx4 v[146:147], off
	v_lshl_add_u64 v[146:147], s[10:11], 0, v[138:139]
	s_add_i32 m0, s46, 0x2000
	s_nop 0
	global_load_lds_dwordx4 v[146:147], off
	v_lshl_add_u64 v[146:147], v[222:223], 0, s[8:9]
	s_mov_b32 m0, s92
	s_nop 0
	global_load_lds_dwordx4 v[146:147], off
	v_lshl_add_u64 v[146:147], v[226:227], 0, s[8:9]
	s_mov_b32 m0, s93
	s_nop 0
	global_load_lds_dwordx4 v[146:147], off
	s_waitcnt vmcnt(8)
	s_waitcnt lgkmcnt(0)
	s_barrier
	s_setprio 1
	s_waitcnt lgkmcnt(0)
	v_mfma_f32_16x16x32_bf16 v[60:63], v[152:155], v[190:193], v[60:63]
	v_mfma_f32_16x16x32_bf16 v[52:55], v[160:163], v[190:193], v[52:55]
	v_mfma_f32_16x16x32_bf16 v[44:47], v[152:155], v[198:201], v[44:47]
	v_mfma_f32_16x16x32_bf16 v[36:39], v[160:163], v[198:201], v[36:39]
	v_mfma_f32_16x16x32_bf16 v[28:31], v[152:155], v[206:209], v[28:31]
	v_mfma_f32_16x16x32_bf16 v[20:23], v[160:163], v[206:209], v[20:23]
	v_mfma_f32_16x16x32_bf16 v[12:15], v[152:155], v[214:217], v[12:15]
	v_mfma_f32_16x16x32_bf16 v[4:7], v[160:163], v[214:217], v[4:7]
	v_mfma_f32_16x16x32_bf16 v[60:63], v[156:159], v[194:197], v[60:63]
	v_mfma_f32_16x16x32_bf16 v[52:55], v[164:167], v[194:197], v[52:55]
	v_mfma_f32_16x16x32_bf16 v[44:47], v[156:159], v[202:205], v[44:47]
	v_mfma_f32_16x16x32_bf16 v[36:39], v[164:167], v[202:205], v[36:39]
	v_mfma_f32_16x16x32_bf16 v[28:31], v[156:159], v[210:213], v[28:31]
	v_mfma_f32_16x16x32_bf16 v[20:23], v[164:167], v[210:213], v[20:23]
	v_mfma_f32_16x16x32_bf16 v[12:15], v[156:159], v[218:221], v[12:15]
	v_mfma_f32_16x16x32_bf16 v[4:7], v[164:167], v[218:221], v[4:7]
	v_mfma_f32_16x16x32_bf16 v[56:59], v[172:175], v[190:193], v[56:59]
	v_mfma_f32_16x16x32_bf16 v[48:51], v[182:185], v[190:193], v[48:51]
	v_mfma_f32_16x16x32_bf16 v[40:43], v[172:175], v[198:201], v[40:43]
	v_mfma_f32_16x16x32_bf16 v[32:35], v[182:185], v[198:201], v[32:35]
	v_mfma_f32_16x16x32_bf16 v[24:27], v[172:175], v[206:209], v[24:27]
	v_mfma_f32_16x16x32_bf16 v[16:19], v[182:185], v[206:209], v[16:19]
	v_mfma_f32_16x16x32_bf16 v[8:11], v[172:175], v[214:217], v[8:11]
	v_mfma_f32_16x16x32_bf16 v[0:3], v[182:185], v[214:217], v[0:3]
	v_mfma_f32_16x16x32_bf16 v[56:59], v[178:181], v[194:197], v[56:59]
	v_mfma_f32_16x16x32_bf16 v[48:51], v[186:189], v[194:197], v[48:51]
	v_mfma_f32_16x16x32_bf16 v[40:43], v[178:181], v[202:205], v[40:43]
	v_mfma_f32_16x16x32_bf16 v[32:35], v[186:189], v[202:205], v[32:35]
	v_mfma_f32_16x16x32_bf16 v[24:27], v[178:181], v[210:213], v[24:27]
	v_mfma_f32_16x16x32_bf16 v[16:19], v[186:189], v[210:213], v[16:19]
	v_mfma_f32_16x16x32_bf16 v[8:11], v[178:181], v[218:221], v[8:11]
	v_mfma_f32_16x16x32_bf16 v[0:3], v[186:189], v[218:221], v[0:3]
	s_setprio 0
	s_barrier
	s_add_i32 vcc_hi, vcc_hi, 2
	s_add_u32 s97, s97, 0x100
	s_addc_u32 vcc_lo, vcc_lo, 0
	s_add_u32 s62, s62, 0x100
	s_addc_u32 s63, s63, 0
	s_cmp_gt_u32 vcc_hi, 29
	s_cbranch_scc0 .LBB0_150
	s_and_b64 vcc, exec, s[26:27]
	s_cbranch_vccz .LBB0_153
	s_barrier

; #define PG8_STAGE(bufoff, gbase, voff) do { _Pragma("unroll") for (int _i = 0; _i < 2; ++_i) \
;         __builtin_amdgcn_global_load_lds((const unsigned*)((const char*)(gbase) + (voff)[_i]), (LAS unsigned*)(lds + (bufoff) + ldsw + _i * 8192), 16, 0, 0); } while (0)
; #define PG8_LDA(dst, b, h) do { _Pragma("unroll") for (int m = 0; m < 4; ++m) _Pragma("unroll") for (int k = 0; k < 2; ++k) dst[m][k] = *(const LAS bf16x8*)(lds + PG8_SA(b, h) + aoff + m * 2048 + k * 1024); } while (0)
; #define PG8_LDB(dst, b, h) do { _Pragma("unroll") for (int n = 0; n < 2; ++n) _Pragma("unroll") for (int k = 0; k < 2; ++k) dst[n][k] = *(const LAS bf16x8*)(lds + PG8_SB(b, h) + boff + n * 2048 + k * 1024); } while (0)
; #define PG8_MMA(ai, bj, At, Bt) do { __builtin_amdgcn_s_setprio(1); _Pragma("unroll") for (int m = 0; m < 4; ++m) _Pragma("unroll") for (int n = 0; n < 2; ++n) _Pragma("unroll") for (int k = 0; k < 2; ++k) \
;         acc[ai][bj][m][n] = __builtin_amdgcn_mfma_f32_16x16x32_bf16(Bt[n][k], At[m][k], acc[ai][bj][m][n], 0, 0, 0); __builtin_amdgcn_s_setprio(0); } while (0)
; #define PG8_WAIT_V(n) asm volatile("s_waitcnt vmcnt(" #n ")" ::: "memory")
; #define PG8_BAR __builtin_amdgcn_s_barrier()
; template <class Epi>
; __device__ __forceinline__ void gemm_phase(LAS unsigned char* lds, const Gemm g, const StaticOrder& S, const Epi& E, const int tid) {
;     ...
;         const char* nA = has_next ? (const char*)g.A + (size_t)nxt.pm * tstep : cA; const char* nB = has_next ? (const char*)g.Bt + (size_t)nxt.pn * tstep : cB;
;         for (int t = 0; t < nt; t += 2) {
;             const bool last = (t == nt - 2);
;             const char* a1 = cA + (size_t)(t + 1) * kstep;
;             const char* a2 = last ? nA : cA + (size_t)(t + 2) * kstep; const char* b2 = last ? nB : cB + (size_t)(t + 2) * kstep;
;             const char* a3 = a2 + kstep; const char* b3 = b2 + kstep;
;             PG8_LDB(B0, 0, 0); PG8_LDB(B1, 0, 1); PG8_SCHED; PG8_LDA(At, 0, 0); PG8_STAGE(PG8_SA(1, 1), a1 + hstep, voffA);
;             PG8_WAIT_V(8); PG8_WAIT_L(0); PG8_BAR; PG8_MMA(0, 0, At, B0); PG8_MMA(0, 1, At, B1); PG8_BAR; PG8_SCHED;
;             PG8_LDA(At, 0, 1); PG8_STAGE(PG8_SB(0, 0), b2, voffB); PG8_STAGE(PG8_SB(0, 1), b2 + hstep, voffB); PG8_STAGE(PG8_SA(0, 0), a2, voffA);
;             PG8_WAIT_V(8); PG8_WAIT_L(0); PG8_BAR; PG8_MMA(1, 0, At, B0); PG8_MMA(1, 1, At, B1); PG8_BAR; PG8_SCHED;
.LBB0_271:
	s_add_u32 s56, s52, 0x100
	s_addc_u32 s57, s53, 0
	s_add_i32 s10, 0, 0x10000
	s_cmpk_eq_i32 s90, 0x54
	s_cselect_b32 s61, s39, s57
	s_cselect_b32 s60, s38, s56
	v_add_u32_e32 v144, s10, v147
	s_cselect_b32 s59, s51, s89
	s_cselect_b32 s58, s50, s88
	s_add_i32 s46, 0, 0x14000
	ds_read_b128 v[150:153], v144
	ds_read_b128 v[154:157], v144 offset:1024
	ds_read_b128 v[158:161], v144 offset:2048
	ds_read_b128 v[162:165], v144 offset:3072
	v_add_u32_e32 v144, s46, v147
	ds_read_b128 v[166:169], v144
	ds_read_b128 v[172:175], v144 offset:1024
	ds_read_b128 v[178:181], v144 offset:2048
	ds_read_b128 v[182:185], v144 offset:3072
	v_lshl_add_u64 v[144:145], s[52:53], 0, v[142:143]
	s_add_i32 m0, s67, 0xc000
	ds_read_b128 v[186:189], v149
	ds_read_b128 v[190:193], v149 offset:1024
	ds_read_b128 v[194:197], v149 offset:2048
	ds_read_b128 v[198:201], v149 offset:3072
	ds_read_b128 v[202:205], v149 offset:4096
	ds_read_b128 v[206:209], v149 offset:5120
	ds_read_b128 v[210:213], v149 offset:6144
	ds_read_b128 v[214:217], v149 offset:7168
	global_load_lds_dwordx4 v[144:145], off
	v_lshl_add_u64 v[144:145], s[52:53], 0, v[140:141]
	s_add_i32 m0, s67, 0xe000
	s_nop 0
	global_load_lds_dwordx4 v[144:145], off
	s_waitcnt vmcnt(8)
	s_waitcnt lgkmcnt(0)
	s_barrier
	s_setprio 1
	s_waitcnt lgkmcnt(0)
	v_mfma_f32_16x16x32_bf16 v[124:127], v[150:153], v[186:189], v[124:127]
	v_mfma_f32_16x16x32_bf16 v[120:123], v[158:161], v[186:189], v[120:123]
	v_mfma_f32_16x16x32_bf16 v[116:119], v[150:153], v[194:197], v[116:119]
	v_mfma_f32_16x16x32_bf16 v[108:111], v[158:161], v[194:197], v[108:111]
	v_mfma_f32_16x16x32_bf16 v[100:103], v[150:153], v[202:205], v[100:103]
	v_mfma_f32_16x16x32_bf16 v[92:95], v[158:161], v[202:205], v[92:95]
	v_mfma_f32_16x16x32_bf16 v[84:87], v[150:153], v[210:213], v[84:87]
	v_mfma_f32_16x16x32_bf16 v[76:79], v[158:161], v[210:213], v[76:79]
	v_mfma_f32_16x16x32_bf16 v[124:127], v[154:157], v[190:193], v[124:127]
	v_mfma_f32_16x16x32_bf16 v[120:123], v[162:165], v[190:193], v[120:123]
	v_mfma_f32_16x16x32_bf16 v[116:119], v[154:157], v[198:201], v[116:119]
	v_mfma_f32_16x16x32_bf16 v[108:111], v[162:165], v[198:201], v[108:111]
	v_mfma_f32_16x16x32_bf16 v[100:103], v[154:157], v[206:209], v[100:103]
	v_mfma_f32_16x16x32_bf16 v[92:95], v[162:165], v[206:209], v[92:95]
	v_mfma_f32_16x16x32_bf16 v[84:87], v[154:157], v[214:217], v[84:87]
	v_mfma_f32_16x16x32_bf16 v[76:79], v[162:165], v[214:217], v[76:79]
	v_mfma_f32_16x16x32_bf16 v[112:115], v[166:169], v[186:189], v[112:115]
	v_mfma_f32_16x16x32_bf16 v[104:107], v[178:181], v[186:189], v[104:107]
	v_mfma_f32_16x16x32_bf16 v[96:99], v[166:169], v[194:197], v[96:99]
	v_mfma_f32_16x16x32_bf16 v[88:91], v[178:181], v[194:197], v[88:91]
	v_mfma_f32_16x16x32_bf16 v[80:83], v[166:169], v[202:205], v[80:83]
	v_mfma_f32_16x16x32_bf16 v[72:75], v[178:181], v[202:205], v[72:75]
	v_mfma_f32_16x16x32_bf16 v[68:71], v[166:169], v[210:213], v[68:71]
	v_mfma_f32_16x16x32_bf16 v[64:67], v[178:181], v[210:213], v[64:67]
	v_mfma_f32_16x16x32_bf16 v[112:115], v[172:175], v[190:193], v[112:115]
	v_mfma_f32_16x16x32_bf16 v[104:107], v[182:185], v[190:193], v[104:107]
	v_mfma_f32_16x16x32_bf16 v[96:99], v[172:175], v[198:201], v[96:99]
	v_mfma_f32_16x16x32_bf16 v[88:91], v[182:185], v[198:201], v[88:91]
	v_mfma_f32_16x16x32_bf16 v[80:83], v[172:175], v[206:209], v[80:83]
	v_mfma_f32_16x16x32_bf16 v[72:75], v[182:185], v[206:209], v[72:75]
	v_mfma_f32_16x16x32_bf16 v[68:71], v[172:175], v[214:217], v[68:71]
	v_mfma_f32_16x16x32_bf16 v[64:67], v[182:185], v[214:217], v[64:67]
	s_setprio 0
	s_barrier
	s_add_i32 s10, s10, s66
	v_lshl_add_u64 v[144:145], s[58:59], 0, v[128:129]
	s_mov_b32 m0, s10
	ds_read_b128 v[186:189], v149 offset:16384
	ds_read_b128 v[190:193], v149 offset:17408
	ds_read_b128 v[194:197], v149 offset:18432
	ds_read_b128 v[198:201], v149 offset:19456
	ds_read_b128 v[202:205], v149 offset:20480
	ds_read_b128 v[206:209], v149 offset:21504
	ds_read_b128 v[210:213], v149 offset:22528
	ds_read_b128 v[214:217], v149 offset:23552
	global_load_lds_dwordx4 v[144:145], off
	s_add_i32 m0, s10, 0x2000
	s_add_u32 s10, s58, 0x160000
	v_lshl_add_u64 v[218:219], s[58:59], 0, v[134:135]
	s_addc_u32 s11, s59, 0
	s_add_i32 s46, s46, s66
	global_load_lds_dwordx4 v[218:219], off
	v_lshl_add_u64 v[220:221], s[10:11], 0, v[128:129]
	s_mov_b32 m0, s46
	v_lshl_add_u64 v[222:223], s[60:61], 0, v[136:137]
	global_load_lds_dwordx4 v[220:221], off
	v_lshl_add_u64 v[220:221], s[10:11], 0, v[134:135]
	s_add_i32 m0, s46, 0x2000
	s_nop 0
	global_load_lds_dwordx4 v[220:221], off
	v_lshl_add_u64 v[220:221], s[60:61], 0, v[138:139]
	s_mov_b32 m0, s67
	s_nop 0
	global_load_lds_dwordx4 v[220:221], off
	s_mov_b32 m0, s68
	s_nop 0
	global_load_lds_dwordx4 v[222:223], off
	s_waitcnt vmcnt(8)
	s_waitcnt lgkmcnt(0)
	s_barrier
; #define PG8_STAGE(bufoff, gbase, voff) do { _Pragma("unroll") for (int _i = 0; _i < 2; ++_i) \
;         __builtin_amdgcn_global_load_lds((const unsigned*)((const char*)(gbase) + (voff)[_i]), (LAS unsigned*)(lds + (bufoff) + ldsw + _i * 8192), 16, 0, 0); } while (0)
; #define PG8_LDA(dst, b, h) do { _Pragma("unroll") for (int m = 0; m < 4; ++m) _Pragma("unroll") for (int k = 0; k < 2; ++k) dst[m][k] = *(const LAS bf16x8*)(lds + PG8_SA(b, h) + aoff + m * 2048 + k * 1024); } while (0)
; #define PG8_LDB(dst, b, h) do { _Pragma("unroll") for (int n = 0; n < 2; ++n) _Pragma("unroll") for (int k = 0; k < 2; ++k) dst[n][k] = *(const LAS bf16x8*)(lds + PG8_SB(b, h) + boff + n * 2048 + k * 1024); } while (0)
; #define PG8_MMA(ai, bj, At, Bt) do { __builtin_amdgcn_s_setprio(1); _Pragma("unroll") for (int m = 0; m < 4; ++m) _Pragma("unroll") for (int n = 0; n < 2; ++n) _Pragma("unroll") for (int k = 0; k < 2; ++k) \
;         acc[ai][bj][m][n] = __builtin_amdgcn_mfma_f32_16x16x32_bf16(Bt[n][k], At[m][k], acc[ai][bj][m][n], 0, 0, 0); __builtin_amdgcn_s_setprio(0); } while (0)
; #define PG8_WAIT_V(n) asm volatile("s_waitcnt vmcnt(" #n ")" ::: "memory")
; #define PG8_WAIT_L(n) asm volatile("s_waitcnt lgkmcnt(" #n ")" ::: "memory")
; #define PG8_BAR __builtin_amdgcn_s_barrier()
; #define PG8_SCHED __builtin_amdgcn_sched_barrier(0)
; template <class Epi>
; __device__ __forceinline__ void gemm_phase(LAS unsigned char* lds, const Gemm g, const StaticOrder& S, const Epi& E, const int tid) {
;     ...
;             PG8_WAIT_V(8); PG8_WAIT_L(0); PG8_BAR; PG8_MMA(1, 0, At, B0); PG8_MMA(1, 1, At, B1); PG8_BAR; PG8_SCHED;
;             PG8_LDB(B0, 1, 0); PG8_LDB(B1, 1, 1); PG8_SCHED; PG8_LDA(At, 1, 0); PG8_STAGE(PG8_SA(0, 1), a2 + hstep, voffA);
;             PG8_WAIT_V(8); PG8_WAIT_L(0); PG8_BAR; PG8_MMA(0, 0, At, B0); PG8_MMA(0, 1, At, B1); PG8_BAR; PG8_SCHED;
	s_setprio 1
	s_waitcnt lgkmcnt(0)
	v_mfma_f32_16x16x32_bf16 v[60:63], v[150:153], v[186:189], v[60:63]
	v_mfma_f32_16x16x32_bf16 v[56:59], v[158:161], v[186:189], v[56:59]
	v_mfma_f32_16x16x32_bf16 v[52:55], v[150:153], v[194:197], v[52:55]
	v_mfma_f32_16x16x32_bf16 v[44:47], v[158:161], v[194:197], v[44:47]
	v_mfma_f32_16x16x32_bf16 v[36:39], v[150:153], v[202:205], v[36:39]
	v_mfma_f32_16x16x32_bf16 v[28:31], v[158:161], v[202:205], v[28:31]
	v_mfma_f32_16x16x32_bf16 v[20:23], v[150:153], v[210:213], v[20:23]
	v_mfma_f32_16x16x32_bf16 v[12:15], v[158:161], v[210:213], v[12:15]
	v_mfma_f32_16x16x32_bf16 v[60:63], v[154:157], v[190:193], v[60:63]
	v_mfma_f32_16x16x32_bf16 v[56:59], v[162:165], v[190:193], v[56:59]
	v_mfma_f32_16x16x32_bf16 v[52:55], v[154:157], v[198:201], v[52:55]
	v_mfma_f32_16x16x32_bf16 v[44:47], v[162:165], v[198:201], v[44:47]
	v_mfma_f32_16x16x32_bf16 v[36:39], v[154:157], v[206:209], v[36:39]
	v_mfma_f32_16x16x32_bf16 v[28:31], v[162:165], v[206:209], v[28:31]
	v_mfma_f32_16x16x32_bf16 v[20:23], v[154:157], v[214:217], v[20:23]
	v_mfma_f32_16x16x32_bf16 v[12:15], v[162:165], v[214:217], v[12:15]
	v_mfma_f32_16x16x32_bf16 v[48:51], v[166:169], v[186:189], v[48:51]
	v_mfma_f32_16x16x32_bf16 v[40:43], v[178:181], v[186:189], v[40:43]
	v_mfma_f32_16x16x32_bf16 v[32:35], v[166:169], v[194:197], v[32:35]
	v_mfma_f32_16x16x32_bf16 v[24:27], v[178:181], v[194:197], v[24:27]
	v_mfma_f32_16x16x32_bf16 v[16:19], v[166:169], v[202:205], v[16:19]
	v_mfma_f32_16x16x32_bf16 v[8:11], v[178:181], v[202:205], v[8:11]
	v_mfma_f32_16x16x32_bf16 v[4:7], v[166:169], v[210:213], v[4:7]
	v_mfma_f32_16x16x32_bf16 v[0:3], v[178:181], v[210:213], v[0:3]
	v_mfma_f32_16x16x32_bf16 v[48:51], v[172:175], v[190:193], v[48:51]
	v_mfma_f32_16x16x32_bf16 v[40:43], v[182:185], v[190:193], v[40:43]
	v_mfma_f32_16x16x32_bf16 v[32:35], v[172:175], v[198:201], v[32:35]
	v_mfma_f32_16x16x32_bf16 v[24:27], v[182:185], v[198:201], v[24:27]
	v_mfma_f32_16x16x32_bf16 v[16:19], v[172:175], v[206:209], v[16:19]
	v_mfma_f32_16x16x32_bf16 v[8:11], v[182:185], v[206:209], v[8:11]
	v_mfma_f32_16x16x32_bf16 v[4:7], v[172:175], v[214:217], v[4:7]
	v_mfma_f32_16x16x32_bf16 v[0:3], v[182:185], v[214:217], v[0:3]
	s_setprio 0
	s_barrier
	s_add_i32 s46, 0, 0x18000
	s_add_i32 s47, 0, 0x1c000
	v_add_u32_e32 v162, s46, v147
	v_add_u32_e32 v170, s47, v147
	ds_read_b128 v[150:153], v162
	ds_read_b128 v[154:157], v162 offset:1024
	ds_read_b128 v[158:161], v162 offset:2048
	ds_read_b128 v[162:165], v162 offset:3072
	ds_read_b128 v[166:169], v170
	ds_read_b128 v[172:175], v170 offset:1024
	ds_read_b128 v[178:181], v170 offset:2048
	ds_read_b128 v[182:185], v170 offset:3072
	s_add_u32 s10, s60, 0x160000
	s_addc_u32 s11, s61, 0
	s_mov_b32 m0, s69
	v_lshl_add_u64 v[226:227], s[10:11], 0, v[138:139]
	ds_read_b128 v[186:189], v149 offset:32768
	ds_read_b128 v[190:193], v149 offset:33792
	ds_read_b128 v[194:197], v149 offset:34816
	ds_read_b128 v[198:201], v149 offset:35840
	ds_read_b128 v[202:205], v149 offset:36864
	ds_read_b128 v[206:209], v149 offset:37888
	ds_read_b128 v[210:213], v149 offset:38912
	ds_read_b128 v[214:217], v149 offset:39936
	global_load_lds_dwordx4 v[226:227], off
	v_lshl_add_u64 v[226:227], s[10:11], 0, v[136:137]
	s_mov_b32 m0, s80
	s_nop 0
	global_load_lds_dwordx4 v[226:227], off
	s_waitcnt vmcnt(8)
	s_waitcnt lgkmcnt(0)
	s_barrier
	s_setprio 1
	s_waitcnt lgkmcnt(0)
	v_mfma_f32_16x16x32_bf16 v[124:127], v[150:153], v[186:189], v[124:127]
	v_mfma_f32_16x16x32_bf16 v[120:123], v[158:161], v[186:189], v[120:123]
	v_mfma_f32_16x16x32_bf16 v[116:119], v[150:153], v[194:197], v[116:119]
	v_mfma_f32_16x16x32_bf16 v[108:111], v[158:161], v[194:197], v[108:111]
	v_mfma_f32_16x16x32_bf16 v[100:103], v[150:153], v[202:205], v[100:103]
	v_mfma_f32_16x16x32_bf16 v[92:95], v[158:161], v[202:205], v[92:95]
	v_mfma_f32_16x16x32_bf16 v[84:87], v[150:153], v[210:213], v[84:87]
	v_mfma_f32_16x16x32_bf16 v[76:79], v[158:161], v[210:213], v[76:79]
	v_mfma_f32_16x16x32_bf16 v[124:127], v[154:157], v[190:193], v[124:127]
	v_mfma_f32_16x16x32_bf16 v[120:123], v[162:165], v[190:193], v[120:123]
	v_mfma_f32_16x16x32_bf16 v[116:119], v[154:157], v[198:201], v[116:119]
	v_mfma_f32_16x16x32_bf16 v[108:111], v[162:165], v[198:201], v[108:111]
	v_mfma_f32_16x16x32_bf16 v[100:103], v[154:157], v[206:209], v[100:103]
	v_mfma_f32_16x16x32_bf16 v[92:95], v[162:165], v[206:209], v[92:95]
	v_mfma_f32_16x16x32_bf16 v[84:87], v[154:157], v[214:217], v[84:87]
	v_mfma_f32_16x16x32_bf16 v[76:79], v[162:165], v[214:217], v[76:79]
	v_mfma_f32_16x16x32_bf16 v[112:115], v[166:169], v[186:189], v[112:115]
	v_mfma_f32_16x16x32_bf16 v[104:107], v[178:181], v[186:189], v[104:107]
	v_mfma_f32_16x16x32_bf16 v[96:99], v[166:169], v[194:197], v[96:99]
	v_mfma_f32_16x16x32_bf16 v[88:91], v[178:181], v[194:197], v[88:91]
	v_mfma_f32_16x16x32_bf16 v[80:83], v[166:169], v[202:205], v[80:83]
	v_mfma_f32_16x16x32_bf16 v[72:75], v[178:181], v[202:205], v[72:75]
	v_mfma_f32_16x16x32_bf16 v[68:71], v[166:169], v[210:213], v[68:71]
	v_mfma_f32_16x16x32_bf16 v[64:67], v[178:181], v[210:213], v[64:67]
	v_mfma_f32_16x16x32_bf16 v[112:115], v[172:175], v[190:193], v[112:115]
	v_mfma_f32_16x16x32_bf16 v[104:107], v[182:185], v[190:193], v[104:107]
	v_mfma_f32_16x16x32_bf16 v[96:99], v[172:175], v[198:201], v[96:99]
	v_mfma_f32_16x16x32_bf16 v[88:91], v[182:185], v[198:201], v[88:91]
	v_mfma_f32_16x16x32_bf16 v[80:83], v[172:175], v[206:209], v[80:83]
	v_mfma_f32_16x16x32_bf16 v[72:75], v[182:185], v[206:209], v[72:75]
	v_mfma_f32_16x16x32_bf16 v[68:71], v[172:175], v[214:217], v[68:71]
	v_mfma_f32_16x16x32_bf16 v[64:67], v[182:185], v[214:217], v[64:67]
	s_setprio 0
	s_barrier
; #define PG8_STAGE(bufoff, gbase, voff) do { _Pragma("unroll") for (int _i = 0; _i < 2; ++_i) \
;         __builtin_amdgcn_global_load_lds((const unsigned*)((const char*)(gbase) + (voff)[_i]), (LAS unsigned*)(lds + (bufoff) + ldsw + _i * 8192), 16, 0, 0); } while (0)
; #define PG8_LDA(dst, b, h) do { _Pragma("unroll") for (int m = 0; m < 4; ++m) _Pragma("unroll") for (int k = 0; k < 2; ++k) dst[m][k] = *(const LAS bf16x8*)(lds + PG8_SA(b, h) + aoff + m * 2048 + k * 1024); } while (0)
; #define PG8_MMA(ai, bj, At, Bt) do { __builtin_amdgcn_s_setprio(1); _Pragma("unroll") for (int m = 0; m < 4; ++m) _Pragma("unroll") for (int n = 0; n < 2; ++n) _Pragma("unroll") for (int k = 0; k < 2; ++k) \
;         acc[ai][bj][m][n] = __builtin_amdgcn_mfma_f32_16x16x32_bf16(Bt[n][k], At[m][k], acc[ai][bj][m][n], 0, 0, 0); __builtin_amdgcn_s_setprio(0); } while (0)
; #define PG8_WAIT_V(n) asm volatile("s_waitcnt vmcnt(" #n ")" ::: "memory")
; #define PG8_WAIT_L(n) asm volatile("s_waitcnt lgkmcnt(" #n ")" ::: "memory")
; #define PG8_BAR __builtin_amdgcn_s_barrier()
; #define PG8_SCHED __builtin_amdgcn_sched_barrier(0)
; template <class Epi>
; __device__ __forceinline__ void gemm_phase(LAS unsigned char* lds, const Gemm g, const StaticOrder& S, const Epi& E, const int tid) {
;     ...
;             PG8_LDA(At, 1, 1); PG8_STAGE(PG8_SB(1, 0), b3, voffB); PG8_STAGE(PG8_SB(1, 1), b3 + hstep, voffB); PG8_STAGE(PG8_SA(1, 0), a3, voffA);
;             PG8_WAIT_V(8); PG8_WAIT_L(0); PG8_BAR; PG8_MMA(1, 0, At, B0); PG8_MMA(1, 1, At, B1); PG8_BAR; PG8_SCHED;
;         }
;         if (wr == 0) PG8_BAR;
	s_add_i32 s10, s46, s66
	v_lshl_add_u64 v[144:145], v[144:145], 0, s[8:9]
	s_mov_b32 m0, s10
	ds_read_b128 v[186:189], v149 offset:49152
	ds_read_b128 v[190:193], v149 offset:50176
	ds_read_b128 v[194:197], v149 offset:51200
	ds_read_b128 v[198:201], v149 offset:52224
	ds_read_b128 v[202:205], v149 offset:53248
	ds_read_b128 v[206:209], v149 offset:54272
	ds_read_b128 v[210:213], v149 offset:55296
	ds_read_b128 v[214:217], v149 offset:56320
	global_load_lds_dwordx4 v[144:145], off
	s_add_i32 m0, s10, 0x2000
	s_add_u32 s10, s58, 0x160080
	v_lshl_add_u64 v[144:145], v[218:219], 0, s[8:9]
	s_addc_u32 s11, s59, 0
	s_add_i32 s46, s47, s66
	global_load_lds_dwordx4 v[144:145], off
	v_lshl_add_u64 v[144:145], s[10:11], 0, v[128:129]
	s_mov_b32 m0, s46
	s_nop 0
	global_load_lds_dwordx4 v[144:145], off
	v_lshl_add_u64 v[144:145], s[10:11], 0, v[134:135]
	s_add_i32 m0, s46, 0x2000
	s_nop 0
	global_load_lds_dwordx4 v[144:145], off
	v_lshl_add_u64 v[144:145], v[220:221], 0, s[8:9]
	s_mov_b32 m0, s81
	s_nop 0
	global_load_lds_dwordx4 v[144:145], off
	v_lshl_add_u64 v[144:145], v[222:223], 0, s[8:9]
	s_mov_b32 m0, s82
	s_nop 0
	global_load_lds_dwordx4 v[144:145], off
	s_waitcnt vmcnt(8)
	s_waitcnt lgkmcnt(0)
	s_barrier
	s_setprio 1
	s_waitcnt lgkmcnt(0)
	v_mfma_f32_16x16x32_bf16 v[60:63], v[150:153], v[186:189], v[60:63]
	v_mfma_f32_16x16x32_bf16 v[56:59], v[158:161], v[186:189], v[56:59]
	v_mfma_f32_16x16x32_bf16 v[52:55], v[150:153], v[194:197], v[52:55]
	v_mfma_f32_16x16x32_bf16 v[44:47], v[158:161], v[194:197], v[44:47]
	v_mfma_f32_16x16x32_bf16 v[36:39], v[150:153], v[202:205], v[36:39]
	v_mfma_f32_16x16x32_bf16 v[28:31], v[158:161], v[202:205], v[28:31]
	v_mfma_f32_16x16x32_bf16 v[20:23], v[150:153], v[210:213], v[20:23]
	v_mfma_f32_16x16x32_bf16 v[12:15], v[158:161], v[210:213], v[12:15]
	v_mfma_f32_16x16x32_bf16 v[60:63], v[154:157], v[190:193], v[60:63]
	v_mfma_f32_16x16x32_bf16 v[56:59], v[162:165], v[190:193], v[56:59]
	v_mfma_f32_16x16x32_bf16 v[52:55], v[154:157], v[198:201], v[52:55]
	v_mfma_f32_16x16x32_bf16 v[44:47], v[162:165], v[198:201], v[44:47]
	v_mfma_f32_16x16x32_bf16 v[36:39], v[154:157], v[206:209], v[36:39]
	v_mfma_f32_16x16x32_bf16 v[28:31], v[162:165], v[206:209], v[28:31]
	v_mfma_f32_16x16x32_bf16 v[20:23], v[154:157], v[214:217], v[20:23]
	v_mfma_f32_16x16x32_bf16 v[12:15], v[162:165], v[214:217], v[12:15]
	v_mfma_f32_16x16x32_bf16 v[48:51], v[166:169], v[186:189], v[48:51]
	v_mfma_f32_16x16x32_bf16 v[40:43], v[178:181], v[186:189], v[40:43]
	v_mfma_f32_16x16x32_bf16 v[32:35], v[166:169], v[194:197], v[32:35]
	v_mfma_f32_16x16x32_bf16 v[24:27], v[178:181], v[194:197], v[24:27]
	v_mfma_f32_16x16x32_bf16 v[16:19], v[166:169], v[202:205], v[16:19]
	v_mfma_f32_16x16x32_bf16 v[8:11], v[178:181], v[202:205], v[8:11]
	v_mfma_f32_16x16x32_bf16 v[4:7], v[166:169], v[210:213], v[4:7]
	v_mfma_f32_16x16x32_bf16 v[0:3], v[178:181], v[210:213], v[0:3]
	v_mfma_f32_16x16x32_bf16 v[48:51], v[172:175], v[190:193], v[48:51]
	v_mfma_f32_16x16x32_bf16 v[40:43], v[182:185], v[190:193], v[40:43]
	v_mfma_f32_16x16x32_bf16 v[32:35], v[172:175], v[198:201], v[32:35]
	v_mfma_f32_16x16x32_bf16 v[24:27], v[182:185], v[198:201], v[24:27]
	v_mfma_f32_16x16x32_bf16 v[16:19], v[172:175], v[206:209], v[16:19]
	v_mfma_f32_16x16x32_bf16 v[8:11], v[182:185], v[206:209], v[8:11]
	v_mfma_f32_16x16x32_bf16 v[4:7], v[172:175], v[214:217], v[4:7]
	v_mfma_f32_16x16x32_bf16 v[0:3], v[182:185], v[214:217], v[0:3]
	s_setprio 0
	s_barrier
	s_add_i32 s90, s90, 2
	s_add_u32 s88, s88, 0x100
	s_addc_u32 s89, s89, 0
	s_cmpk_gt_u32 s90, 0x55
	s_mov_b64 s[52:53], s[56:57]
	s_cbranch_scc0 .LBB0_271
	s_and_b64 vcc, exec, s[28:29]
	s_cbranch_vccz .LBB0_274
	s_barrier

; #define PG8_STAGE(bufoff, gbase, voff) do { _Pragma("unroll") for (int _i = 0; _i < 2; ++_i) \
;         __builtin_amdgcn_global_load_lds((const unsigned*)((const char*)(gbase) + (voff)[_i]), (LAS unsigned*)(lds + (bufoff) + ldsw + _i * 8192), 16, 0, 0); } while (0)
; #define PG8_LDA(dst, b, h) do { _Pragma("unroll") for (int m = 0; m < 4; ++m) _Pragma("unroll") for (int k = 0; k < 2; ++k) dst[m][k] = *(const LAS bf16x8*)(lds + PG8_SA(b, h) + aoff + m * 2048 + k * 1024); } while (0)
; #define PG8_LDB(dst, b, h) do { _Pragma("unroll") for (int n = 0; n < 2; ++n) _Pragma("unroll") for (int k = 0; k < 2; ++k) dst[n][k] = *(const LAS bf16x8*)(lds + PG8_SB(b, h) + boff + n * 2048 + k * 1024); } while (0)
; #define PG8_MMA(ai, bj, At, Bt) do { __builtin_amdgcn_s_setprio(1); _Pragma("unroll") for (int m = 0; m < 4; ++m) _Pragma("unroll") for (int n = 0; n < 2; ++n) _Pragma("unroll") for (int k = 0; k < 2; ++k) \
;         acc[ai][bj][m][n] = __builtin_amdgcn_mfma_f32_16x16x32_bf16(Bt[n][k], At[m][k], acc[ai][bj][m][n], 0, 0, 0); __builtin_amdgcn_s_setprio(0); } while (0)
; #define PG8_WAIT_V(n) asm volatile("s_waitcnt vmcnt(" #n ")" ::: "memory")
; #define PG8_BAR __builtin_amdgcn_s_barrier()
; template <class Epi>
; __device__ __forceinline__ void gemm_phase(LAS unsigned char* lds, const Gemm g, const StaticOrder& S, const Epi& E, const int tid) {
;     ...
;         const char* nA = has_next ? (const char*)g.A + (size_t)nxt.pm * tstep : cA; const char* nB = has_next ? (const char*)g.Bt + (size_t)nxt.pn * tstep : cB;
;         for (int t = 0; t < nt; t += 2) {
;             const bool last = (t == nt - 2);
;             const char* a1 = cA + (size_t)(t + 1) * kstep;
;             const char* a2 = last ? nA : cA + (size_t)(t + 2) * kstep; const char* b2 = last ? nB : cB + (size_t)(t + 2) * kstep;
;             const char* a3 = a2 + kstep; const char* b3 = b2 + kstep;
;             PG8_LDB(B0, 0, 0); PG8_LDB(B1, 0, 1); PG8_SCHED; PG8_LDA(At, 0, 0); PG8_STAGE(PG8_SA(1, 1), a1 + hstep, voffA);
;             PG8_WAIT_V(8); PG8_WAIT_L(0); PG8_BAR; PG8_MMA(0, 0, At, B0); PG8_MMA(0, 1, At, B1); PG8_BAR; PG8_SCHED;
;             PG8_LDA(At, 0, 1); PG8_STAGE(PG8_SB(0, 0), b2, voffB); PG8_STAGE(PG8_SB(0, 1), b2 + hstep, voffB); PG8_STAGE(PG8_SA(0, 0), a2, voffA);
;             PG8_WAIT_V(8); PG8_WAIT_L(0); PG8_BAR; PG8_MMA(1, 0, At, B0); PG8_MMA(1, 1, At, B1); PG8_BAR; PG8_SCHED;
.LBB0_382:
	ds_read_b128 v[150:153], v146
	ds_read_b128 v[154:157], v146 offset:1024
	ds_read_b128 v[158:161], v146 offset:2048
	ds_read_b128 v[162:165], v146 offset:3072
	ds_read_b128 v[166:169], v147
	ds_read_b128 v[170:173], v147 offset:1024
	ds_read_b128 v[174:177], v147 offset:2048
	ds_read_b128 v[178:181], v147 offset:3072
	s_add_u32 s46, s38, 0x100
	s_addc_u32 s47, s39, 0
	s_cmpk_eq_i32 s67, 0x54
	s_cselect_b32 s51, s29, s47
	s_cselect_b32 s50, s28, s46
	s_cselect_b32 s49, s35, s66
	s_cselect_b32 s48, s34, s65
	v_lshl_add_u64 v[140:141], s[38:39], 0, v[138:139]
	s_add_i32 m0, s30, 0xc000
	ds_read_b128 v[182:185], v148
	ds_read_b128 v[186:189], v148 offset:1024
	ds_read_b128 v[190:193], v148 offset:2048
	ds_read_b128 v[194:197], v148 offset:3072
	ds_read_b128 v[198:201], v148 offset:4096
	ds_read_b128 v[202:205], v148 offset:5120
	ds_read_b128 v[206:209], v148 offset:6144
	ds_read_b128 v[210:213], v148 offset:7168
	global_load_lds_dwordx4 v[140:141], off
	v_lshl_add_u64 v[140:141], s[38:39], 0, v[136:137]
	s_add_i32 m0, s30, 0xe000
	s_nop 0
	global_load_lds_dwordx4 v[140:141], off
	s_waitcnt vmcnt(8)
	s_waitcnt lgkmcnt(0)
	s_barrier
	s_setprio 1
	s_waitcnt lgkmcnt(0)
	v_mfma_f32_16x16x32_bf16 v[124:127], v[150:153], v[182:185], v[124:127]
	v_mfma_f32_16x16x32_bf16 v[120:123], v[158:161], v[182:185], v[120:123]
	v_mfma_f32_16x16x32_bf16 v[116:119], v[150:153], v[190:193], v[116:119]
	v_mfma_f32_16x16x32_bf16 v[108:111], v[158:161], v[190:193], v[108:111]
	v_mfma_f32_16x16x32_bf16 v[100:103], v[150:153], v[198:201], v[100:103]
	v_mfma_f32_16x16x32_bf16 v[92:95], v[158:161], v[198:201], v[92:95]
	v_mfma_f32_16x16x32_bf16 v[84:87], v[150:153], v[206:209], v[84:87]
	v_mfma_f32_16x16x32_bf16 v[76:79], v[158:161], v[206:209], v[76:79]
	v_mfma_f32_16x16x32_bf16 v[124:127], v[154:157], v[186:189], v[124:127]
	v_mfma_f32_16x16x32_bf16 v[120:123], v[162:165], v[186:189], v[120:123]
	v_mfma_f32_16x16x32_bf16 v[116:119], v[154:157], v[194:197], v[116:119]
	v_mfma_f32_16x16x32_bf16 v[108:111], v[162:165], v[194:197], v[108:111]
	v_mfma_f32_16x16x32_bf16 v[100:103], v[154:157], v[202:205], v[100:103]
	v_mfma_f32_16x16x32_bf16 v[92:95], v[162:165], v[202:205], v[92:95]
	v_mfma_f32_16x16x32_bf16 v[84:87], v[154:157], v[210:213], v[84:87]
	v_mfma_f32_16x16x32_bf16 v[76:79], v[162:165], v[210:213], v[76:79]
	v_mfma_f32_16x16x32_bf16 v[112:115], v[166:169], v[182:185], v[112:115]
	v_mfma_f32_16x16x32_bf16 v[104:107], v[174:177], v[182:185], v[104:107]
	v_mfma_f32_16x16x32_bf16 v[96:99], v[166:169], v[190:193], v[96:99]
	v_mfma_f32_16x16x32_bf16 v[88:91], v[174:177], v[190:193], v[88:91]
	v_mfma_f32_16x16x32_bf16 v[80:83], v[166:169], v[198:201], v[80:83]
	v_mfma_f32_16x16x32_bf16 v[72:75], v[174:177], v[198:201], v[72:75]
	v_mfma_f32_16x16x32_bf16 v[68:71], v[166:169], v[206:209], v[68:71]
	v_mfma_f32_16x16x32_bf16 v[64:67], v[174:177], v[206:209], v[64:67]
	v_mfma_f32_16x16x32_bf16 v[112:115], v[170:173], v[186:189], v[112:115]
	v_mfma_f32_16x16x32_bf16 v[104:107], v[178:181], v[186:189], v[104:107]
	v_mfma_f32_16x16x32_bf16 v[96:99], v[170:173], v[194:197], v[96:99]
	v_mfma_f32_16x16x32_bf16 v[88:91], v[178:181], v[194:197], v[88:91]
	v_mfma_f32_16x16x32_bf16 v[80:83], v[170:173], v[202:205], v[80:83]
	v_mfma_f32_16x16x32_bf16 v[72:75], v[178:181], v[202:205], v[72:75]
	v_mfma_f32_16x16x32_bf16 v[68:71], v[170:173], v[210:213], v[68:71]
	v_mfma_f32_16x16x32_bf16 v[64:67], v[178:181], v[210:213], v[64:67]
	s_setprio 0
	s_barrier
	s_add_i32 s38, s59, s23
	v_lshl_add_u64 v[140:141], s[48:49], 0, v[132:133]
	s_mov_b32 m0, s38
	ds_read_b128 v[182:185], v148 offset:16384
	ds_read_b128 v[186:189], v148 offset:17408
	ds_read_b128 v[190:193], v148 offset:18432
	ds_read_b128 v[194:197], v148 offset:19456
	ds_read_b128 v[198:201], v148 offset:20480
	ds_read_b128 v[202:205], v148 offset:21504
	ds_read_b128 v[206:209], v148 offset:22528
	ds_read_b128 v[210:213], v148 offset:23552
	global_load_lds_dwordx4 v[140:141], off
	s_add_i32 m0, s38, 0x2000
	s_add_u32 s38, s48, 0x160000
	v_lshl_add_u64 v[214:215], s[48:49], 0, v[128:129]
	s_addc_u32 s39, s49, 0
	s_add_i32 s68, s60, s23
	global_load_lds_dwordx4 v[214:215], off
	v_lshl_add_u64 v[216:217], s[38:39], 0, v[132:133]
	s_mov_b32 m0, s68
	v_lshl_add_u64 v[218:219], s[50:51], 0, v[130:131]
	global_load_lds_dwordx4 v[216:217], off
	v_lshl_add_u64 v[216:217], s[38:39], 0, v[128:129]
	s_add_i32 m0, s68, 0x2000
	s_nop 0
	global_load_lds_dwordx4 v[216:217], off
	v_lshl_add_u64 v[216:217], s[50:51], 0, v[134:135]
	s_mov_b32 m0, s30
	s_nop 0
	global_load_lds_dwordx4 v[216:217], off
	s_mov_b32 m0, s31
	s_nop 0
	global_load_lds_dwordx4 v[218:219], off
	s_waitcnt vmcnt(8)
	s_waitcnt lgkmcnt(0)
	s_barrier
; #define PG8_STAGE(bufoff, gbase, voff) do { _Pragma("unroll") for (int _i = 0; _i < 2; ++_i) \
;         __builtin_amdgcn_global_load_lds((const unsigned*)((const char*)(gbase) + (voff)[_i]), (LAS unsigned*)(lds + (bufoff) + ldsw + _i * 8192), 16, 0, 0); } while (0)
; #define PG8_LDA(dst, b, h) do { _Pragma("unroll") for (int m = 0; m < 4; ++m) _Pragma("unroll") for (int k = 0; k < 2; ++k) dst[m][k] = *(const LAS bf16x8*)(lds + PG8_SA(b, h) + aoff + m * 2048 + k * 1024); } while (0)
; #define PG8_LDB(dst, b, h) do { _Pragma("unroll") for (int n = 0; n < 2; ++n) _Pragma("unroll") for (int k = 0; k < 2; ++k) dst[n][k] = *(const LAS bf16x8*)(lds + PG8_SB(b, h) + boff + n * 2048 + k * 1024); } while (0)
; #define PG8_MMA(ai, bj, At, Bt) do { __builtin_amdgcn_s_setprio(1); _Pragma("unroll") for (int m = 0; m < 4; ++m) _Pragma("unroll") for (int n = 0; n < 2; ++n) _Pragma("unroll") for (int k = 0; k < 2; ++k) \
;         acc[ai][bj][m][n] = __builtin_amdgcn_mfma_f32_16x16x32_bf16(Bt[n][k], At[m][k], acc[ai][bj][m][n], 0, 0, 0); __builtin_amdgcn_s_setprio(0); } while (0)
; #define PG8_WAIT_V(n) asm volatile("s_waitcnt vmcnt(" #n ")" ::: "memory")
; #define PG8_WAIT_L(n) asm volatile("s_waitcnt lgkmcnt(" #n ")" ::: "memory")
; #define PG8_BAR __builtin_amdgcn_s_barrier()
; #define PG8_SCHED __builtin_amdgcn_sched_barrier(0)
; template <class Epi>
; __device__ __forceinline__ void gemm_phase(LAS unsigned char* lds, const Gemm g, const StaticOrder& S, const Epi& E, const int tid) {
;     ...
;             PG8_WAIT_V(8); PG8_WAIT_L(0); PG8_BAR; PG8_MMA(1, 0, At, B0); PG8_MMA(1, 1, At, B1); PG8_BAR; PG8_SCHED;
;             PG8_LDB(B0, 1, 0); PG8_LDB(B1, 1, 1); PG8_SCHED; PG8_LDA(At, 1, 0); PG8_STAGE(PG8_SA(0, 1), a2 + hstep, voffA);
;             PG8_WAIT_V(8); PG8_WAIT_L(0); PG8_BAR; PG8_MMA(0, 0, At, B0); PG8_MMA(0, 1, At, B1); PG8_BAR; PG8_SCHED;
	s_setprio 1
	s_waitcnt lgkmcnt(0)
	v_mfma_f32_16x16x32_bf16 v[60:63], v[150:153], v[182:185], v[60:63]
	v_mfma_f32_16x16x32_bf16 v[56:59], v[158:161], v[182:185], v[56:59]
	v_mfma_f32_16x16x32_bf16 v[52:55], v[150:153], v[190:193], v[52:55]
	v_mfma_f32_16x16x32_bf16 v[44:47], v[158:161], v[190:193], v[44:47]
	v_mfma_f32_16x16x32_bf16 v[36:39], v[150:153], v[198:201], v[36:39]
	v_mfma_f32_16x16x32_bf16 v[28:31], v[158:161], v[198:201], v[28:31]
	v_mfma_f32_16x16x32_bf16 v[20:23], v[150:153], v[206:209], v[20:23]
	v_mfma_f32_16x16x32_bf16 v[12:15], v[158:161], v[206:209], v[12:15]
	v_mfma_f32_16x16x32_bf16 v[60:63], v[154:157], v[186:189], v[60:63]
	v_mfma_f32_16x16x32_bf16 v[56:59], v[162:165], v[186:189], v[56:59]
	v_mfma_f32_16x16x32_bf16 v[52:55], v[154:157], v[194:197], v[52:55]
	v_mfma_f32_16x16x32_bf16 v[44:47], v[162:165], v[194:197], v[44:47]
	v_mfma_f32_16x16x32_bf16 v[36:39], v[154:157], v[202:205], v[36:39]
	v_mfma_f32_16x16x32_bf16 v[28:31], v[162:165], v[202:205], v[28:31]
	v_mfma_f32_16x16x32_bf16 v[20:23], v[154:157], v[210:213], v[20:23]
	v_mfma_f32_16x16x32_bf16 v[12:15], v[162:165], v[210:213], v[12:15]
	v_mfma_f32_16x16x32_bf16 v[48:51], v[166:169], v[182:185], v[48:51]
	v_mfma_f32_16x16x32_bf16 v[40:43], v[174:177], v[182:185], v[40:43]
	v_mfma_f32_16x16x32_bf16 v[32:35], v[166:169], v[190:193], v[32:35]
	v_mfma_f32_16x16x32_bf16 v[24:27], v[174:177], v[190:193], v[24:27]
	v_mfma_f32_16x16x32_bf16 v[16:19], v[166:169], v[198:201], v[16:19]
	v_mfma_f32_16x16x32_bf16 v[8:11], v[174:177], v[198:201], v[8:11]
	v_mfma_f32_16x16x32_bf16 v[4:7], v[166:169], v[206:209], v[4:7]
	v_mfma_f32_16x16x32_bf16 v[0:3], v[174:177], v[206:209], v[0:3]
	v_mfma_f32_16x16x32_bf16 v[48:51], v[170:173], v[186:189], v[48:51]
	v_mfma_f32_16x16x32_bf16 v[40:43], v[178:181], v[186:189], v[40:43]
	v_mfma_f32_16x16x32_bf16 v[32:35], v[170:173], v[194:197], v[32:35]
	v_mfma_f32_16x16x32_bf16 v[24:27], v[178:181], v[194:197], v[24:27]
	v_mfma_f32_16x16x32_bf16 v[16:19], v[170:173], v[202:205], v[16:19]
	v_mfma_f32_16x16x32_bf16 v[8:11], v[178:181], v[202:205], v[8:11]
	v_mfma_f32_16x16x32_bf16 v[4:7], v[170:173], v[210:213], v[4:7]
	v_mfma_f32_16x16x32_bf16 v[0:3], v[178:181], v[210:213], v[0:3]
	s_setprio 0
	s_barrier
	s_add_i32 s68, 0, 0x18000
	v_add_u32_e32 v149, s68, v144
	s_add_i32 s69, 0, 0x1c000
	ds_read_b128 v[150:153], v149
	ds_read_b128 v[154:157], v149 offset:1024
	ds_read_b128 v[158:161], v149 offset:2048
	ds_read_b128 v[162:165], v149 offset:3072
	v_add_u32_e32 v149, s69, v144
	ds_read_b128 v[166:169], v149
	ds_read_b128 v[170:173], v149 offset:1024
	ds_read_b128 v[174:177], v149 offset:2048
	ds_read_b128 v[178:181], v149 offset:3072
	s_add_u32 s38, s50, 0x160000
	s_addc_u32 s39, s51, 0
	s_mov_b32 m0, s52
	v_lshl_add_u64 v[220:221], s[38:39], 0, v[134:135]
	ds_read_b128 v[182:185], v148 offset:32768
	ds_read_b128 v[186:189], v148 offset:33792
	ds_read_b128 v[190:193], v148 offset:34816
	ds_read_b128 v[194:197], v148 offset:35840
	ds_read_b128 v[198:201], v148 offset:36864
	ds_read_b128 v[202:205], v148 offset:37888
	ds_read_b128 v[206:209], v148 offset:38912
	ds_read_b128 v[210:213], v148 offset:39936
	global_load_lds_dwordx4 v[220:221], off
	v_lshl_add_u64 v[220:221], s[38:39], 0, v[130:131]
	s_mov_b32 m0, s53
	s_nop 0
	global_load_lds_dwordx4 v[220:221], off
	s_waitcnt vmcnt(8)
	s_waitcnt lgkmcnt(0)
	s_barrier
	s_setprio 1
	s_waitcnt lgkmcnt(0)
	v_mfma_f32_16x16x32_bf16 v[124:127], v[150:153], v[182:185], v[124:127]
	v_mfma_f32_16x16x32_bf16 v[120:123], v[158:161], v[182:185], v[120:123]
	v_mfma_f32_16x16x32_bf16 v[116:119], v[150:153], v[190:193], v[116:119]
	v_mfma_f32_16x16x32_bf16 v[108:111], v[158:161], v[190:193], v[108:111]
	v_mfma_f32_16x16x32_bf16 v[100:103], v[150:153], v[198:201], v[100:103]
	v_mfma_f32_16x16x32_bf16 v[92:95], v[158:161], v[198:201], v[92:95]
	v_mfma_f32_16x16x32_bf16 v[84:87], v[150:153], v[206:209], v[84:87]
	v_mfma_f32_16x16x32_bf16 v[76:79], v[158:161], v[206:209], v[76:79]
	v_mfma_f32_16x16x32_bf16 v[124:127], v[154:157], v[186:189], v[124:127]
	v_mfma_f32_16x16x32_bf16 v[120:123], v[162:165], v[186:189], v[120:123]
	v_mfma_f32_16x16x32_bf16 v[116:119], v[154:157], v[194:197], v[116:119]
	v_mfma_f32_16x16x32_bf16 v[108:111], v[162:165], v[194:197], v[108:111]
	v_mfma_f32_16x16x32_bf16 v[100:103], v[154:157], v[202:205], v[100:103]
	v_mfma_f32_16x16x32_bf16 v[92:95], v[162:165], v[202:205], v[92:95]
	v_mfma_f32_16x16x32_bf16 v[84:87], v[154:157], v[210:213], v[84:87]
	v_mfma_f32_16x16x32_bf16 v[76:79], v[162:165], v[210:213], v[76:79]
	v_mfma_f32_16x16x32_bf16 v[112:115], v[166:169], v[182:185], v[112:115]
	v_mfma_f32_16x16x32_bf16 v[104:107], v[174:177], v[182:185], v[104:107]
	v_mfma_f32_16x16x32_bf16 v[96:99], v[166:169], v[190:193], v[96:99]
	v_mfma_f32_16x16x32_bf16 v[88:91], v[174:177], v[190:193], v[88:91]
	v_mfma_f32_16x16x32_bf16 v[80:83], v[166:169], v[198:201], v[80:83]
	v_mfma_f32_16x16x32_bf16 v[72:75], v[174:177], v[198:201], v[72:75]
	v_mfma_f32_16x16x32_bf16 v[68:71], v[166:169], v[206:209], v[68:71]
	v_mfma_f32_16x16x32_bf16 v[64:67], v[174:177], v[206:209], v[64:67]
	v_mfma_f32_16x16x32_bf16 v[112:115], v[170:173], v[186:189], v[112:115]
	v_mfma_f32_16x16x32_bf16 v[104:107], v[178:181], v[186:189], v[104:107]
	v_mfma_f32_16x16x32_bf16 v[96:99], v[170:173], v[194:197], v[96:99]
	v_mfma_f32_16x16x32_bf16 v[88:91], v[178:181], v[194:197], v[88:91]
	v_mfma_f32_16x16x32_bf16 v[80:83], v[170:173], v[202:205], v[80:83]
	v_mfma_f32_16x16x32_bf16 v[72:75], v[178:181], v[202:205], v[72:75]
	v_mfma_f32_16x16x32_bf16 v[68:71], v[170:173], v[210:213], v[68:71]
	v_mfma_f32_16x16x32_bf16 v[64:67], v[178:181], v[210:213], v[64:67]
	s_setprio 0
	s_barrier
; #define PG8_STAGE(bufoff, gbase, voff) do { _Pragma("unroll") for (int _i = 0; _i < 2; ++_i) \
;         __builtin_amdgcn_global_load_lds((const unsigned*)((const char*)(gbase) + (voff)[_i]), (LAS unsigned*)(lds + (bufoff) + ldsw + _i * 8192), 16, 0, 0); } while (0)
; #define PG8_LDA(dst, b, h) do { _Pragma("unroll") for (int m = 0; m < 4; ++m) _Pragma("unroll") for (int k = 0; k < 2; ++k) dst[m][k] = *(const LAS bf16x8*)(lds + PG8_SA(b, h) + aoff + m * 2048 + k * 1024); } while (0)
; #define PG8_MMA(ai, bj, At, Bt) do { __builtin_amdgcn_s_setprio(1); _Pragma("unroll") for (int m = 0; m < 4; ++m) _Pragma("unroll") for (int n = 0; n < 2; ++n) _Pragma("unroll") for (int k = 0; k < 2; ++k) \
;         acc[ai][bj][m][n] = __builtin_amdgcn_mfma_f32_16x16x32_bf16(Bt[n][k], At[m][k], acc[ai][bj][m][n], 0, 0, 0); __builtin_amdgcn_s_setprio(0); } while (0)
; #define PG8_WAIT_V(n) asm volatile("s_waitcnt vmcnt(" #n ")" ::: "memory")
; #define PG8_WAIT_L(n) asm volatile("s_waitcnt lgkmcnt(" #n ")" ::: "memory")
; #define PG8_BAR __builtin_amdgcn_s_barrier()
; #define PG8_SCHED __builtin_amdgcn_sched_barrier(0)
; template <class Epi>
; __device__ __forceinline__ void gemm_phase(LAS unsigned char* lds, const Gemm g, const StaticOrder& S, const Epi& E, const int tid) {
;     ...
;             PG8_LDA(At, 1, 1); PG8_STAGE(PG8_SB(1, 0), b3, voffB); PG8_STAGE(PG8_SB(1, 1), b3 + hstep, voffB); PG8_STAGE(PG8_SA(1, 0), a3, voffA);
;             PG8_WAIT_V(8); PG8_WAIT_L(0); PG8_BAR; PG8_MMA(1, 0, At, B0); PG8_MMA(1, 1, At, B1); PG8_BAR; PG8_SCHED;
;         }
;         if (wr == 0) PG8_BAR;
	s_add_i32 s38, s68, s23
	v_lshl_add_u64 v[140:141], v[140:141], 0, s[24:25]
	s_mov_b32 m0, s38
	ds_read_b128 v[182:185], v148 offset:49152
	ds_read_b128 v[186:189], v148 offset:50176
	ds_read_b128 v[190:193], v148 offset:51200
	ds_read_b128 v[194:197], v148 offset:52224
	ds_read_b128 v[198:201], v148 offset:53248
	ds_read_b128 v[202:205], v148 offset:54272
	ds_read_b128 v[206:209], v148 offset:55296
	ds_read_b128 v[210:213], v148 offset:56320
	global_load_lds_dwordx4 v[140:141], off
	s_add_i32 m0, s38, 0x2000
	s_add_u32 s38, s48, 0x160080
	v_lshl_add_u64 v[140:141], v[214:215], 0, s[24:25]
	s_addc_u32 s39, s49, 0
	s_add_i32 s48, s69, s23
	global_load_lds_dwordx4 v[140:141], off
	v_lshl_add_u64 v[140:141], s[38:39], 0, v[132:133]
	s_mov_b32 m0, s48
	s_nop 0
	global_load_lds_dwordx4 v[140:141], off
	v_lshl_add_u64 v[140:141], s[38:39], 0, v[128:129]
	s_add_i32 m0, s48, 0x2000
	s_nop 0
	global_load_lds_dwordx4 v[140:141], off
	v_lshl_add_u64 v[140:141], v[216:217], 0, s[24:25]
	s_mov_b32 m0, s57
	s_nop 0
	global_load_lds_dwordx4 v[140:141], off
	v_lshl_add_u64 v[140:141], v[218:219], 0, s[24:25]
	s_mov_b32 m0, s58
	s_nop 0
	global_load_lds_dwordx4 v[140:141], off
	s_waitcnt vmcnt(8)
	s_waitcnt lgkmcnt(0)
	s_barrier
	s_setprio 1
	s_waitcnt lgkmcnt(0)
	v_mfma_f32_16x16x32_bf16 v[60:63], v[150:153], v[182:185], v[60:63]
	v_mfma_f32_16x16x32_bf16 v[56:59], v[158:161], v[182:185], v[56:59]
	v_mfma_f32_16x16x32_bf16 v[52:55], v[150:153], v[190:193], v[52:55]
	v_mfma_f32_16x16x32_bf16 v[44:47], v[158:161], v[190:193], v[44:47]
	v_mfma_f32_16x16x32_bf16 v[36:39], v[150:153], v[198:201], v[36:39]
	v_mfma_f32_16x16x32_bf16 v[28:31], v[158:161], v[198:201], v[28:31]
	v_mfma_f32_16x16x32_bf16 v[20:23], v[150:153], v[206:209], v[20:23]
	v_mfma_f32_16x16x32_bf16 v[12:15], v[158:161], v[206:209], v[12:15]
	v_mfma_f32_16x16x32_bf16 v[60:63], v[154:157], v[186:189], v[60:63]
	v_mfma_f32_16x16x32_bf16 v[56:59], v[162:165], v[186:189], v[56:59]
	v_mfma_f32_16x16x32_bf16 v[52:55], v[154:157], v[194:197], v[52:55]
	v_mfma_f32_16x16x32_bf16 v[44:47], v[162:165], v[194:197], v[44:47]
	v_mfma_f32_16x16x32_bf16 v[36:39], v[154:157], v[202:205], v[36:39]
	v_mfma_f32_16x16x32_bf16 v[28:31], v[162:165], v[202:205], v[28:31]
	v_mfma_f32_16x16x32_bf16 v[20:23], v[154:157], v[210:213], v[20:23]
	v_mfma_f32_16x16x32_bf16 v[12:15], v[162:165], v[210:213], v[12:15]
	v_mfma_f32_16x16x32_bf16 v[48:51], v[166:169], v[182:185], v[48:51]
	v_mfma_f32_16x16x32_bf16 v[40:43], v[174:177], v[182:185], v[40:43]
	v_mfma_f32_16x16x32_bf16 v[32:35], v[166:169], v[190:193], v[32:35]
	v_mfma_f32_16x16x32_bf16 v[24:27], v[174:177], v[190:193], v[24:27]
	v_mfma_f32_16x16x32_bf16 v[16:19], v[166:169], v[198:201], v[16:19]
	v_mfma_f32_16x16x32_bf16 v[8:11], v[174:177], v[198:201], v[8:11]
	v_mfma_f32_16x16x32_bf16 v[4:7], v[166:169], v[206:209], v[4:7]
	v_mfma_f32_16x16x32_bf16 v[0:3], v[174:177], v[206:209], v[0:3]
	v_mfma_f32_16x16x32_bf16 v[48:51], v[170:173], v[186:189], v[48:51]
	v_mfma_f32_16x16x32_bf16 v[40:43], v[178:181], v[186:189], v[40:43]
	v_mfma_f32_16x16x32_bf16 v[32:35], v[170:173], v[194:197], v[32:35]
	v_mfma_f32_16x16x32_bf16 v[24:27], v[178:181], v[194:197], v[24:27]
	v_mfma_f32_16x16x32_bf16 v[16:19], v[170:173], v[202:205], v[16:19]
	v_mfma_f32_16x16x32_bf16 v[8:11], v[178:181], v[202:205], v[8:11]
	v_mfma_f32_16x16x32_bf16 v[4:7], v[170:173], v[210:213], v[4:7]
	v_mfma_f32_16x16x32_bf16 v[0:3], v[178:181], v[210:213], v[0:3]
	s_setprio 0
	s_barrier
	s_add_i32 s67, s67, 2
	s_add_u32 s65, s65, 0x100
	s_addc_u32 s66, s66, 0
	s_cmpk_gt_u32 s67, 0x55
	s_mov_b64 s[38:39], s[46:47]
	s_cbranch_scc0 .LBB0_382
	s_and_b64 vcc, exec, s[26:27]
	s_cbranch_vccz .LBB0_385
	s_barrier

; #define PG8_STAGE(bufoff, gbase, voff) do { _Pragma("unroll") for (int _i = 0; _i < 2; ++_i) \
;         __builtin_amdgcn_global_load_lds((const unsigned*)((const char*)(gbase) + (voff)[_i]), (LAS unsigned*)(lds + (bufoff) + ldsw + _i * 8192), 16, 0, 0); } while (0)
; #define PG8_LDA(dst, b, h) do { _Pragma("unroll") for (int m = 0; m < 4; ++m) _Pragma("unroll") for (int k = 0; k < 2; ++k) dst[m][k] = *(const LAS bf16x8*)(lds + PG8_SA(b, h) + aoff + m * 2048 + k * 1024); } while (0)
; #define PG8_LDB(dst, b, h) do { _Pragma("unroll") for (int n = 0; n < 2; ++n) _Pragma("unroll") for (int k = 0; k < 2; ++k) dst[n][k] = *(const LAS bf16x8*)(lds + PG8_SB(b, h) + boff + n * 2048 + k * 1024); } while (0)
; #define PG8_MMA(ai, bj, At, Bt) do { __builtin_amdgcn_s_setprio(1); _Pragma("unroll") for (int m = 0; m < 4; ++m) _Pragma("unroll") for (int n = 0; n < 2; ++n) _Pragma("unroll") for (int k = 0; k < 2; ++k) \
;         acc[ai][bj][m][n] = __builtin_amdgcn_mfma_f32_16x16x32_bf16(Bt[n][k], At[m][k], acc[ai][bj][m][n], 0, 0, 0); __builtin_amdgcn_s_setprio(0); } while (0)
; #define PG8_WAIT_V(n) asm volatile("s_waitcnt vmcnt(" #n ")" ::: "memory")
; #define PG8_BAR __builtin_amdgcn_s_barrier()
; template <class Epi>
; __device__ __forceinline__ void gemm_phase(LAS unsigned char* lds, const Gemm g, const StaticOrder& S, const Epi& E, const int tid) {
;     ...
;         const char* nA = has_next ? (const char*)g.A + (size_t)nxt.pm * tstep : cA; const char* nB = has_next ? (const char*)g.Bt + (size_t)nxt.pn * tstep : cB;
;         for (int t = 0; t < nt; t += 2) {
;             const bool last = (t == nt - 2);
;             const char* a1 = cA + (size_t)(t + 1) * kstep;
;             const char* a2 = last ? nA : cA + (size_t)(t + 2) * kstep; const char* b2 = last ? nB : cB + (size_t)(t + 2) * kstep;
;             const char* a3 = a2 + kstep; const char* b3 = b2 + kstep;
;             PG8_LDB(B0, 0, 0); PG8_LDB(B1, 0, 1); PG8_SCHED; PG8_LDA(At, 0, 0); PG8_STAGE(PG8_SA(1, 1), a1 + hstep, voffA);
;             PG8_WAIT_V(8); PG8_WAIT_L(0); PG8_BAR; PG8_MMA(0, 0, At, B0); PG8_MMA(0, 1, At, B1); PG8_BAR; PG8_SCHED;
;             PG8_LDA(At, 0, 1); PG8_STAGE(PG8_SB(0, 0), b2, voffB); PG8_STAGE(PG8_SB(0, 1), b2 + hstep, voffB); PG8_STAGE(PG8_SA(0, 0), a2, voffA);
;             PG8_WAIT_V(8); PG8_WAIT_L(0); PG8_BAR; PG8_MMA(1, 0, At, B0); PG8_MMA(1, 1, At, B1); PG8_BAR; PG8_SCHED;
.LBB0_628:
	ds_read_b128 v[152:155], v163
	ds_read_b128 v[172:175], v163 offset:1024
	ds_read_b128 v[176:179], v163 offset:2048
	ds_read_b128 v[180:183], v163 offset:3072
	ds_read_b128 v[184:187], v164
	ds_read_b128 v[188:191], v164 offset:1024
	ds_read_b128 v[192:195], v164 offset:2048
	ds_read_b128 v[196:199], v164 offset:3072
	s_add_u32 s28, s26, 0xfff80080
	s_addc_u32 s29, s27, -1
	s_cmp_eq_u32 s79, 28
	s_cselect_b32 s35, s25, s29
	s_cselect_b32 s34, s39, s28
	s_cselect_b32 s29, s53, s78
	s_cselect_b32 s28, s55, s77
	v_lshl_add_u64 v[234:235], s[26:27], 0, v[144:145]
	s_add_i32 m0, s21, 0xc000
	ds_read_b128 v[200:203], v165
	ds_read_b128 v[204:207], v165 offset:1024
	ds_read_b128 v[208:211], v165 offset:2048
	ds_read_b128 v[212:215], v165 offset:3072
	ds_read_b128 v[216:219], v165 offset:4096
	ds_read_b128 v[220:223], v165 offset:5120
	ds_read_b128 v[226:229], v165 offset:6144
	ds_read_b128 v[230:233], v165 offset:7168
	global_load_lds_dwordx4 v[234:235], off
	v_lshl_add_u64 v[234:235], s[26:27], 0, v[142:143]
	s_add_i32 m0, s21, 0xe000
	s_nop 0
	global_load_lds_dwordx4 v[234:235], off
	s_waitcnt vmcnt(8)
	s_waitcnt lgkmcnt(0)
	s_barrier
	s_setprio 1
	s_waitcnt lgkmcnt(0)
	v_mfma_f32_16x16x32_bf16 v[124:127], v[152:155], v[200:203], v[124:127]
	v_mfma_f32_16x16x32_bf16 v[120:123], v[176:179], v[200:203], v[120:123]
	v_mfma_f32_16x16x32_bf16 v[108:111], v[152:155], v[208:211], v[108:111]
	v_mfma_f32_16x16x32_bf16 v[104:107], v[176:179], v[208:211], v[104:107]
	v_mfma_f32_16x16x32_bf16 v[92:95], v[152:155], v[216:219], v[92:95]
	v_mfma_f32_16x16x32_bf16 v[88:91], v[176:179], v[216:219], v[88:91]
	v_mfma_f32_16x16x32_bf16 v[76:79], v[152:155], v[226:229], v[76:79]
	v_mfma_f32_16x16x32_bf16 v[72:75], v[176:179], v[226:229], v[72:75]
	v_mfma_f32_16x16x32_bf16 v[124:127], v[172:175], v[204:207], v[124:127]
	v_mfma_f32_16x16x32_bf16 v[120:123], v[180:183], v[204:207], v[120:123]
	v_mfma_f32_16x16x32_bf16 v[108:111], v[172:175], v[212:215], v[108:111]
	v_mfma_f32_16x16x32_bf16 v[104:107], v[180:183], v[212:215], v[104:107]
	v_mfma_f32_16x16x32_bf16 v[92:95], v[172:175], v[220:223], v[92:95]
	v_mfma_f32_16x16x32_bf16 v[88:91], v[180:183], v[220:223], v[88:91]
	v_mfma_f32_16x16x32_bf16 v[76:79], v[172:175], v[230:233], v[76:79]
	v_mfma_f32_16x16x32_bf16 v[72:75], v[180:183], v[230:233], v[72:75]
	v_mfma_f32_16x16x32_bf16 v[116:119], v[184:187], v[200:203], v[116:119]
	v_mfma_f32_16x16x32_bf16 v[112:115], v[192:195], v[200:203], v[112:115]
	v_mfma_f32_16x16x32_bf16 v[100:103], v[184:187], v[208:211], v[100:103]
	v_mfma_f32_16x16x32_bf16 v[96:99], v[192:195], v[208:211], v[96:99]
	v_mfma_f32_16x16x32_bf16 v[84:87], v[184:187], v[216:219], v[84:87]
	v_mfma_f32_16x16x32_bf16 v[80:83], v[192:195], v[216:219], v[80:83]
	v_mfma_f32_16x16x32_bf16 v[68:71], v[184:187], v[226:229], v[68:71]
	v_mfma_f32_16x16x32_bf16 v[64:67], v[192:195], v[226:229], v[64:67]
	v_mfma_f32_16x16x32_bf16 v[116:119], v[188:191], v[204:207], v[116:119]
	v_mfma_f32_16x16x32_bf16 v[112:115], v[196:199], v[204:207], v[112:115]
	v_mfma_f32_16x16x32_bf16 v[100:103], v[188:191], v[212:215], v[100:103]
	v_mfma_f32_16x16x32_bf16 v[96:99], v[196:199], v[212:215], v[96:99]
	v_mfma_f32_16x16x32_bf16 v[84:87], v[188:191], v[220:223], v[84:87]
	v_mfma_f32_16x16x32_bf16 v[80:83], v[196:199], v[220:223], v[80:83]
	v_mfma_f32_16x16x32_bf16 v[68:71], v[188:191], v[230:233], v[68:71]
	v_mfma_f32_16x16x32_bf16 v[64:67], v[196:199], v[230:233], v[64:67]
	s_setprio 0
	s_barrier
	s_add_i32 s80, s65, s20
	v_lshl_add_u64 v[234:235], s[28:29], 0, v[130:131]
	s_mov_b32 m0, s80
	ds_read_b128 v[200:203], v165 offset:16384
	ds_read_b128 v[204:207], v165 offset:17408
	ds_read_b128 v[208:211], v165 offset:18432
	ds_read_b128 v[212:215], v165 offset:19456
	ds_read_b128 v[216:219], v165 offset:20480
	ds_read_b128 v[220:223], v165 offset:21504
	ds_read_b128 v[226:229], v165 offset:22528
	ds_read_b128 v[230:233], v165 offset:23552
	global_load_lds_dwordx4 v[234:235], off
	s_add_i32 m0, s80, 0x2000
	s_add_u32 s80, s28, 0x80000
	v_lshl_add_u64 v[236:237], s[28:29], 0, v[134:135]
	s_addc_u32 s81, s29, 0
	s_add_i32 s82, s66, s20
	global_load_lds_dwordx4 v[236:237], off
	v_lshl_add_u64 v[238:239], s[80:81], 0, v[130:131]
	s_mov_b32 m0, s82
	v_lshl_add_u64 v[240:241], s[34:35], 0, v[132:133]
	global_load_lds_dwordx4 v[238:239], off
	v_lshl_add_u64 v[238:239], s[80:81], 0, v[134:135]
	s_add_i32 m0, s82, 0x2000
	s_nop 0
	global_load_lds_dwordx4 v[238:239], off
	v_lshl_add_u64 v[238:239], s[34:35], 0, v[128:129]
	s_mov_b32 m0, s21
	s_nop 0
	global_load_lds_dwordx4 v[238:239], off
	s_mov_b32 m0, s23
	s_nop 0
	global_load_lds_dwordx4 v[240:241], off
	s_waitcnt vmcnt(8)
	s_waitcnt lgkmcnt(0)
	s_barrier
; #define PG8_STAGE(bufoff, gbase, voff) do { _Pragma("unroll") for (int _i = 0; _i < 2; ++_i) \
;         __builtin_amdgcn_global_load_lds((const unsigned*)((const char*)(gbase) + (voff)[_i]), (LAS unsigned*)(lds + (bufoff) + ldsw + _i * 8192), 16, 0, 0); } while (0)
; #define PG8_LDA(dst, b, h) do { _Pragma("unroll") for (int m = 0; m < 4; ++m) _Pragma("unroll") for (int k = 0; k < 2; ++k) dst[m][k] = *(const LAS bf16x8*)(lds + PG8_SA(b, h) + aoff + m * 2048 + k * 1024); } while (0)
; #define PG8_LDB(dst, b, h) do { _Pragma("unroll") for (int n = 0; n < 2; ++n) _Pragma("unroll") for (int k = 0; k < 2; ++k) dst[n][k] = *(const LAS bf16x8*)(lds + PG8_SB(b, h) + boff + n * 2048 + k * 1024); } while (0)
; #define PG8_MMA(ai, bj, At, Bt) do { __builtin_amdgcn_s_setprio(1); _Pragma("unroll") for (int m = 0; m < 4; ++m) _Pragma("unroll") for (int n = 0; n < 2; ++n) _Pragma("unroll") for (int k = 0; k < 2; ++k) \
;         acc[ai][bj][m][n] = __builtin_amdgcn_mfma_f32_16x16x32_bf16(Bt[n][k], At[m][k], acc[ai][bj][m][n], 0, 0, 0); __builtin_amdgcn_s_setprio(0); } while (0)
; #define PG8_WAIT_V(n) asm volatile("s_waitcnt vmcnt(" #n ")" ::: "memory")
; #define PG8_WAIT_L(n) asm volatile("s_waitcnt lgkmcnt(" #n ")" ::: "memory")
; #define PG8_BAR __builtin_amdgcn_s_barrier()
; #define PG8_SCHED __builtin_amdgcn_sched_barrier(0)
; template <class Epi>
; __device__ __forceinline__ void gemm_phase(LAS unsigned char* lds, const Gemm g, const StaticOrder& S, const Epi& E, const int tid) {
;     ...
;             PG8_WAIT_V(8); PG8_WAIT_L(0); PG8_BAR; PG8_MMA(1, 0, At, B0); PG8_MMA(1, 1, At, B1); PG8_BAR; PG8_SCHED;
;             PG8_LDB(B0, 1, 0); PG8_LDB(B1, 1, 1); PG8_SCHED; PG8_LDA(At, 1, 0); PG8_STAGE(PG8_SA(0, 1), a2 + hstep, voffA);
;             PG8_WAIT_V(8); PG8_WAIT_L(0); PG8_BAR; PG8_MMA(0, 0, At, B0); PG8_MMA(0, 1, At, B1); PG8_BAR; PG8_SCHED;
	s_setprio 1
	s_waitcnt lgkmcnt(0)
	v_mfma_f32_16x16x32_bf16 v[60:63], v[152:155], v[200:203], v[60:63]
	v_mfma_f32_16x16x32_bf16 v[56:59], v[176:179], v[200:203], v[56:59]
	v_mfma_f32_16x16x32_bf16 v[44:47], v[152:155], v[208:211], v[44:47]
	v_mfma_f32_16x16x32_bf16 v[40:43], v[176:179], v[208:211], v[40:43]
	v_mfma_f32_16x16x32_bf16 v[28:31], v[152:155], v[216:219], v[28:31]
	v_mfma_f32_16x16x32_bf16 v[24:27], v[176:179], v[216:219], v[24:27]
	v_mfma_f32_16x16x32_bf16 v[12:15], v[152:155], v[226:229], v[12:15]
	v_mfma_f32_16x16x32_bf16 v[8:11], v[176:179], v[226:229], v[8:11]
	v_mfma_f32_16x16x32_bf16 v[60:63], v[172:175], v[204:207], v[60:63]
	v_mfma_f32_16x16x32_bf16 v[56:59], v[180:183], v[204:207], v[56:59]
	v_mfma_f32_16x16x32_bf16 v[44:47], v[172:175], v[212:215], v[44:47]
	v_mfma_f32_16x16x32_bf16 v[40:43], v[180:183], v[212:215], v[40:43]
	v_mfma_f32_16x16x32_bf16 v[28:31], v[172:175], v[220:223], v[28:31]
	v_mfma_f32_16x16x32_bf16 v[24:27], v[180:183], v[220:223], v[24:27]
	v_mfma_f32_16x16x32_bf16 v[12:15], v[172:175], v[230:233], v[12:15]
	v_mfma_f32_16x16x32_bf16 v[8:11], v[180:183], v[230:233], v[8:11]
	v_mfma_f32_16x16x32_bf16 v[52:55], v[184:187], v[200:203], v[52:55]
	v_mfma_f32_16x16x32_bf16 v[48:51], v[192:195], v[200:203], v[48:51]
	v_mfma_f32_16x16x32_bf16 v[36:39], v[184:187], v[208:211], v[36:39]
	v_mfma_f32_16x16x32_bf16 v[32:35], v[192:195], v[208:211], v[32:35]
	v_mfma_f32_16x16x32_bf16 v[20:23], v[184:187], v[216:219], v[20:23]
	v_mfma_f32_16x16x32_bf16 v[16:19], v[192:195], v[216:219], v[16:19]
	v_mfma_f32_16x16x32_bf16 v[4:7], v[184:187], v[226:229], v[4:7]
	v_mfma_f32_16x16x32_bf16 v[0:3], v[192:195], v[226:229], v[0:3]
	v_mfma_f32_16x16x32_bf16 v[52:55], v[188:191], v[204:207], v[52:55]
	v_mfma_f32_16x16x32_bf16 v[48:51], v[196:199], v[204:207], v[48:51]
	v_mfma_f32_16x16x32_bf16 v[36:39], v[188:191], v[212:215], v[36:39]
	v_mfma_f32_16x16x32_bf16 v[32:35], v[196:199], v[212:215], v[32:35]
	v_mfma_f32_16x16x32_bf16 v[20:23], v[188:191], v[220:223], v[20:23]
	v_mfma_f32_16x16x32_bf16 v[16:19], v[196:199], v[220:223], v[16:19]
	v_mfma_f32_16x16x32_bf16 v[4:7], v[188:191], v[230:233], v[4:7]
	v_mfma_f32_16x16x32_bf16 v[0:3], v[196:199], v[230:233], v[0:3]
	s_setprio 0
	s_barrier
	s_add_i32 s80, 0, 0x18000
	v_add_u32_e32 v136, s80, v159
	s_add_i32 s81, 0, 0x1c000
	ds_read_b128 v[152:155], v136
	ds_read_b128 v[172:175], v136 offset:1024
	ds_read_b128 v[176:179], v136 offset:2048
	ds_read_b128 v[180:183], v136 offset:3072
	v_add_u32_e32 v136, s81, v159
	ds_read_b128 v[184:187], v136
	ds_read_b128 v[188:191], v136 offset:1024
	ds_read_b128 v[192:195], v136 offset:2048
	ds_read_b128 v[196:199], v136 offset:3072
	s_add_u32 s34, s34, 0x80000
	s_addc_u32 s35, s35, 0
	s_mov_b32 m0, s30
	v_lshl_add_u64 v[242:243], s[34:35], 0, v[128:129]
	ds_read_b128 v[200:203], v165 offset:32768
	ds_read_b128 v[204:207], v165 offset:33792
	ds_read_b128 v[208:211], v165 offset:34816
	ds_read_b128 v[212:215], v165 offset:35840
	ds_read_b128 v[216:219], v165 offset:36864
	ds_read_b128 v[220:223], v165 offset:37888
	ds_read_b128 v[226:229], v165 offset:38912
	ds_read_b128 v[230:233], v165 offset:39936
	global_load_lds_dwordx4 v[242:243], off
	v_lshl_add_u64 v[242:243], s[34:35], 0, v[132:133]
	s_mov_b32 m0, s31
	s_nop 0
	global_load_lds_dwordx4 v[242:243], off
	s_waitcnt vmcnt(8)
	s_waitcnt lgkmcnt(0)
	s_barrier
	s_setprio 1
	s_waitcnt lgkmcnt(0)
	v_mfma_f32_16x16x32_bf16 v[124:127], v[152:155], v[200:203], v[124:127]
	v_mfma_f32_16x16x32_bf16 v[120:123], v[176:179], v[200:203], v[120:123]
	v_mfma_f32_16x16x32_bf16 v[108:111], v[152:155], v[208:211], v[108:111]
	v_mfma_f32_16x16x32_bf16 v[104:107], v[176:179], v[208:211], v[104:107]
	v_mfma_f32_16x16x32_bf16 v[92:95], v[152:155], v[216:219], v[92:95]
	v_mfma_f32_16x16x32_bf16 v[88:91], v[176:179], v[216:219], v[88:91]
	v_mfma_f32_16x16x32_bf16 v[76:79], v[152:155], v[226:229], v[76:79]
	v_mfma_f32_16x16x32_bf16 v[72:75], v[176:179], v[226:229], v[72:75]
	v_mfma_f32_16x16x32_bf16 v[124:127], v[172:175], v[204:207], v[124:127]
	v_mfma_f32_16x16x32_bf16 v[120:123], v[180:183], v[204:207], v[120:123]
	v_mfma_f32_16x16x32_bf16 v[108:111], v[172:175], v[212:215], v[108:111]
	v_mfma_f32_16x16x32_bf16 v[104:107], v[180:183], v[212:215], v[104:107]
	v_mfma_f32_16x16x32_bf16 v[92:95], v[172:175], v[220:223], v[92:95]
	v_mfma_f32_16x16x32_bf16 v[88:91], v[180:183], v[220:223], v[88:91]
	v_mfma_f32_16x16x32_bf16 v[76:79], v[172:175], v[230:233], v[76:79]
	v_mfma_f32_16x16x32_bf16 v[72:75], v[180:183], v[230:233], v[72:75]
	v_mfma_f32_16x16x32_bf16 v[116:119], v[184:187], v[200:203], v[116:119]
	v_mfma_f32_16x16x32_bf16 v[112:115], v[192:195], v[200:203], v[112:115]
	v_mfma_f32_16x16x32_bf16 v[100:103], v[184:187], v[208:211], v[100:103]
	v_mfma_f32_16x16x32_bf16 v[96:99], v[192:195], v[208:211], v[96:99]
	v_mfma_f32_16x16x32_bf16 v[84:87], v[184:187], v[216:219], v[84:87]
	v_mfma_f32_16x16x32_bf16 v[80:83], v[192:195], v[216:219], v[80:83]
	v_mfma_f32_16x16x32_bf16 v[68:71], v[184:187], v[226:229], v[68:71]
	v_mfma_f32_16x16x32_bf16 v[64:67], v[192:195], v[226:229], v[64:67]
	v_mfma_f32_16x16x32_bf16 v[116:119], v[188:191], v[204:207], v[116:119]
	v_mfma_f32_16x16x32_bf16 v[112:115], v[196:199], v[204:207], v[112:115]
	v_mfma_f32_16x16x32_bf16 v[100:103], v[188:191], v[212:215], v[100:103]
	v_mfma_f32_16x16x32_bf16 v[96:99], v[196:199], v[212:215], v[96:99]
	v_mfma_f32_16x16x32_bf16 v[84:87], v[188:191], v[220:223], v[84:87]
	v_mfma_f32_16x16x32_bf16 v[80:83], v[196:199], v[220:223], v[80:83]
	v_mfma_f32_16x16x32_bf16 v[68:71], v[188:191], v[230:233], v[68:71]
	v_mfma_f32_16x16x32_bf16 v[64:67], v[196:199], v[230:233], v[64:67]
	s_setprio 0
	s_barrier
; #define PG8_STAGE(bufoff, gbase, voff) do { _Pragma("unroll") for (int _i = 0; _i < 2; ++_i) \
;         __builtin_amdgcn_global_load_lds((const unsigned*)((const char*)(gbase) + (voff)[_i]), (LAS unsigned*)(lds + (bufoff) + ldsw + _i * 8192), 16, 0, 0); } while (0)
; #define PG8_LDA(dst, b, h) do { _Pragma("unroll") for (int m = 0; m < 4; ++m) _Pragma("unroll") for (int k = 0; k < 2; ++k) dst[m][k] = *(const LAS bf16x8*)(lds + PG8_SA(b, h) + aoff + m * 2048 + k * 1024); } while (0)
; #define PG8_MMA(ai, bj, At, Bt) do { __builtin_amdgcn_s_setprio(1); _Pragma("unroll") for (int m = 0; m < 4; ++m) _Pragma("unroll") for (int n = 0; n < 2; ++n) _Pragma("unroll") for (int k = 0; k < 2; ++k) \
;         acc[ai][bj][m][n] = __builtin_amdgcn_mfma_f32_16x16x32_bf16(Bt[n][k], At[m][k], acc[ai][bj][m][n], 0, 0, 0); __builtin_amdgcn_s_setprio(0); } while (0)
; #define PG8_WAIT_V(n) asm volatile("s_waitcnt vmcnt(" #n ")" ::: "memory")
; #define PG8_WAIT_L(n) asm volatile("s_waitcnt lgkmcnt(" #n ")" ::: "memory")
; #define PG8_BAR __builtin_amdgcn_s_barrier()
; #define PG8_SCHED __builtin_amdgcn_sched_barrier(0)
; template <class Epi>
; __device__ __forceinline__ void gemm_phase(LAS unsigned char* lds, const Gemm g, const StaticOrder& S, const Epi& E, const int tid) {
;     ...
;             PG8_LDA(At, 1, 1); PG8_STAGE(PG8_SB(1, 0), b3, voffB); PG8_STAGE(PG8_SB(1, 1), b3 + hstep, voffB); PG8_STAGE(PG8_SA(1, 0), a3, voffA);
;             PG8_WAIT_V(8); PG8_WAIT_L(0); PG8_BAR; PG8_MMA(1, 0, At, B0); PG8_MMA(1, 1, At, B1); PG8_BAR; PG8_SCHED;
;         }
;         if (wr == 0) PG8_BAR;
	s_add_i32 s34, s80, s20
	v_lshl_add_u64 v[234:235], v[234:235], 0, s[46:47]
	s_mov_b32 m0, s34
	ds_read_b128 v[200:203], v165 offset:49152
	ds_read_b128 v[204:207], v165 offset:50176
	ds_read_b128 v[208:211], v165 offset:51200
	ds_read_b128 v[212:215], v165 offset:52224
	ds_read_b128 v[216:219], v165 offset:53248
	ds_read_b128 v[220:223], v165 offset:54272
	ds_read_b128 v[226:229], v165 offset:55296
	ds_read_b128 v[230:233], v165 offset:56320
	global_load_lds_dwordx4 v[234:235], off
	s_add_i32 m0, s34, 0x2000
	s_add_u32 s28, s28, 0x80080
	v_lshl_add_u64 v[234:235], v[236:237], 0, s[46:47]
	s_addc_u32 s29, s29, 0
	s_add_i32 s34, s81, s20
	global_load_lds_dwordx4 v[234:235], off
	v_lshl_add_u64 v[234:235], s[28:29], 0, v[130:131]
	s_mov_b32 m0, s34
	s_nop 0
	global_load_lds_dwordx4 v[234:235], off
	v_lshl_add_u64 v[234:235], s[28:29], 0, v[134:135]
	s_add_i32 m0, s34, 0x2000
	s_nop 0
	global_load_lds_dwordx4 v[234:235], off
	v_lshl_add_u64 v[234:235], v[238:239], 0, s[46:47]
	s_mov_b32 m0, s61
	s_nop 0
	global_load_lds_dwordx4 v[234:235], off
	v_lshl_add_u64 v[234:235], v[240:241], 0, s[46:47]
	s_mov_b32 m0, s62
	s_nop 0
	global_load_lds_dwordx4 v[234:235], off
	s_waitcnt vmcnt(8)
	s_waitcnt lgkmcnt(0)
	s_barrier
	s_setprio 1
	s_waitcnt lgkmcnt(0)
	v_mfma_f32_16x16x32_bf16 v[60:63], v[152:155], v[200:203], v[60:63]
	v_mfma_f32_16x16x32_bf16 v[56:59], v[176:179], v[200:203], v[56:59]
	v_mfma_f32_16x16x32_bf16 v[44:47], v[152:155], v[208:211], v[44:47]
	v_mfma_f32_16x16x32_bf16 v[40:43], v[176:179], v[208:211], v[40:43]
	v_mfma_f32_16x16x32_bf16 v[28:31], v[152:155], v[216:219], v[28:31]
	v_mfma_f32_16x16x32_bf16 v[24:27], v[176:179], v[216:219], v[24:27]
	v_mfma_f32_16x16x32_bf16 v[12:15], v[152:155], v[226:229], v[12:15]
	v_mfma_f32_16x16x32_bf16 v[8:11], v[176:179], v[226:229], v[8:11]
	v_mfma_f32_16x16x32_bf16 v[60:63], v[172:175], v[204:207], v[60:63]
	v_mfma_f32_16x16x32_bf16 v[56:59], v[180:183], v[204:207], v[56:59]
	v_mfma_f32_16x16x32_bf16 v[44:47], v[172:175], v[212:215], v[44:47]
	v_mfma_f32_16x16x32_bf16 v[40:43], v[180:183], v[212:215], v[40:43]
	v_mfma_f32_16x16x32_bf16 v[28:31], v[172:175], v[220:223], v[28:31]
	v_mfma_f32_16x16x32_bf16 v[24:27], v[180:183], v[220:223], v[24:27]
	v_mfma_f32_16x16x32_bf16 v[12:15], v[172:175], v[230:233], v[12:15]
	v_mfma_f32_16x16x32_bf16 v[8:11], v[180:183], v[230:233], v[8:11]
	v_mfma_f32_16x16x32_bf16 v[52:55], v[184:187], v[200:203], v[52:55]
	v_mfma_f32_16x16x32_bf16 v[48:51], v[192:195], v[200:203], v[48:51]
	v_mfma_f32_16x16x32_bf16 v[36:39], v[184:187], v[208:211], v[36:39]
	v_mfma_f32_16x16x32_bf16 v[32:35], v[192:195], v[208:211], v[32:35]
	v_mfma_f32_16x16x32_bf16 v[20:23], v[184:187], v[216:219], v[20:23]
	v_mfma_f32_16x16x32_bf16 v[16:19], v[192:195], v[216:219], v[16:19]
	v_mfma_f32_16x16x32_bf16 v[4:7], v[184:187], v[226:229], v[4:7]
	v_mfma_f32_16x16x32_bf16 v[0:3], v[192:195], v[226:229], v[0:3]
	v_mfma_f32_16x16x32_bf16 v[52:55], v[188:191], v[204:207], v[52:55]
	v_mfma_f32_16x16x32_bf16 v[48:51], v[196:199], v[204:207], v[48:51]
	v_mfma_f32_16x16x32_bf16 v[36:39], v[188:191], v[212:215], v[36:39]
	v_mfma_f32_16x16x32_bf16 v[32:35], v[196:199], v[212:215], v[32:35]
	v_mfma_f32_16x16x32_bf16 v[20:23], v[188:191], v[220:223], v[20:23]
	v_mfma_f32_16x16x32_bf16 v[16:19], v[196:199], v[220:223], v[16:19]
	v_mfma_f32_16x16x32_bf16 v[4:7], v[188:191], v[230:233], v[4:7]
	v_mfma_f32_16x16x32_bf16 v[0:3], v[196:199], v[230:233], v[0:3]
	s_setprio 0
	s_barrier
	s_add_i32 s79, s79, 2
	s_add_u32 s77, s77, 0x100
	s_addc_u32 s78, s78, 0
	s_add_u32 s26, s26, 0x100
	s_addc_u32 s27, s27, 0
	s_cmp_gt_u32 s79, 29
	s_cbranch_scc0 .LBB0_628
	s_and_b64 vcc, exec, s[48:49]
	s_cbranch_vccz .LBB0_631
	s_barrier

; #define PG8_STAGE(bufoff, gbase, voff) do { _Pragma("unroll") for (int _i = 0; _i < 2; ++_i) \
;         __builtin_amdgcn_global_load_lds((const unsigned*)((const char*)(gbase) + (voff)[_i]), (LAS unsigned*)(lds + (bufoff) + ldsw + _i * 8192), 16, 0, 0); } while (0)
; #define PG8_LDA(dst, b, h) do { _Pragma("unroll") for (int m = 0; m < 4; ++m) _Pragma("unroll") for (int k = 0; k < 2; ++k) dst[m][k] = *(const LAS bf16x8*)(lds + PG8_SA(b, h) + aoff + m * 2048 + k * 1024); } while (0)
; #define PG8_LDB(dst, b, h) do { _Pragma("unroll") for (int n = 0; n < 2; ++n) _Pragma("unroll") for (int k = 0; k < 2; ++k) dst[n][k] = *(const LAS bf16x8*)(lds + PG8_SB(b, h) + boff + n * 2048 + k * 1024); } while (0)
; #define PG8_MMA(ai, bj, At, Bt) do { __builtin_amdgcn_s_setprio(1); _Pragma("unroll") for (int m = 0; m < 4; ++m) _Pragma("unroll") for (int n = 0; n < 2; ++n) _Pragma("unroll") for (int k = 0; k < 2; ++k) \
;         acc[ai][bj][m][n] = __builtin_amdgcn_mfma_f32_16x16x32_bf16(Bt[n][k], At[m][k], acc[ai][bj][m][n], 0, 0, 0); __builtin_amdgcn_s_setprio(0); } while (0)
; #define PG8_WAIT_V(n) asm volatile("s_waitcnt vmcnt(" #n ")" ::: "memory")
; #define PG8_BAR __builtin_amdgcn_s_barrier()
; template <class Epi>
; __device__ __forceinline__ void gemm_phase(LAS unsigned char* lds, const Gemm g, const StaticOrder& S, const Epi& E, const int tid) {
;     ...
;         const char* nA = has_next ? (const char*)g.A + (size_t)nxt.pm * tstep : cA; const char* nB = has_next ? (const char*)g.Bt + (size_t)nxt.pn * tstep : cB;
;         for (int t = 0; t < nt; t += 2) {
;             const bool last = (t == nt - 2);
;             const char* a1 = cA + (size_t)(t + 1) * kstep;
;             const char* a2 = last ? nA : cA + (size_t)(t + 2) * kstep; const char* b2 = last ? nB : cB + (size_t)(t + 2) * kstep;
;             const char* a3 = a2 + kstep; const char* b3 = b2 + kstep;
;             PG8_LDB(B0, 0, 0); PG8_LDB(B1, 0, 1); PG8_SCHED; PG8_LDA(At, 0, 0); PG8_STAGE(PG8_SA(1, 1), a1 + hstep, voffA);
;             PG8_WAIT_V(8); PG8_WAIT_L(0); PG8_BAR; PG8_MMA(0, 0, At, B0); PG8_MMA(0, 1, At, B1); PG8_BAR; PG8_SCHED;
;             PG8_LDA(At, 0, 1); PG8_STAGE(PG8_SB(0, 0), b2, voffB); PG8_STAGE(PG8_SB(0, 1), b2 + hstep, voffB); PG8_STAGE(PG8_SA(0, 0), a2, voffA);
;             PG8_WAIT_V(8); PG8_WAIT_L(0); PG8_BAR; PG8_MMA(1, 0, At, B0); PG8_MMA(1, 1, At, B1); PG8_BAR; PG8_SCHED;
.LBB0_1533:
	ds_read_b128 v[154:157], v150
	ds_read_b128 v[158:161], v150 offset:1024
	ds_read_b128 v[162:165], v150 offset:2048
	ds_read_b128 v[166:169], v150 offset:3072
	ds_read_b128 v[170:173], v151
	ds_read_b128 v[174:177], v151 offset:1024
	ds_read_b128 v[178:181], v151 offset:2048
	ds_read_b128 v[182:185], v151 offset:3072
	s_add_u32 s46, s44, 0xfff80080
	s_addc_u32 s47, s45, -1
	s_cmp_eq_u32 s61, 28
	s_cselect_b32 s49, s35, s47
	s_cselect_b32 s48, s57, s46
	s_cselect_b32 s47, s29, s60
	s_cselect_b32 s46, s58, s59
	v_lshl_add_u64 v[144:145], s[44:45], 0, v[138:139]
	s_add_i32 m0, s31, 0xc000
	ds_read_b128 v[186:189], v152
	ds_read_b128 v[190:193], v152 offset:1024
	ds_read_b128 v[194:197], v152 offset:2048
	ds_read_b128 v[198:201], v152 offset:3072
	ds_read_b128 v[202:205], v152 offset:4096
	ds_read_b128 v[206:209], v152 offset:5120
	ds_read_b128 v[210:213], v152 offset:6144
	ds_read_b128 v[214:217], v152 offset:7168
	global_load_lds_dwordx4 v[144:145], off
	v_lshl_add_u64 v[144:145], s[44:45], 0, v[136:137]
	s_add_i32 m0, s31, 0xe000
	s_nop 0
	global_load_lds_dwordx4 v[144:145], off
	s_waitcnt vmcnt(8)
	s_waitcnt lgkmcnt(0)
	s_barrier
	s_setprio 1
	s_waitcnt lgkmcnt(0)
	v_mfma_f32_16x16x32_bf16 v[124:127], v[154:157], v[186:189], v[124:127]
	v_mfma_f32_16x16x32_bf16 v[120:123], v[162:165], v[186:189], v[120:123]
	v_mfma_f32_16x16x32_bf16 v[116:119], v[154:157], v[194:197], v[116:119]
	v_mfma_f32_16x16x32_bf16 v[108:111], v[162:165], v[194:197], v[108:111]
	v_mfma_f32_16x16x32_bf16 v[100:103], v[154:157], v[202:205], v[100:103]
	v_mfma_f32_16x16x32_bf16 v[92:95], v[162:165], v[202:205], v[92:95]
	v_mfma_f32_16x16x32_bf16 v[84:87], v[154:157], v[210:213], v[84:87]
	v_mfma_f32_16x16x32_bf16 v[76:79], v[162:165], v[210:213], v[76:79]
	v_mfma_f32_16x16x32_bf16 v[124:127], v[158:161], v[190:193], v[124:127]
	v_mfma_f32_16x16x32_bf16 v[120:123], v[166:169], v[190:193], v[120:123]
	v_mfma_f32_16x16x32_bf16 v[116:119], v[158:161], v[198:201], v[116:119]
	v_mfma_f32_16x16x32_bf16 v[108:111], v[166:169], v[198:201], v[108:111]
	v_mfma_f32_16x16x32_bf16 v[100:103], v[158:161], v[206:209], v[100:103]
	v_mfma_f32_16x16x32_bf16 v[92:95], v[166:169], v[206:209], v[92:95]
	v_mfma_f32_16x16x32_bf16 v[84:87], v[158:161], v[214:217], v[84:87]
	v_mfma_f32_16x16x32_bf16 v[76:79], v[166:169], v[214:217], v[76:79]
	v_mfma_f32_16x16x32_bf16 v[112:115], v[170:173], v[186:189], v[112:115]
	v_mfma_f32_16x16x32_bf16 v[104:107], v[178:181], v[186:189], v[104:107]
	v_mfma_f32_16x16x32_bf16 v[96:99], v[170:173], v[194:197], v[96:99]
	v_mfma_f32_16x16x32_bf16 v[88:91], v[178:181], v[194:197], v[88:91]
	v_mfma_f32_16x16x32_bf16 v[80:83], v[170:173], v[202:205], v[80:83]
	v_mfma_f32_16x16x32_bf16 v[72:75], v[178:181], v[202:205], v[72:75]
	v_mfma_f32_16x16x32_bf16 v[68:71], v[170:173], v[210:213], v[68:71]
	v_mfma_f32_16x16x32_bf16 v[64:67], v[178:181], v[210:213], v[64:67]
	v_mfma_f32_16x16x32_bf16 v[112:115], v[174:177], v[190:193], v[112:115]
	v_mfma_f32_16x16x32_bf16 v[104:107], v[182:185], v[190:193], v[104:107]
	v_mfma_f32_16x16x32_bf16 v[96:99], v[174:177], v[198:201], v[96:99]
	v_mfma_f32_16x16x32_bf16 v[88:91], v[182:185], v[198:201], v[88:91]
	v_mfma_f32_16x16x32_bf16 v[80:83], v[174:177], v[206:209], v[80:83]
	v_mfma_f32_16x16x32_bf16 v[72:75], v[182:185], v[206:209], v[72:75]
	v_mfma_f32_16x16x32_bf16 v[68:71], v[174:177], v[214:217], v[68:71]
	v_mfma_f32_16x16x32_bf16 v[64:67], v[182:185], v[214:217], v[64:67]
	s_setprio 0
	s_barrier
	s_add_i32 s62, s54, s30
	v_lshl_add_u64 v[144:145], s[46:47], 0, v[130:131]
	s_mov_b32 m0, s62
	ds_read_b128 v[186:189], v152 offset:16384
	ds_read_b128 v[190:193], v152 offset:17408
	ds_read_b128 v[194:197], v152 offset:18432
	ds_read_b128 v[198:201], v152 offset:19456
	ds_read_b128 v[202:205], v152 offset:20480
	ds_read_b128 v[206:209], v152 offset:21504
	ds_read_b128 v[210:213], v152 offset:22528
	ds_read_b128 v[214:217], v152 offset:23552
	global_load_lds_dwordx4 v[144:145], off
	s_add_i32 m0, s62, 0x2000
	s_add_u32 s62, s46, 0x80000
	v_lshl_add_u64 v[218:219], s[46:47], 0, v[134:135]
	s_addc_u32 s63, s47, 0
	s_add_i32 s64, s55, s30
	global_load_lds_dwordx4 v[218:219], off
	v_lshl_add_u64 v[220:221], s[62:63], 0, v[130:131]
	s_mov_b32 m0, s64
	v_lshl_add_u64 v[222:223], s[48:49], 0, v[132:133]
	global_load_lds_dwordx4 v[220:221], off
	v_lshl_add_u64 v[220:221], s[62:63], 0, v[134:135]
	s_add_i32 m0, s64, 0x2000
	s_nop 0
	global_load_lds_dwordx4 v[220:221], off
	v_lshl_add_u64 v[220:221], s[48:49], 0, v[128:129]
	s_mov_b32 m0, s31
	s_nop 0
	global_load_lds_dwordx4 v[220:221], off
	s_mov_b32 m0, s39
	s_nop 0
	global_load_lds_dwordx4 v[222:223], off
	s_waitcnt vmcnt(8)
	s_waitcnt lgkmcnt(0)
	s_barrier
; #define PG8_STAGE(bufoff, gbase, voff) do { _Pragma("unroll") for (int _i = 0; _i < 2; ++_i) \
;         __builtin_amdgcn_global_load_lds((const unsigned*)((const char*)(gbase) + (voff)[_i]), (LAS unsigned*)(lds + (bufoff) + ldsw + _i * 8192), 16, 0, 0); } while (0)
; #define PG8_LDA(dst, b, h) do { _Pragma("unroll") for (int m = 0; m < 4; ++m) _Pragma("unroll") for (int k = 0; k < 2; ++k) dst[m][k] = *(const LAS bf16x8*)(lds + PG8_SA(b, h) + aoff + m * 2048 + k * 1024); } while (0)
; #define PG8_LDB(dst, b, h) do { _Pragma("unroll") for (int n = 0; n < 2; ++n) _Pragma("unroll") for (int k = 0; k < 2; ++k) dst[n][k] = *(const LAS bf16x8*)(lds + PG8_SB(b, h) + boff + n * 2048 + k * 1024); } while (0)
; #define PG8_MMA(ai, bj, At, Bt) do { __builtin_amdgcn_s_setprio(1); _Pragma("unroll") for (int m = 0; m < 4; ++m) _Pragma("unroll") for (int n = 0; n < 2; ++n) _Pragma("unroll") for (int k = 0; k < 2; ++k) \
;         acc[ai][bj][m][n] = __builtin_amdgcn_mfma_f32_16x16x32_bf16(Bt[n][k], At[m][k], acc[ai][bj][m][n], 0, 0, 0); __builtin_amdgcn_s_setprio(0); } while (0)
; #define PG8_WAIT_V(n) asm volatile("s_waitcnt vmcnt(" #n ")" ::: "memory")
; #define PG8_WAIT_L(n) asm volatile("s_waitcnt lgkmcnt(" #n ")" ::: "memory")
; #define PG8_BAR __builtin_amdgcn_s_barrier()
; #define PG8_SCHED __builtin_amdgcn_sched_barrier(0)
; template <class Epi>
; __device__ __forceinline__ void gemm_phase(LAS unsigned char* lds, const Gemm g, const StaticOrder& S, const Epi& E, const int tid) {
;     ...
;             PG8_WAIT_V(8); PG8_WAIT_L(0); PG8_BAR; PG8_MMA(1, 0, At, B0); PG8_MMA(1, 1, At, B1); PG8_BAR; PG8_SCHED;
;             PG8_LDB(B0, 1, 0); PG8_LDB(B1, 1, 1); PG8_SCHED; PG8_LDA(At, 1, 0); PG8_STAGE(PG8_SA(0, 1), a2 + hstep, voffA);
;             PG8_WAIT_V(8); PG8_WAIT_L(0); PG8_BAR; PG8_MMA(0, 0, At, B0); PG8_MMA(0, 1, At, B1); PG8_BAR; PG8_SCHED;
	s_setprio 1
	s_waitcnt lgkmcnt(0)
	v_mfma_f32_16x16x32_bf16 v[60:63], v[154:157], v[186:189], v[60:63]
	v_mfma_f32_16x16x32_bf16 v[56:59], v[162:165], v[186:189], v[56:59]
	v_mfma_f32_16x16x32_bf16 v[52:55], v[154:157], v[194:197], v[52:55]
	v_mfma_f32_16x16x32_bf16 v[44:47], v[162:165], v[194:197], v[44:47]
	v_mfma_f32_16x16x32_bf16 v[36:39], v[154:157], v[202:205], v[36:39]
	v_mfma_f32_16x16x32_bf16 v[28:31], v[162:165], v[202:205], v[28:31]
	v_mfma_f32_16x16x32_bf16 v[20:23], v[154:157], v[210:213], v[20:23]
	v_mfma_f32_16x16x32_bf16 v[12:15], v[162:165], v[210:213], v[12:15]
	v_mfma_f32_16x16x32_bf16 v[60:63], v[158:161], v[190:193], v[60:63]
	v_mfma_f32_16x16x32_bf16 v[56:59], v[166:169], v[190:193], v[56:59]
	v_mfma_f32_16x16x32_bf16 v[52:55], v[158:161], v[198:201], v[52:55]
	v_mfma_f32_16x16x32_bf16 v[44:47], v[166:169], v[198:201], v[44:47]
	v_mfma_f32_16x16x32_bf16 v[36:39], v[158:161], v[206:209], v[36:39]
	v_mfma_f32_16x16x32_bf16 v[28:31], v[166:169], v[206:209], v[28:31]
	v_mfma_f32_16x16x32_bf16 v[20:23], v[158:161], v[214:217], v[20:23]
	v_mfma_f32_16x16x32_bf16 v[12:15], v[166:169], v[214:217], v[12:15]
	v_mfma_f32_16x16x32_bf16 v[48:51], v[170:173], v[186:189], v[48:51]
	v_mfma_f32_16x16x32_bf16 v[40:43], v[178:181], v[186:189], v[40:43]
	v_mfma_f32_16x16x32_bf16 v[32:35], v[170:173], v[194:197], v[32:35]
	v_mfma_f32_16x16x32_bf16 v[24:27], v[178:181], v[194:197], v[24:27]
	v_mfma_f32_16x16x32_bf16 v[16:19], v[170:173], v[202:205], v[16:19]
	v_mfma_f32_16x16x32_bf16 v[8:11], v[178:181], v[202:205], v[8:11]
	v_mfma_f32_16x16x32_bf16 v[4:7], v[170:173], v[210:213], v[4:7]
	v_mfma_f32_16x16x32_bf16 v[0:3], v[178:181], v[210:213], v[0:3]
	v_mfma_f32_16x16x32_bf16 v[48:51], v[174:177], v[190:193], v[48:51]
	v_mfma_f32_16x16x32_bf16 v[40:43], v[182:185], v[190:193], v[40:43]
	v_mfma_f32_16x16x32_bf16 v[32:35], v[174:177], v[198:201], v[32:35]
	v_mfma_f32_16x16x32_bf16 v[24:27], v[182:185], v[198:201], v[24:27]
	v_mfma_f32_16x16x32_bf16 v[16:19], v[174:177], v[206:209], v[16:19]
	v_mfma_f32_16x16x32_bf16 v[8:11], v[182:185], v[206:209], v[8:11]
	v_mfma_f32_16x16x32_bf16 v[4:7], v[174:177], v[214:217], v[4:7]
	v_mfma_f32_16x16x32_bf16 v[0:3], v[182:185], v[214:217], v[0:3]
	s_setprio 0
	s_barrier
	s_add_i32 s62, 0, 0x18000
	v_add_u32_e32 v153, s62, v148
	s_add_i32 s63, 0, 0x1c000
	ds_read_b128 v[154:157], v153
	ds_read_b128 v[158:161], v153 offset:1024
	ds_read_b128 v[162:165], v153 offset:2048
	ds_read_b128 v[166:169], v153 offset:3072
	v_add_u32_e32 v153, s63, v148
	ds_read_b128 v[170:173], v153
	ds_read_b128 v[174:177], v153 offset:1024
	ds_read_b128 v[178:181], v153 offset:2048
	ds_read_b128 v[182:185], v153 offset:3072
	s_add_u32 s48, s48, 0x80000
	s_addc_u32 s49, s49, 0
	s_mov_b32 m0, s50
	v_lshl_add_u64 v[226:227], s[48:49], 0, v[128:129]
	ds_read_b128 v[186:189], v152 offset:32768
	ds_read_b128 v[190:193], v152 offset:33792
	ds_read_b128 v[194:197], v152 offset:34816
	ds_read_b128 v[198:201], v152 offset:35840
	ds_read_b128 v[202:205], v152 offset:36864
	ds_read_b128 v[206:209], v152 offset:37888
	ds_read_b128 v[210:213], v152 offset:38912
	ds_read_b128 v[214:217], v152 offset:39936
	global_load_lds_dwordx4 v[226:227], off
	v_lshl_add_u64 v[226:227], s[48:49], 0, v[132:133]
	s_mov_b32 m0, s51
	s_nop 0
	global_load_lds_dwordx4 v[226:227], off
	s_waitcnt vmcnt(8)
	s_waitcnt lgkmcnt(0)
	s_barrier
	s_setprio 1
	s_waitcnt lgkmcnt(0)
	v_mfma_f32_16x16x32_bf16 v[124:127], v[154:157], v[186:189], v[124:127]
	v_mfma_f32_16x16x32_bf16 v[120:123], v[162:165], v[186:189], v[120:123]
	v_mfma_f32_16x16x32_bf16 v[116:119], v[154:157], v[194:197], v[116:119]
	v_mfma_f32_16x16x32_bf16 v[108:111], v[162:165], v[194:197], v[108:111]
	v_mfma_f32_16x16x32_bf16 v[100:103], v[154:157], v[202:205], v[100:103]
	v_mfma_f32_16x16x32_bf16 v[92:95], v[162:165], v[202:205], v[92:95]
	v_mfma_f32_16x16x32_bf16 v[84:87], v[154:157], v[210:213], v[84:87]
	v_mfma_f32_16x16x32_bf16 v[76:79], v[162:165], v[210:213], v[76:79]
	v_mfma_f32_16x16x32_bf16 v[124:127], v[158:161], v[190:193], v[124:127]
	v_mfma_f32_16x16x32_bf16 v[120:123], v[166:169], v[190:193], v[120:123]
	v_mfma_f32_16x16x32_bf16 v[116:119], v[158:161], v[198:201], v[116:119]
	v_mfma_f32_16x16x32_bf16 v[108:111], v[166:169], v[198:201], v[108:111]
	v_mfma_f32_16x16x32_bf16 v[100:103], v[158:161], v[206:209], v[100:103]
	v_mfma_f32_16x16x32_bf16 v[92:95], v[166:169], v[206:209], v[92:95]
	v_mfma_f32_16x16x32_bf16 v[84:87], v[158:161], v[214:217], v[84:87]
	v_mfma_f32_16x16x32_bf16 v[76:79], v[166:169], v[214:217], v[76:79]
	v_mfma_f32_16x16x32_bf16 v[112:115], v[170:173], v[186:189], v[112:115]
	v_mfma_f32_16x16x32_bf16 v[104:107], v[178:181], v[186:189], v[104:107]
	v_mfma_f32_16x16x32_bf16 v[96:99], v[170:173], v[194:197], v[96:99]
	v_mfma_f32_16x16x32_bf16 v[88:91], v[178:181], v[194:197], v[88:91]
	v_mfma_f32_16x16x32_bf16 v[80:83], v[170:173], v[202:205], v[80:83]
	v_mfma_f32_16x16x32_bf16 v[72:75], v[178:181], v[202:205], v[72:75]
	v_mfma_f32_16x16x32_bf16 v[68:71], v[170:173], v[210:213], v[68:71]
	v_mfma_f32_16x16x32_bf16 v[64:67], v[178:181], v[210:213], v[64:67]
	v_mfma_f32_16x16x32_bf16 v[112:115], v[174:177], v[190:193], v[112:115]
	v_mfma_f32_16x16x32_bf16 v[104:107], v[182:185], v[190:193], v[104:107]
	v_mfma_f32_16x16x32_bf16 v[96:99], v[174:177], v[198:201], v[96:99]
	v_mfma_f32_16x16x32_bf16 v[88:91], v[182:185], v[198:201], v[88:91]
	v_mfma_f32_16x16x32_bf16 v[80:83], v[174:177], v[206:209], v[80:83]
	v_mfma_f32_16x16x32_bf16 v[72:75], v[182:185], v[206:209], v[72:75]
	v_mfma_f32_16x16x32_bf16 v[68:71], v[174:177], v[214:217], v[68:71]
	v_mfma_f32_16x16x32_bf16 v[64:67], v[182:185], v[214:217], v[64:67]
	s_setprio 0
	s_barrier
; #define PG8_STAGE(bufoff, gbase, voff) do { _Pragma("unroll") for (int _i = 0; _i < 2; ++_i) \
;         __builtin_amdgcn_global_load_lds((const unsigned*)((const char*)(gbase) + (voff)[_i]), (LAS unsigned*)(lds + (bufoff) + ldsw + _i * 8192), 16, 0, 0); } while (0)
; #define PG8_LDA(dst, b, h) do { _Pragma("unroll") for (int m = 0; m < 4; ++m) _Pragma("unroll") for (int k = 0; k < 2; ++k) dst[m][k] = *(const LAS bf16x8*)(lds + PG8_SA(b, h) + aoff + m * 2048 + k * 1024); } while (0)
; #define PG8_MMA(ai, bj, At, Bt) do { __builtin_amdgcn_s_setprio(1); _Pragma("unroll") for (int m = 0; m < 4; ++m) _Pragma("unroll") for (int n = 0; n < 2; ++n) _Pragma("unroll") for (int k = 0; k < 2; ++k) \
;         acc[ai][bj][m][n] = __builtin_amdgcn_mfma_f32_16x16x32_bf16(Bt[n][k], At[m][k], acc[ai][bj][m][n], 0, 0, 0); __builtin_amdgcn_s_setprio(0); } while (0)
; #define PG8_WAIT_V(n) asm volatile("s_waitcnt vmcnt(" #n ")" ::: "memory")
; #define PG8_WAIT_L(n) asm volatile("s_waitcnt lgkmcnt(" #n ")" ::: "memory")
; #define PG8_BAR __builtin_amdgcn_s_barrier()
; #define PG8_SCHED __builtin_amdgcn_sched_barrier(0)
; template <class Epi>
; __device__ __forceinline__ void gemm_phase(LAS unsigned char* lds, const Gemm g, const StaticOrder& S, const Epi& E, const int tid) {
;     ...
;             PG8_LDA(At, 1, 1); PG8_STAGE(PG8_SB(1, 0), b3, voffB); PG8_STAGE(PG8_SB(1, 1), b3 + hstep, voffB); PG8_STAGE(PG8_SA(1, 0), a3, voffA);
;             PG8_WAIT_V(8); PG8_WAIT_L(0); PG8_BAR; PG8_MMA(1, 0, At, B0); PG8_MMA(1, 1, At, B1); PG8_BAR; PG8_SCHED;
;         }
;         if (wr == 0) PG8_BAR;
	s_add_i32 s48, s62, s30
	v_lshl_add_u64 v[144:145], v[144:145], 0, s[24:25]
	s_mov_b32 m0, s48
	ds_read_b128 v[186:189], v152 offset:49152
	ds_read_b128 v[190:193], v152 offset:50176
	ds_read_b128 v[194:197], v152 offset:51200
	ds_read_b128 v[198:201], v152 offset:52224
	ds_read_b128 v[202:205], v152 offset:53248
	ds_read_b128 v[206:209], v152 offset:54272
	ds_read_b128 v[210:213], v152 offset:55296
	ds_read_b128 v[214:217], v152 offset:56320
	global_load_lds_dwordx4 v[144:145], off
	s_add_i32 m0, s48, 0x2000
	s_add_u32 s46, s46, 0x80080
	v_lshl_add_u64 v[144:145], v[218:219], 0, s[24:25]
	s_addc_u32 s47, s47, 0
	s_add_i32 s48, s63, s30
	global_load_lds_dwordx4 v[144:145], off
	v_lshl_add_u64 v[144:145], s[46:47], 0, v[130:131]
	s_mov_b32 m0, s48
	s_nop 0
	global_load_lds_dwordx4 v[144:145], off
	v_lshl_add_u64 v[144:145], s[46:47], 0, v[134:135]
	s_add_i32 m0, s48, 0x2000
	s_nop 0
	global_load_lds_dwordx4 v[144:145], off
	v_lshl_add_u64 v[144:145], v[220:221], 0, s[24:25]
	s_mov_b32 m0, s0
	s_nop 0
	global_load_lds_dwordx4 v[144:145], off
	v_lshl_add_u64 v[144:145], v[222:223], 0, s[24:25]
	s_mov_b32 m0, s53
	s_nop 0
	global_load_lds_dwordx4 v[144:145], off
	s_waitcnt vmcnt(8)
	s_waitcnt lgkmcnt(0)
	s_barrier
	s_setprio 1
	s_waitcnt lgkmcnt(0)
	v_mfma_f32_16x16x32_bf16 v[60:63], v[154:157], v[186:189], v[60:63]
	v_mfma_f32_16x16x32_bf16 v[56:59], v[162:165], v[186:189], v[56:59]
	v_mfma_f32_16x16x32_bf16 v[52:55], v[154:157], v[194:197], v[52:55]
	v_mfma_f32_16x16x32_bf16 v[44:47], v[162:165], v[194:197], v[44:47]
	v_mfma_f32_16x16x32_bf16 v[36:39], v[154:157], v[202:205], v[36:39]
	v_mfma_f32_16x16x32_bf16 v[28:31], v[162:165], v[202:205], v[28:31]
	v_mfma_f32_16x16x32_bf16 v[20:23], v[154:157], v[210:213], v[20:23]
	v_mfma_f32_16x16x32_bf16 v[12:15], v[162:165], v[210:213], v[12:15]
	v_mfma_f32_16x16x32_bf16 v[60:63], v[158:161], v[190:193], v[60:63]
	v_mfma_f32_16x16x32_bf16 v[56:59], v[166:169], v[190:193], v[56:59]
	v_mfma_f32_16x16x32_bf16 v[52:55], v[158:161], v[198:201], v[52:55]
	v_mfma_f32_16x16x32_bf16 v[44:47], v[166:169], v[198:201], v[44:47]
	v_mfma_f32_16x16x32_bf16 v[36:39], v[158:161], v[206:209], v[36:39]
	v_mfma_f32_16x16x32_bf16 v[28:31], v[166:169], v[206:209], v[28:31]
	v_mfma_f32_16x16x32_bf16 v[20:23], v[158:161], v[214:217], v[20:23]
	v_mfma_f32_16x16x32_bf16 v[12:15], v[166:169], v[214:217], v[12:15]
	v_mfma_f32_16x16x32_bf16 v[48:51], v[170:173], v[186:189], v[48:51]
	v_mfma_f32_16x16x32_bf16 v[40:43], v[178:181], v[186:189], v[40:43]
	v_mfma_f32_16x16x32_bf16 v[32:35], v[170:173], v[194:197], v[32:35]
	v_mfma_f32_16x16x32_bf16 v[24:27], v[178:181], v[194:197], v[24:27]
	v_mfma_f32_16x16x32_bf16 v[16:19], v[170:173], v[202:205], v[16:19]
	v_mfma_f32_16x16x32_bf16 v[8:11], v[178:181], v[202:205], v[8:11]
	v_mfma_f32_16x16x32_bf16 v[4:7], v[170:173], v[210:213], v[4:7]
	v_mfma_f32_16x16x32_bf16 v[0:3], v[178:181], v[210:213], v[0:3]
	v_mfma_f32_16x16x32_bf16 v[48:51], v[174:177], v[190:193], v[48:51]
	v_mfma_f32_16x16x32_bf16 v[40:43], v[182:185], v[190:193], v[40:43]
	v_mfma_f32_16x16x32_bf16 v[32:35], v[174:177], v[198:201], v[32:35]
	v_mfma_f32_16x16x32_bf16 v[24:27], v[182:185], v[198:201], v[24:27]
	v_mfma_f32_16x16x32_bf16 v[16:19], v[174:177], v[206:209], v[16:19]
	v_mfma_f32_16x16x32_bf16 v[8:11], v[182:185], v[206:209], v[8:11]
	v_mfma_f32_16x16x32_bf16 v[4:7], v[174:177], v[214:217], v[4:7]
	v_mfma_f32_16x16x32_bf16 v[0:3], v[182:185], v[214:217], v[0:3]
	s_setprio 0
	s_barrier
	s_add_i32 s61, s61, 2
	s_add_u32 s59, s59, 0x100
	s_addc_u32 s60, s60, 0
	s_add_u32 s44, s44, 0x100
	s_addc_u32 s45, s45, 0
	s_cmp_gt_u32 s61, 29
	s_cbranch_scc0 .LBB0_1533
	s_and_b64 vcc, exec, s[26:27]
	s_cbranch_vccz .LBB0_1536
	s_barrier

; #define PG8_STAGE(bufoff, gbase, voff) do { _Pragma("unroll") for (int _i = 0; _i < 2; ++_i) \
;         __builtin_amdgcn_global_load_lds((const unsigned*)((const char*)(gbase) + (voff)[_i]), (LAS unsigned*)(lds + (bufoff) + ldsw + _i * 8192), 16, 0, 0); } while (0)
; #define PG8_LDA(dst, b, h) do { _Pragma("unroll") for (int m = 0; m < 4; ++m) _Pragma("unroll") for (int k = 0; k < 2; ++k) dst[m][k] = *(const LAS bf16x8*)(lds + PG8_SA(b, h) + aoff + m * 2048 + k * 1024); } while (0)
; #define PG8_LDB(dst, b, h) do { _Pragma("unroll") for (int n = 0; n < 2; ++n) _Pragma("unroll") for (int k = 0; k < 2; ++k) dst[n][k] = *(const LAS bf16x8*)(lds + PG8_SB(b, h) + boff + n * 2048 + k * 1024); } while (0)
; #define PG8_MMA(ai, bj, At, Bt) do { __builtin_amdgcn_s_setprio(1); _Pragma("unroll") for (int m = 0; m < 4; ++m) _Pragma("unroll") for (int n = 0; n < 2; ++n) _Pragma("unroll") for (int k = 0; k < 2; ++k) \
;         acc[ai][bj][m][n] = __builtin_amdgcn_mfma_f32_16x16x32_bf16(Bt[n][k], At[m][k], acc[ai][bj][m][n], 0, 0, 0); __builtin_amdgcn_s_setprio(0); } while (0)
; #define PG8_WAIT_V(n) asm volatile("s_waitcnt vmcnt(" #n ")" ::: "memory")
; #define PG8_BAR __builtin_amdgcn_s_barrier()
; template <class Epi>
; __device__ __forceinline__ void gemm_phase(LAS unsigned char* lds, const Gemm g, const StaticOrder& S, const Epi& E, const int tid) {
;     ...
;         const char* nA = has_next ? (const char*)g.A + (size_t)nxt.pm * tstep : cA; const char* nB = has_next ? (const char*)g.Bt + (size_t)nxt.pn * tstep : cB;
;         for (int t = 0; t < nt; t += 2) {
;             const bool last = (t == nt - 2);
;             const char* a1 = cA + (size_t)(t + 1) * kstep;
;             const char* a2 = last ? nA : cA + (size_t)(t + 2) * kstep; const char* b2 = last ? nB : cB + (size_t)(t + 2) * kstep;
;             const char* a3 = a2 + kstep; const char* b3 = b2 + kstep;
;             PG8_LDB(B0, 0, 0); PG8_LDB(B1, 0, 1); PG8_SCHED; PG8_LDA(At, 0, 0); PG8_STAGE(PG8_SA(1, 1), a1 + hstep, voffA);
;             PG8_WAIT_V(8); PG8_WAIT_L(0); PG8_BAR; PG8_MMA(0, 0, At, B0); PG8_MMA(0, 1, At, B1); PG8_BAR; PG8_SCHED;
;             PG8_LDA(At, 0, 1); PG8_STAGE(PG8_SB(0, 0), b2, voffB); PG8_STAGE(PG8_SB(0, 1), b2 + hstep, voffB); PG8_STAGE(PG8_SA(0, 0), a2, voffA);
;             PG8_WAIT_V(8); PG8_WAIT_L(0); PG8_BAR; PG8_MMA(1, 0, At, B0); PG8_MMA(1, 1, At, B1); PG8_BAR; PG8_SCHED;
.LBB0_1706:
	s_add_u32 s64, s62, 0xfff80080
	s_addc_u32 s65, s63, -1
	s_add_i32 s95, 0, 0x10000
	s_cmp_eq_u32 s94, 28
	s_cselect_b32 s67, s57, s65
	s_cselect_b32 s66, s90, s64
	v_add_u32_e32 v148, s95, v151
	s_cselect_b32 s65, s55, s93
	s_cselect_b32 s64, s91, s92
	s_add_i32 vcc_lo, 0, 0x14000
	ds_read_b128 v[154:157], v148
	ds_read_b128 v[162:165], v148 offset:1024
	ds_read_b128 v[166:169], v148 offset:2048
	ds_read_b128 v[170:173], v148 offset:3072
	v_add_u32_e32 v148, vcc_lo, v151
	ds_read_b128 v[174:177], v148
	ds_read_b128 v[178:181], v148 offset:1024
	ds_read_b128 v[182:185], v148 offset:2048
	ds_read_b128 v[186:189], v148 offset:3072
	v_lshl_add_u64 v[148:149], s[62:63], 0, v[146:147]
	s_add_i32 m0, s81, 0xc000
	ds_read_b128 v[190:193], v153
	ds_read_b128 v[194:197], v153 offset:1024
	ds_read_b128 v[198:201], v153 offset:2048
	ds_read_b128 v[202:205], v153 offset:3072
	ds_read_b128 v[206:209], v153 offset:4096
	ds_read_b128 v[210:213], v153 offset:5120
	ds_read_b128 v[214:217], v153 offset:6144
	ds_read_b128 v[218:221], v153 offset:7168
	global_load_lds_dwordx4 v[148:149], off
	v_lshl_add_u64 v[148:149], s[62:63], 0, v[144:145]
	s_add_i32 m0, s81, 0xe000
	s_nop 0
	global_load_lds_dwordx4 v[148:149], off
	s_waitcnt vmcnt(8)
	s_waitcnt lgkmcnt(0)
	s_barrier
	s_setprio 1
	s_waitcnt lgkmcnt(0)
	v_mfma_f32_16x16x32_bf16 v[124:127], v[154:157], v[190:193], v[124:127]
	v_mfma_f32_16x16x32_bf16 v[116:119], v[166:169], v[190:193], v[116:119]
	v_mfma_f32_16x16x32_bf16 v[108:111], v[154:157], v[198:201], v[108:111]
	v_mfma_f32_16x16x32_bf16 v[100:103], v[166:169], v[198:201], v[100:103]
	v_mfma_f32_16x16x32_bf16 v[92:95], v[154:157], v[206:209], v[92:95]
	v_mfma_f32_16x16x32_bf16 v[84:87], v[166:169], v[206:209], v[84:87]
	v_mfma_f32_16x16x32_bf16 v[76:79], v[154:157], v[214:217], v[76:79]
	v_mfma_f32_16x16x32_bf16 v[68:71], v[166:169], v[214:217], v[68:71]
	v_mfma_f32_16x16x32_bf16 v[124:127], v[162:165], v[194:197], v[124:127]
	v_mfma_f32_16x16x32_bf16 v[116:119], v[170:173], v[194:197], v[116:119]
	v_mfma_f32_16x16x32_bf16 v[108:111], v[162:165], v[202:205], v[108:111]
	v_mfma_f32_16x16x32_bf16 v[100:103], v[170:173], v[202:205], v[100:103]
	v_mfma_f32_16x16x32_bf16 v[92:95], v[162:165], v[210:213], v[92:95]
	v_mfma_f32_16x16x32_bf16 v[84:87], v[170:173], v[210:213], v[84:87]
	v_mfma_f32_16x16x32_bf16 v[76:79], v[162:165], v[218:221], v[76:79]
	v_mfma_f32_16x16x32_bf16 v[68:71], v[170:173], v[218:221], v[68:71]
	v_mfma_f32_16x16x32_bf16 v[120:123], v[174:177], v[190:193], v[120:123]
	v_mfma_f32_16x16x32_bf16 v[112:115], v[182:185], v[190:193], v[112:115]
	v_mfma_f32_16x16x32_bf16 v[104:107], v[174:177], v[198:201], v[104:107]
	v_mfma_f32_16x16x32_bf16 v[96:99], v[182:185], v[198:201], v[96:99]
	v_mfma_f32_16x16x32_bf16 v[88:91], v[174:177], v[206:209], v[88:91]
	v_mfma_f32_16x16x32_bf16 v[80:83], v[182:185], v[206:209], v[80:83]
	v_mfma_f32_16x16x32_bf16 v[72:75], v[174:177], v[214:217], v[72:75]
	v_mfma_f32_16x16x32_bf16 v[64:67], v[182:185], v[214:217], v[64:67]
	v_mfma_f32_16x16x32_bf16 v[120:123], v[178:181], v[194:197], v[120:123]
	v_mfma_f32_16x16x32_bf16 v[112:115], v[186:189], v[194:197], v[112:115]
	v_mfma_f32_16x16x32_bf16 v[104:107], v[178:181], v[202:205], v[104:107]
	v_mfma_f32_16x16x32_bf16 v[96:99], v[186:189], v[202:205], v[96:99]
	v_mfma_f32_16x16x32_bf16 v[88:91], v[178:181], v[210:213], v[88:91]
	v_mfma_f32_16x16x32_bf16 v[80:83], v[186:189], v[210:213], v[80:83]
	v_mfma_f32_16x16x32_bf16 v[72:75], v[178:181], v[218:221], v[72:75]
	v_mfma_f32_16x16x32_bf16 v[64:67], v[186:189], v[218:221], v[64:67]
	s_setprio 0
	s_barrier
	s_add_i32 s95, s95, s80
	v_lshl_add_u64 v[148:149], s[64:65], 0, v[128:129]
	s_mov_b32 m0, s95
	ds_read_b128 v[190:193], v153 offset:16384
	ds_read_b128 v[194:197], v153 offset:17408
	ds_read_b128 v[198:201], v153 offset:18432
	ds_read_b128 v[202:205], v153 offset:19456
	ds_read_b128 v[206:209], v153 offset:20480
	ds_read_b128 v[210:213], v153 offset:21504
	ds_read_b128 v[214:217], v153 offset:22528
	ds_read_b128 v[218:221], v153 offset:23552
	global_load_lds_dwordx4 v[148:149], off
	s_add_i32 m0, s95, 0x2000
	s_add_u32 s96, s64, 0x80000
	v_lshl_add_u64 v[222:223], s[64:65], 0, v[138:139]
	s_addc_u32 s97, s65, 0
	s_add_i32 s95, vcc_lo, s80
	global_load_lds_dwordx4 v[222:223], off
	v_lshl_add_u64 v[226:227], s[96:97], 0, v[128:129]
	s_mov_b32 m0, s95
	v_lshl_add_u64 v[228:229], s[66:67], 0, v[140:141]
	global_load_lds_dwordx4 v[226:227], off
	v_lshl_add_u64 v[226:227], s[96:97], 0, v[138:139]
	s_add_i32 m0, s95, 0x2000
	s_nop 0
	global_load_lds_dwordx4 v[226:227], off
	v_lshl_add_u64 v[226:227], s[66:67], 0, v[142:143]
	s_mov_b32 m0, s81
	s_nop 0
	global_load_lds_dwordx4 v[226:227], off
	s_mov_b32 m0, s82
	s_nop 0
	global_load_lds_dwordx4 v[228:229], off
	s_waitcnt vmcnt(8)
	s_waitcnt lgkmcnt(0)
	s_barrier
; #define PG8_STAGE(bufoff, gbase, voff) do { _Pragma("unroll") for (int _i = 0; _i < 2; ++_i) \
;         __builtin_amdgcn_global_load_lds((const unsigned*)((const char*)(gbase) + (voff)[_i]), (LAS unsigned*)(lds + (bufoff) + ldsw + _i * 8192), 16, 0, 0); } while (0)
; #define PG8_LDA(dst, b, h) do { _Pragma("unroll") for (int m = 0; m < 4; ++m) _Pragma("unroll") for (int k = 0; k < 2; ++k) dst[m][k] = *(const LAS bf16x8*)(lds + PG8_SA(b, h) + aoff + m * 2048 + k * 1024); } while (0)
; #define PG8_LDB(dst, b, h) do { _Pragma("unroll") for (int n = 0; n < 2; ++n) _Pragma("unroll") for (int k = 0; k < 2; ++k) dst[n][k] = *(const LAS bf16x8*)(lds + PG8_SB(b, h) + boff + n * 2048 + k * 1024); } while (0)
; #define PG8_MMA(ai, bj, At, Bt) do { __builtin_amdgcn_s_setprio(1); _Pragma("unroll") for (int m = 0; m < 4; ++m) _Pragma("unroll") for (int n = 0; n < 2; ++n) _Pragma("unroll") for (int k = 0; k < 2; ++k) \
;         acc[ai][bj][m][n] = __builtin_amdgcn_mfma_f32_16x16x32_bf16(Bt[n][k], At[m][k], acc[ai][bj][m][n], 0, 0, 0); __builtin_amdgcn_s_setprio(0); } while (0)
; #define PG8_WAIT_V(n) asm volatile("s_waitcnt vmcnt(" #n ")" ::: "memory")
; #define PG8_WAIT_L(n) asm volatile("s_waitcnt lgkmcnt(" #n ")" ::: "memory")
; #define PG8_BAR __builtin_amdgcn_s_barrier()
; #define PG8_SCHED __builtin_amdgcn_sched_barrier(0)
; template <class Epi>
; __device__ __forceinline__ void gemm_phase(LAS unsigned char* lds, const Gemm g, const StaticOrder& S, const Epi& E, const int tid) {
;     ...
;             PG8_WAIT_V(8); PG8_WAIT_L(0); PG8_BAR; PG8_MMA(1, 0, At, B0); PG8_MMA(1, 1, At, B1); PG8_BAR; PG8_SCHED;
;             PG8_LDB(B0, 1, 0); PG8_LDB(B1, 1, 1); PG8_SCHED; PG8_LDA(At, 1, 0); PG8_STAGE(PG8_SA(0, 1), a2 + hstep, voffA);
;             PG8_WAIT_V(8); PG8_WAIT_L(0); PG8_BAR; PG8_MMA(0, 0, At, B0); PG8_MMA(0, 1, At, B1); PG8_BAR; PG8_SCHED;
	s_setprio 1
	s_waitcnt lgkmcnt(0)
	v_mfma_f32_16x16x32_bf16 v[60:63], v[154:157], v[190:193], v[60:63]
	v_mfma_f32_16x16x32_bf16 v[52:55], v[166:169], v[190:193], v[52:55]
	v_mfma_f32_16x16x32_bf16 v[44:47], v[154:157], v[198:201], v[44:47]
	v_mfma_f32_16x16x32_bf16 v[36:39], v[166:169], v[198:201], v[36:39]
	v_mfma_f32_16x16x32_bf16 v[28:31], v[154:157], v[206:209], v[28:31]
	v_mfma_f32_16x16x32_bf16 v[20:23], v[166:169], v[206:209], v[20:23]
	v_mfma_f32_16x16x32_bf16 v[12:15], v[154:157], v[214:217], v[12:15]
	v_mfma_f32_16x16x32_bf16 v[4:7], v[166:169], v[214:217], v[4:7]
	v_mfma_f32_16x16x32_bf16 v[60:63], v[162:165], v[194:197], v[60:63]
	v_mfma_f32_16x16x32_bf16 v[52:55], v[170:173], v[194:197], v[52:55]
	v_mfma_f32_16x16x32_bf16 v[44:47], v[162:165], v[202:205], v[44:47]
	v_mfma_f32_16x16x32_bf16 v[36:39], v[170:173], v[202:205], v[36:39]
	v_mfma_f32_16x16x32_bf16 v[28:31], v[162:165], v[210:213], v[28:31]
	v_mfma_f32_16x16x32_bf16 v[20:23], v[170:173], v[210:213], v[20:23]
	v_mfma_f32_16x16x32_bf16 v[12:15], v[162:165], v[218:221], v[12:15]
	v_mfma_f32_16x16x32_bf16 v[4:7], v[170:173], v[218:221], v[4:7]
	v_mfma_f32_16x16x32_bf16 v[56:59], v[174:177], v[190:193], v[56:59]
	v_mfma_f32_16x16x32_bf16 v[48:51], v[182:185], v[190:193], v[48:51]
	v_mfma_f32_16x16x32_bf16 v[40:43], v[174:177], v[198:201], v[40:43]
	v_mfma_f32_16x16x32_bf16 v[32:35], v[182:185], v[198:201], v[32:35]
	v_mfma_f32_16x16x32_bf16 v[24:27], v[174:177], v[206:209], v[24:27]
	v_mfma_f32_16x16x32_bf16 v[16:19], v[182:185], v[206:209], v[16:19]
	v_mfma_f32_16x16x32_bf16 v[8:11], v[174:177], v[214:217], v[8:11]
	v_mfma_f32_16x16x32_bf16 v[0:3], v[182:185], v[214:217], v[0:3]
	v_mfma_f32_16x16x32_bf16 v[56:59], v[178:181], v[194:197], v[56:59]
	v_mfma_f32_16x16x32_bf16 v[48:51], v[186:189], v[194:197], v[48:51]
	v_mfma_f32_16x16x32_bf16 v[40:43], v[178:181], v[202:205], v[40:43]
	v_mfma_f32_16x16x32_bf16 v[32:35], v[186:189], v[202:205], v[32:35]
	v_mfma_f32_16x16x32_bf16 v[24:27], v[178:181], v[210:213], v[24:27]
	v_mfma_f32_16x16x32_bf16 v[16:19], v[186:189], v[210:213], v[16:19]
	v_mfma_f32_16x16x32_bf16 v[8:11], v[178:181], v[218:221], v[8:11]
	v_mfma_f32_16x16x32_bf16 v[0:3], v[186:189], v[218:221], v[0:3]
	s_setprio 0
	s_barrier
	s_add_i32 s95, 0, 0x18000
	v_add_u32_e32 v161, s95, v151
	s_add_i32 s96, 0, 0x1c000
	ds_read_b128 v[154:157], v161
	ds_read_b128 v[162:165], v161 offset:1024
	ds_read_b128 v[166:169], v161 offset:2048
	ds_read_b128 v[170:173], v161 offset:3072
	v_add_u32_e32 v161, s96, v151
	ds_read_b128 v[174:177], v161
	ds_read_b128 v[178:181], v161 offset:1024
	ds_read_b128 v[182:185], v161 offset:2048
	ds_read_b128 v[186:189], v161 offset:3072
	s_add_u32 s66, s66, 0x80000
	s_addc_u32 s67, s67, 0
	s_mov_b32 m0, s83
	v_lshl_add_u64 v[230:231], s[66:67], 0, v[142:143]
	ds_read_b128 v[190:193], v153 offset:32768
	ds_read_b128 v[194:197], v153 offset:33792
	ds_read_b128 v[198:201], v153 offset:34816
	ds_read_b128 v[202:205], v153 offset:35840
	ds_read_b128 v[206:209], v153 offset:36864
	ds_read_b128 v[210:213], v153 offset:37888
	ds_read_b128 v[214:217], v153 offset:38912
	ds_read_b128 v[218:221], v153 offset:39936
	global_load_lds_dwordx4 v[230:231], off
	v_lshl_add_u64 v[230:231], s[66:67], 0, v[140:141]
	s_mov_b32 m0, s84
	s_nop 0
	global_load_lds_dwordx4 v[230:231], off
	s_waitcnt vmcnt(8)
	s_waitcnt lgkmcnt(0)
	s_barrier
	s_setprio 1
	s_waitcnt lgkmcnt(0)
	v_mfma_f32_16x16x32_bf16 v[124:127], v[154:157], v[190:193], v[124:127]
	v_mfma_f32_16x16x32_bf16 v[116:119], v[166:169], v[190:193], v[116:119]
	v_mfma_f32_16x16x32_bf16 v[108:111], v[154:157], v[198:201], v[108:111]
	v_mfma_f32_16x16x32_bf16 v[100:103], v[166:169], v[198:201], v[100:103]
	v_mfma_f32_16x16x32_bf16 v[92:95], v[154:157], v[206:209], v[92:95]
	v_mfma_f32_16x16x32_bf16 v[84:87], v[166:169], v[206:209], v[84:87]
	v_mfma_f32_16x16x32_bf16 v[76:79], v[154:157], v[214:217], v[76:79]
	v_mfma_f32_16x16x32_bf16 v[68:71], v[166:169], v[214:217], v[68:71]
	v_mfma_f32_16x16x32_bf16 v[124:127], v[162:165], v[194:197], v[124:127]
	v_mfma_f32_16x16x32_bf16 v[116:119], v[170:173], v[194:197], v[116:119]
	v_mfma_f32_16x16x32_bf16 v[108:111], v[162:165], v[202:205], v[108:111]
	v_mfma_f32_16x16x32_bf16 v[100:103], v[170:173], v[202:205], v[100:103]
	v_mfma_f32_16x16x32_bf16 v[92:95], v[162:165], v[210:213], v[92:95]
	v_mfma_f32_16x16x32_bf16 v[84:87], v[170:173], v[210:213], v[84:87]
	v_mfma_f32_16x16x32_bf16 v[76:79], v[162:165], v[218:221], v[76:79]
	v_mfma_f32_16x16x32_bf16 v[68:71], v[170:173], v[218:221], v[68:71]
	v_mfma_f32_16x16x32_bf16 v[120:123], v[174:177], v[190:193], v[120:123]
	v_mfma_f32_16x16x32_bf16 v[112:115], v[182:185], v[190:193], v[112:115]
	v_mfma_f32_16x16x32_bf16 v[104:107], v[174:177], v[198:201], v[104:107]
	v_mfma_f32_16x16x32_bf16 v[96:99], v[182:185], v[198:201], v[96:99]
	v_mfma_f32_16x16x32_bf16 v[88:91], v[174:177], v[206:209], v[88:91]
	v_mfma_f32_16x16x32_bf16 v[80:83], v[182:185], v[206:209], v[80:83]
	v_mfma_f32_16x16x32_bf16 v[72:75], v[174:177], v[214:217], v[72:75]
	v_mfma_f32_16x16x32_bf16 v[64:67], v[182:185], v[214:217], v[64:67]
	v_mfma_f32_16x16x32_bf16 v[120:123], v[178:181], v[194:197], v[120:123]
	v_mfma_f32_16x16x32_bf16 v[112:115], v[186:189], v[194:197], v[112:115]
	v_mfma_f32_16x16x32_bf16 v[104:107], v[178:181], v[202:205], v[104:107]
	v_mfma_f32_16x16x32_bf16 v[96:99], v[186:189], v[202:205], v[96:99]
	v_mfma_f32_16x16x32_bf16 v[88:91], v[178:181], v[210:213], v[88:91]
	v_mfma_f32_16x16x32_bf16 v[80:83], v[186:189], v[210:213], v[80:83]
	v_mfma_f32_16x16x32_bf16 v[72:75], v[178:181], v[218:221], v[72:75]
	v_mfma_f32_16x16x32_bf16 v[64:67], v[186:189], v[218:221], v[64:67]
	s_setprio 0
	s_barrier
; #define PG8_STAGE(bufoff, gbase, voff) do { _Pragma("unroll") for (int _i = 0; _i < 2; ++_i) \
;         __builtin_amdgcn_global_load_lds((const unsigned*)((const char*)(gbase) + (voff)[_i]), (LAS unsigned*)(lds + (bufoff) + ldsw + _i * 8192), 16, 0, 0); } while (0)
; #define PG8_LDA(dst, b, h) do { _Pragma("unroll") for (int m = 0; m < 4; ++m) _Pragma("unroll") for (int k = 0; k < 2; ++k) dst[m][k] = *(const LAS bf16x8*)(lds + PG8_SA(b, h) + aoff + m * 2048 + k * 1024); } while (0)
; #define PG8_MMA(ai, bj, At, Bt) do { __builtin_amdgcn_s_setprio(1); _Pragma("unroll") for (int m = 0; m < 4; ++m) _Pragma("unroll") for (int n = 0; n < 2; ++n) _Pragma("unroll") for (int k = 0; k < 2; ++k) \
;         acc[ai][bj][m][n] = __builtin_amdgcn_mfma_f32_16x16x32_bf16(Bt[n][k], At[m][k], acc[ai][bj][m][n], 0, 0, 0); __builtin_amdgcn_s_setprio(0); } while (0)
; #define PG8_WAIT_V(n) asm volatile("s_waitcnt vmcnt(" #n ")" ::: "memory")
; #define PG8_WAIT_L(n) asm volatile("s_waitcnt lgkmcnt(" #n ")" ::: "memory")
; #define PG8_BAR __builtin_amdgcn_s_barrier()
; #define PG8_SCHED __builtin_amdgcn_sched_barrier(0)
; template <class Epi>
; __device__ __forceinline__ void gemm_phase(LAS unsigned char* lds, const Gemm g, const StaticOrder& S, const Epi& E, const int tid) {
;     ...
;             PG8_LDA(At, 1, 1); PG8_STAGE(PG8_SB(1, 0), b3, voffB); PG8_STAGE(PG8_SB(1, 1), b3 + hstep, voffB); PG8_STAGE(PG8_SA(1, 0), a3, voffA);
;             PG8_WAIT_V(8); PG8_WAIT_L(0); PG8_BAR; PG8_MMA(1, 0, At, B0); PG8_MMA(1, 1, At, B1); PG8_BAR; PG8_SCHED;
;         }
;         if (wr == 0) PG8_BAR;
	s_add_i32 s66, s95, s80
	v_lshl_add_u64 v[148:149], v[148:149], 0, s[8:9]
	s_mov_b32 m0, s66
	ds_read_b128 v[190:193], v153 offset:49152
	ds_read_b128 v[194:197], v153 offset:50176
	ds_read_b128 v[198:201], v153 offset:51200
	ds_read_b128 v[202:205], v153 offset:52224
	ds_read_b128 v[206:209], v153 offset:53248
	ds_read_b128 v[210:213], v153 offset:54272
	ds_read_b128 v[214:217], v153 offset:55296
	ds_read_b128 v[218:221], v153 offset:56320
	global_load_lds_dwordx4 v[148:149], off
	s_add_i32 m0, s66, 0x2000
	s_add_u32 s64, s64, 0x80080
	v_lshl_add_u64 v[148:149], v[222:223], 0, s[8:9]
	s_addc_u32 s65, s65, 0
	s_add_i32 s66, s96, s80
	global_load_lds_dwordx4 v[148:149], off
	v_lshl_add_u64 v[148:149], s[64:65], 0, v[128:129]
	s_mov_b32 m0, s66
	s_nop 0
	global_load_lds_dwordx4 v[148:149], off
	v_lshl_add_u64 v[148:149], s[64:65], 0, v[138:139]
	s_add_i32 m0, s66, 0x2000
	s_nop 0
	global_load_lds_dwordx4 v[148:149], off
	v_lshl_add_u64 v[148:149], v[226:227], 0, s[8:9]
	s_mov_b32 m0, s85
	s_nop 0
	global_load_lds_dwordx4 v[148:149], off
	v_lshl_add_u64 v[148:149], v[228:229], 0, s[8:9]
	s_mov_b32 m0, s86
	s_nop 0
	global_load_lds_dwordx4 v[148:149], off
	s_waitcnt vmcnt(8)
	s_waitcnt lgkmcnt(0)
	s_barrier
	s_setprio 1
	s_waitcnt lgkmcnt(0)
	v_mfma_f32_16x16x32_bf16 v[60:63], v[154:157], v[190:193], v[60:63]
	v_mfma_f32_16x16x32_bf16 v[52:55], v[166:169], v[190:193], v[52:55]
	v_mfma_f32_16x16x32_bf16 v[44:47], v[154:157], v[198:201], v[44:47]
	v_mfma_f32_16x16x32_bf16 v[36:39], v[166:169], v[198:201], v[36:39]
	v_mfma_f32_16x16x32_bf16 v[28:31], v[154:157], v[206:209], v[28:31]
	v_mfma_f32_16x16x32_bf16 v[20:23], v[166:169], v[206:209], v[20:23]
	v_mfma_f32_16x16x32_bf16 v[12:15], v[154:157], v[214:217], v[12:15]
	v_mfma_f32_16x16x32_bf16 v[4:7], v[166:169], v[214:217], v[4:7]
	v_mfma_f32_16x16x32_bf16 v[60:63], v[162:165], v[194:197], v[60:63]
	v_mfma_f32_16x16x32_bf16 v[52:55], v[170:173], v[194:197], v[52:55]
	v_mfma_f32_16x16x32_bf16 v[44:47], v[162:165], v[202:205], v[44:47]
	v_mfma_f32_16x16x32_bf16 v[36:39], v[170:173], v[202:205], v[36:39]
	v_mfma_f32_16x16x32_bf16 v[28:31], v[162:165], v[210:213], v[28:31]
	v_mfma_f32_16x16x32_bf16 v[20:23], v[170:173], v[210:213], v[20:23]
	v_mfma_f32_16x16x32_bf16 v[12:15], v[162:165], v[218:221], v[12:15]
	v_mfma_f32_16x16x32_bf16 v[4:7], v[170:173], v[218:221], v[4:7]
	v_mfma_f32_16x16x32_bf16 v[56:59], v[174:177], v[190:193], v[56:59]
	v_mfma_f32_16x16x32_bf16 v[48:51], v[182:185], v[190:193], v[48:51]
	v_mfma_f32_16x16x32_bf16 v[40:43], v[174:177], v[198:201], v[40:43]
	v_mfma_f32_16x16x32_bf16 v[32:35], v[182:185], v[198:201], v[32:35]
	v_mfma_f32_16x16x32_bf16 v[24:27], v[174:177], v[206:209], v[24:27]
	v_mfma_f32_16x16x32_bf16 v[16:19], v[182:185], v[206:209], v[16:19]
	v_mfma_f32_16x16x32_bf16 v[8:11], v[174:177], v[214:217], v[8:11]
	v_mfma_f32_16x16x32_bf16 v[0:3], v[182:185], v[214:217], v[0:3]
	v_mfma_f32_16x16x32_bf16 v[56:59], v[178:181], v[194:197], v[56:59]
	v_mfma_f32_16x16x32_bf16 v[48:51], v[186:189], v[194:197], v[48:51]
	v_mfma_f32_16x16x32_bf16 v[40:43], v[178:181], v[202:205], v[40:43]
	v_mfma_f32_16x16x32_bf16 v[32:35], v[186:189], v[202:205], v[32:35]
	v_mfma_f32_16x16x32_bf16 v[24:27], v[178:181], v[210:213], v[24:27]
	v_mfma_f32_16x16x32_bf16 v[16:19], v[186:189], v[210:213], v[16:19]
	v_mfma_f32_16x16x32_bf16 v[8:11], v[178:181], v[218:221], v[8:11]
	v_mfma_f32_16x16x32_bf16 v[0:3], v[186:189], v[218:221], v[0:3]
	s_setprio 0
	s_barrier
	s_add_i32 s94, s94, 2
	s_add_u32 s92, s92, 0x100
	s_addc_u32 s93, s93, 0
	s_add_u32 s62, s62, 0x100
	s_addc_u32 s63, s63, 0
	s_cmp_gt_u32 s94, 29
	s_cbranch_scc0 .LBB0_1706
	s_and_b64 vcc, exec, s[52:53]
	s_cbranch_vccz .LBB0_1709
	s_barrier

; #define PG8_STAGE(bufoff, gbase, voff) do { _Pragma("unroll") for (int _i = 0; _i < 2; ++_i) \
;         __builtin_amdgcn_global_load_lds((const unsigned*)((const char*)(gbase) + (voff)[_i]), (LAS unsigned*)(lds + (bufoff) + ldsw + _i * 8192), 16, 0, 0); } while (0)
; #define PG8_LDA(dst, b, h) do { _Pragma("unroll") for (int m = 0; m < 4; ++m) _Pragma("unroll") for (int k = 0; k < 2; ++k) dst[m][k] = *(const LAS bf16x8*)(lds + PG8_SA(b, h) + aoff + m * 2048 + k * 1024); } while (0)
; #define PG8_LDB(dst, b, h) do { _Pragma("unroll") for (int n = 0; n < 2; ++n) _Pragma("unroll") for (int k = 0; k < 2; ++k) dst[n][k] = *(const LAS bf16x8*)(lds + PG8_SB(b, h) + boff + n * 2048 + k * 1024); } while (0)
; #define PG8_MMA(ai, bj, At, Bt) do { __builtin_amdgcn_s_setprio(1); _Pragma("unroll") for (int m = 0; m < 4; ++m) _Pragma("unroll") for (int n = 0; n < 2; ++n) _Pragma("unroll") for (int k = 0; k < 2; ++k) \
;         acc[ai][bj][m][n] = __builtin_amdgcn_mfma_f32_16x16x32_bf16(Bt[n][k], At[m][k], acc[ai][bj][m][n], 0, 0, 0); __builtin_amdgcn_s_setprio(0); } while (0)
; #define PG8_WAIT_V(n) asm volatile("s_waitcnt vmcnt(" #n ")" ::: "memory")
; #define PG8_BAR __builtin_amdgcn_s_barrier()
; template <class Epi>
; __device__ __forceinline__ void gemm_phase(LAS unsigned char* lds, const Gemm g, const StaticOrder& S, const Epi& E, const int tid) {
;     ...
;         const char* nA = has_next ? (const char*)g.A + (size_t)nxt.pm * tstep : cA; const char* nB = has_next ? (const char*)g.Bt + (size_t)nxt.pn * tstep : cB;
;         for (int t = 0; t < nt; t += 2) {
;             const bool last = (t == nt - 2);
;             const char* a1 = cA + (size_t)(t + 1) * kstep;
;             const char* a2 = last ? nA : cA + (size_t)(t + 2) * kstep; const char* b2 = last ? nB : cB + (size_t)(t + 2) * kstep;
;             const char* a3 = a2 + kstep; const char* b3 = b2 + kstep;
;             PG8_LDB(B0, 0, 0); PG8_LDB(B1, 0, 1); PG8_SCHED; PG8_LDA(At, 0, 0); PG8_STAGE(PG8_SA(1, 1), a1 + hstep, voffA);
;             PG8_WAIT_V(8); PG8_WAIT_L(0); PG8_BAR; PG8_MMA(0, 0, At, B0); PG8_MMA(0, 1, At, B1); PG8_BAR; PG8_SCHED;
;             PG8_LDA(At, 0, 1); PG8_STAGE(PG8_SB(0, 0), b2, voffB); PG8_STAGE(PG8_SB(0, 1), b2 + hstep, voffB); PG8_STAGE(PG8_SA(0, 0), a2, voffA);
;             PG8_WAIT_V(8); PG8_WAIT_L(0); PG8_BAR; PG8_MMA(1, 0, At, B0); PG8_MMA(1, 1, At, B1); PG8_BAR; PG8_SCHED;
.LBB0_1804:
	s_add_u32 s58, s56, 0x100
	s_addc_u32 s59, s57, 0
	s_add_i32 s91, 0, 0x10000
	s_cmpk_eq_i32 s90, 0x54
	s_cselect_b32 s63, s41, s59
	s_cselect_b32 s62, s40, s58
	v_add_u32_e32 v148, s91, v151
	s_cselect_b32 s61, s55, s89
	s_cselect_b32 s60, s54, s88
	s_add_i32 s92, 0, 0x14000
	ds_read_b128 v[154:157], v148
	ds_read_b128 v[162:165], v148 offset:1024
	ds_read_b128 v[166:169], v148 offset:2048
	ds_read_b128 v[170:173], v148 offset:3072
	v_add_u32_e32 v148, s92, v151
	ds_read_b128 v[174:177], v148
	ds_read_b128 v[178:181], v148 offset:1024
	ds_read_b128 v[182:185], v148 offset:2048
	ds_read_b128 v[186:189], v148 offset:3072
	v_lshl_add_u64 v[148:149], s[56:57], 0, v[146:147]
	s_add_i32 m0, s77, 0xc000
	ds_read_b128 v[190:193], v153
	ds_read_b128 v[194:197], v153 offset:1024
	ds_read_b128 v[198:201], v153 offset:2048
	ds_read_b128 v[202:205], v153 offset:3072
	ds_read_b128 v[206:209], v153 offset:4096
	ds_read_b128 v[210:213], v153 offset:5120
	ds_read_b128 v[214:217], v153 offset:6144
	ds_read_b128 v[218:221], v153 offset:7168
	global_load_lds_dwordx4 v[148:149], off
	v_lshl_add_u64 v[148:149], s[56:57], 0, v[144:145]
	s_add_i32 m0, s77, 0xe000
	s_nop 0
	global_load_lds_dwordx4 v[148:149], off
	s_waitcnt vmcnt(8)
	s_waitcnt lgkmcnt(0)
	s_barrier
	s_setprio 1
	s_waitcnt lgkmcnt(0)
	v_mfma_f32_16x16x32_bf16 v[124:127], v[154:157], v[190:193], v[124:127]
	v_mfma_f32_16x16x32_bf16 v[120:123], v[166:169], v[190:193], v[120:123]
	v_mfma_f32_16x16x32_bf16 v[116:119], v[154:157], v[198:201], v[116:119]
	v_mfma_f32_16x16x32_bf16 v[108:111], v[166:169], v[198:201], v[108:111]
	v_mfma_f32_16x16x32_bf16 v[100:103], v[154:157], v[206:209], v[100:103]
	v_mfma_f32_16x16x32_bf16 v[92:95], v[166:169], v[206:209], v[92:95]
	v_mfma_f32_16x16x32_bf16 v[84:87], v[154:157], v[214:217], v[84:87]
	v_mfma_f32_16x16x32_bf16 v[76:79], v[166:169], v[214:217], v[76:79]
	v_mfma_f32_16x16x32_bf16 v[124:127], v[162:165], v[194:197], v[124:127]
	v_mfma_f32_16x16x32_bf16 v[120:123], v[170:173], v[194:197], v[120:123]
	v_mfma_f32_16x16x32_bf16 v[116:119], v[162:165], v[202:205], v[116:119]
	v_mfma_f32_16x16x32_bf16 v[108:111], v[170:173], v[202:205], v[108:111]
	v_mfma_f32_16x16x32_bf16 v[100:103], v[162:165], v[210:213], v[100:103]
	v_mfma_f32_16x16x32_bf16 v[92:95], v[170:173], v[210:213], v[92:95]
	v_mfma_f32_16x16x32_bf16 v[84:87], v[162:165], v[218:221], v[84:87]
	v_mfma_f32_16x16x32_bf16 v[76:79], v[170:173], v[218:221], v[76:79]
	v_mfma_f32_16x16x32_bf16 v[112:115], v[174:177], v[190:193], v[112:115]
	v_mfma_f32_16x16x32_bf16 v[104:107], v[182:185], v[190:193], v[104:107]
	v_mfma_f32_16x16x32_bf16 v[96:99], v[174:177], v[198:201], v[96:99]
	v_mfma_f32_16x16x32_bf16 v[88:91], v[182:185], v[198:201], v[88:91]
	v_mfma_f32_16x16x32_bf16 v[80:83], v[174:177], v[206:209], v[80:83]
	v_mfma_f32_16x16x32_bf16 v[72:75], v[182:185], v[206:209], v[72:75]
	v_mfma_f32_16x16x32_bf16 v[68:71], v[174:177], v[214:217], v[68:71]
	v_mfma_f32_16x16x32_bf16 v[64:67], v[182:185], v[214:217], v[64:67]
	v_mfma_f32_16x16x32_bf16 v[112:115], v[178:181], v[194:197], v[112:115]
	v_mfma_f32_16x16x32_bf16 v[104:107], v[186:189], v[194:197], v[104:107]
	v_mfma_f32_16x16x32_bf16 v[96:99], v[178:181], v[202:205], v[96:99]
	v_mfma_f32_16x16x32_bf16 v[88:91], v[186:189], v[202:205], v[88:91]
	v_mfma_f32_16x16x32_bf16 v[80:83], v[178:181], v[210:213], v[80:83]
	v_mfma_f32_16x16x32_bf16 v[72:75], v[186:189], v[210:213], v[72:75]
	v_mfma_f32_16x16x32_bf16 v[68:71], v[178:181], v[218:221], v[68:71]
	v_mfma_f32_16x16x32_bf16 v[64:67], v[186:189], v[218:221], v[64:67]
	s_setprio 0
	s_barrier
	s_add_i32 s56, s91, s76
	v_lshl_add_u64 v[148:149], s[60:61], 0, v[128:129]
	s_mov_b32 m0, s56
	ds_read_b128 v[190:193], v153 offset:16384
	ds_read_b128 v[194:197], v153 offset:17408
	ds_read_b128 v[198:201], v153 offset:18432
	ds_read_b128 v[202:205], v153 offset:19456
	ds_read_b128 v[206:209], v153 offset:20480
	ds_read_b128 v[210:213], v153 offset:21504
	ds_read_b128 v[214:217], v153 offset:22528
	ds_read_b128 v[218:221], v153 offset:23552
	global_load_lds_dwordx4 v[148:149], off
	s_add_i32 m0, s56, 0x2000
	s_add_u32 s56, s60, 0x160000
	v_lshl_add_u64 v[222:223], s[60:61], 0, v[138:139]
	s_addc_u32 s57, s61, 0
	s_add_i32 s91, s92, s76
	global_load_lds_dwordx4 v[222:223], off
	v_lshl_add_u64 v[226:227], s[56:57], 0, v[128:129]
	s_mov_b32 m0, s91
	v_lshl_add_u64 v[228:229], s[62:63], 0, v[140:141]
	global_load_lds_dwordx4 v[226:227], off
	v_lshl_add_u64 v[226:227], s[56:57], 0, v[138:139]
	s_add_i32 m0, s91, 0x2000
	s_nop 0
	global_load_lds_dwordx4 v[226:227], off
	v_lshl_add_u64 v[226:227], s[62:63], 0, v[142:143]
	s_mov_b32 m0, s77
	s_nop 0
	global_load_lds_dwordx4 v[226:227], off
	s_mov_b32 m0, s78
	s_nop 0
	global_load_lds_dwordx4 v[228:229], off
	s_waitcnt vmcnt(8)
	s_waitcnt lgkmcnt(0)
	s_barrier
; #define PG8_STAGE(bufoff, gbase, voff) do { _Pragma("unroll") for (int _i = 0; _i < 2; ++_i) \
;         __builtin_amdgcn_global_load_lds((const unsigned*)((const char*)(gbase) + (voff)[_i]), (LAS unsigned*)(lds + (bufoff) + ldsw + _i * 8192), 16, 0, 0); } while (0)
; #define PG8_LDA(dst, b, h) do { _Pragma("unroll") for (int m = 0; m < 4; ++m) _Pragma("unroll") for (int k = 0; k < 2; ++k) dst[m][k] = *(const LAS bf16x8*)(lds + PG8_SA(b, h) + aoff + m * 2048 + k * 1024); } while (0)
; #define PG8_LDB(dst, b, h) do { _Pragma("unroll") for (int n = 0; n < 2; ++n) _Pragma("unroll") for (int k = 0; k < 2; ++k) dst[n][k] = *(const LAS bf16x8*)(lds + PG8_SB(b, h) + boff + n * 2048 + k * 1024); } while (0)
; #define PG8_MMA(ai, bj, At, Bt) do { __builtin_amdgcn_s_setprio(1); _Pragma("unroll") for (int m = 0; m < 4; ++m) _Pragma("unroll") for (int n = 0; n < 2; ++n) _Pragma("unroll") for (int k = 0; k < 2; ++k) \
;         acc[ai][bj][m][n] = __builtin_amdgcn_mfma_f32_16x16x32_bf16(Bt[n][k], At[m][k], acc[ai][bj][m][n], 0, 0, 0); __builtin_amdgcn_s_setprio(0); } while (0)
; #define PG8_WAIT_V(n) asm volatile("s_waitcnt vmcnt(" #n ")" ::: "memory")
; #define PG8_WAIT_L(n) asm volatile("s_waitcnt lgkmcnt(" #n ")" ::: "memory")
; #define PG8_BAR __builtin_amdgcn_s_barrier()
; #define PG8_SCHED __builtin_amdgcn_sched_barrier(0)
; template <class Epi>
; __device__ __forceinline__ void gemm_phase(LAS unsigned char* lds, const Gemm g, const StaticOrder& S, const Epi& E, const int tid) {
;     ...
;             PG8_WAIT_V(8); PG8_WAIT_L(0); PG8_BAR; PG8_MMA(1, 0, At, B0); PG8_MMA(1, 1, At, B1); PG8_BAR; PG8_SCHED;
;             PG8_LDB(B0, 1, 0); PG8_LDB(B1, 1, 1); PG8_SCHED; PG8_LDA(At, 1, 0); PG8_STAGE(PG8_SA(0, 1), a2 + hstep, voffA);
;             PG8_WAIT_V(8); PG8_WAIT_L(0); PG8_BAR; PG8_MMA(0, 0, At, B0); PG8_MMA(0, 1, At, B1); PG8_BAR; PG8_SCHED;
	s_setprio 1
	s_waitcnt lgkmcnt(0)
	v_mfma_f32_16x16x32_bf16 v[60:63], v[154:157], v[190:193], v[60:63]
	v_mfma_f32_16x16x32_bf16 v[56:59], v[166:169], v[190:193], v[56:59]
	v_mfma_f32_16x16x32_bf16 v[52:55], v[154:157], v[198:201], v[52:55]
	v_mfma_f32_16x16x32_bf16 v[44:47], v[166:169], v[198:201], v[44:47]
	v_mfma_f32_16x16x32_bf16 v[36:39], v[154:157], v[206:209], v[36:39]
	v_mfma_f32_16x16x32_bf16 v[28:31], v[166:169], v[206:209], v[28:31]
	v_mfma_f32_16x16x32_bf16 v[20:23], v[154:157], v[214:217], v[20:23]
	v_mfma_f32_16x16x32_bf16 v[12:15], v[166:169], v[214:217], v[12:15]
	v_mfma_f32_16x16x32_bf16 v[60:63], v[162:165], v[194:197], v[60:63]
	v_mfma_f32_16x16x32_bf16 v[56:59], v[170:173], v[194:197], v[56:59]
	v_mfma_f32_16x16x32_bf16 v[52:55], v[162:165], v[202:205], v[52:55]
	v_mfma_f32_16x16x32_bf16 v[44:47], v[170:173], v[202:205], v[44:47]
	v_mfma_f32_16x16x32_bf16 v[36:39], v[162:165], v[210:213], v[36:39]
	v_mfma_f32_16x16x32_bf16 v[28:31], v[170:173], v[210:213], v[28:31]
	v_mfma_f32_16x16x32_bf16 v[20:23], v[162:165], v[218:221], v[20:23]
	v_mfma_f32_16x16x32_bf16 v[12:15], v[170:173], v[218:221], v[12:15]
	v_mfma_f32_16x16x32_bf16 v[48:51], v[174:177], v[190:193], v[48:51]
	v_mfma_f32_16x16x32_bf16 v[40:43], v[182:185], v[190:193], v[40:43]
	v_mfma_f32_16x16x32_bf16 v[32:35], v[174:177], v[198:201], v[32:35]
	v_mfma_f32_16x16x32_bf16 v[24:27], v[182:185], v[198:201], v[24:27]
	v_mfma_f32_16x16x32_bf16 v[16:19], v[174:177], v[206:209], v[16:19]
	v_mfma_f32_16x16x32_bf16 v[8:11], v[182:185], v[206:209], v[8:11]
	v_mfma_f32_16x16x32_bf16 v[4:7], v[174:177], v[214:217], v[4:7]
	v_mfma_f32_16x16x32_bf16 v[0:3], v[182:185], v[214:217], v[0:3]
	v_mfma_f32_16x16x32_bf16 v[48:51], v[178:181], v[194:197], v[48:51]
	v_mfma_f32_16x16x32_bf16 v[40:43], v[186:189], v[194:197], v[40:43]
	v_mfma_f32_16x16x32_bf16 v[32:35], v[178:181], v[202:205], v[32:35]
	v_mfma_f32_16x16x32_bf16 v[24:27], v[186:189], v[202:205], v[24:27]
	v_mfma_f32_16x16x32_bf16 v[16:19], v[178:181], v[210:213], v[16:19]
	v_mfma_f32_16x16x32_bf16 v[8:11], v[186:189], v[210:213], v[8:11]
	v_mfma_f32_16x16x32_bf16 v[4:7], v[178:181], v[218:221], v[4:7]
	v_mfma_f32_16x16x32_bf16 v[0:3], v[186:189], v[218:221], v[0:3]
	s_setprio 0
	s_barrier
	s_add_i32 s91, 0, 0x18000
	v_add_u32_e32 v161, s91, v151
	s_add_i32 s92, 0, 0x1c000
	ds_read_b128 v[154:157], v161
	ds_read_b128 v[162:165], v161 offset:1024
	ds_read_b128 v[166:169], v161 offset:2048
	ds_read_b128 v[170:173], v161 offset:3072
	v_add_u32_e32 v161, s92, v151
	ds_read_b128 v[174:177], v161
	ds_read_b128 v[178:181], v161 offset:1024
	ds_read_b128 v[182:185], v161 offset:2048
	ds_read_b128 v[186:189], v161 offset:3072
	s_add_u32 s56, s62, 0x160000
	s_addc_u32 s57, s63, 0
	s_mov_b32 m0, s79
	v_lshl_add_u64 v[230:231], s[56:57], 0, v[142:143]
	ds_read_b128 v[190:193], v153 offset:32768
	ds_read_b128 v[194:197], v153 offset:33792
	ds_read_b128 v[198:201], v153 offset:34816
	ds_read_b128 v[202:205], v153 offset:35840
	ds_read_b128 v[206:209], v153 offset:36864
	ds_read_b128 v[210:213], v153 offset:37888
	ds_read_b128 v[214:217], v153 offset:38912
	ds_read_b128 v[218:221], v153 offset:39936
	global_load_lds_dwordx4 v[230:231], off
	v_lshl_add_u64 v[230:231], s[56:57], 0, v[140:141]
	s_mov_b32 m0, s80
	s_nop 0
	global_load_lds_dwordx4 v[230:231], off
	s_waitcnt vmcnt(8)
	s_waitcnt lgkmcnt(0)
	s_barrier
	s_setprio 1
	s_waitcnt lgkmcnt(0)
	v_mfma_f32_16x16x32_bf16 v[124:127], v[154:157], v[190:193], v[124:127]
	v_mfma_f32_16x16x32_bf16 v[120:123], v[166:169], v[190:193], v[120:123]
	v_mfma_f32_16x16x32_bf16 v[116:119], v[154:157], v[198:201], v[116:119]
	v_mfma_f32_16x16x32_bf16 v[108:111], v[166:169], v[198:201], v[108:111]
	v_mfma_f32_16x16x32_bf16 v[100:103], v[154:157], v[206:209], v[100:103]
	v_mfma_f32_16x16x32_bf16 v[92:95], v[166:169], v[206:209], v[92:95]
	v_mfma_f32_16x16x32_bf16 v[84:87], v[154:157], v[214:217], v[84:87]
	v_mfma_f32_16x16x32_bf16 v[76:79], v[166:169], v[214:217], v[76:79]
	v_mfma_f32_16x16x32_bf16 v[124:127], v[162:165], v[194:197], v[124:127]
	v_mfma_f32_16x16x32_bf16 v[120:123], v[170:173], v[194:197], v[120:123]
	v_mfma_f32_16x16x32_bf16 v[116:119], v[162:165], v[202:205], v[116:119]
	v_mfma_f32_16x16x32_bf16 v[108:111], v[170:173], v[202:205], v[108:111]
	v_mfma_f32_16x16x32_bf16 v[100:103], v[162:165], v[210:213], v[100:103]
	v_mfma_f32_16x16x32_bf16 v[92:95], v[170:173], v[210:213], v[92:95]
	v_mfma_f32_16x16x32_bf16 v[84:87], v[162:165], v[218:221], v[84:87]
	v_mfma_f32_16x16x32_bf16 v[76:79], v[170:173], v[218:221], v[76:79]
	v_mfma_f32_16x16x32_bf16 v[112:115], v[174:177], v[190:193], v[112:115]
	v_mfma_f32_16x16x32_bf16 v[104:107], v[182:185], v[190:193], v[104:107]
	v_mfma_f32_16x16x32_bf16 v[96:99], v[174:177], v[198:201], v[96:99]
	v_mfma_f32_16x16x32_bf16 v[88:91], v[182:185], v[198:201], v[88:91]
	v_mfma_f32_16x16x32_bf16 v[80:83], v[174:177], v[206:209], v[80:83]
	v_mfma_f32_16x16x32_bf16 v[72:75], v[182:185], v[206:209], v[72:75]
	v_mfma_f32_16x16x32_bf16 v[68:71], v[174:177], v[214:217], v[68:71]
	v_mfma_f32_16x16x32_bf16 v[64:67], v[182:185], v[214:217], v[64:67]
	v_mfma_f32_16x16x32_bf16 v[112:115], v[178:181], v[194:197], v[112:115]
	v_mfma_f32_16x16x32_bf16 v[104:107], v[186:189], v[194:197], v[104:107]
	v_mfma_f32_16x16x32_bf16 v[96:99], v[178:181], v[202:205], v[96:99]
	v_mfma_f32_16x16x32_bf16 v[88:91], v[186:189], v[202:205], v[88:91]
	v_mfma_f32_16x16x32_bf16 v[80:83], v[178:181], v[210:213], v[80:83]
	v_mfma_f32_16x16x32_bf16 v[72:75], v[186:189], v[210:213], v[72:75]
	v_mfma_f32_16x16x32_bf16 v[68:71], v[178:181], v[218:221], v[68:71]
	v_mfma_f32_16x16x32_bf16 v[64:67], v[186:189], v[218:221], v[64:67]
	s_setprio 0
	s_barrier
; #define PG8_STAGE(bufoff, gbase, voff) do { _Pragma("unroll") for (int _i = 0; _i < 2; ++_i) \
;         __builtin_amdgcn_global_load_lds((const unsigned*)((const char*)(gbase) + (voff)[_i]), (LAS unsigned*)(lds + (bufoff) + ldsw + _i * 8192), 16, 0, 0); } while (0)
; #define PG8_LDA(dst, b, h) do { _Pragma("unroll") for (int m = 0; m < 4; ++m) _Pragma("unroll") for (int k = 0; k < 2; ++k) dst[m][k] = *(const LAS bf16x8*)(lds + PG8_SA(b, h) + aoff + m * 2048 + k * 1024); } while (0)
; #define PG8_MMA(ai, bj, At, Bt) do { __builtin_amdgcn_s_setprio(1); _Pragma("unroll") for (int m = 0; m < 4; ++m) _Pragma("unroll") for (int n = 0; n < 2; ++n) _Pragma("unroll") for (int k = 0; k < 2; ++k) \
;         acc[ai][bj][m][n] = __builtin_amdgcn_mfma_f32_16x16x32_bf16(Bt[n][k], At[m][k], acc[ai][bj][m][n], 0, 0, 0); __builtin_amdgcn_s_setprio(0); } while (0)
; #define PG8_WAIT_V(n) asm volatile("s_waitcnt vmcnt(" #n ")" ::: "memory")
; #define PG8_WAIT_L(n) asm volatile("s_waitcnt lgkmcnt(" #n ")" ::: "memory")
; #define PG8_BAR __builtin_amdgcn_s_barrier()
; #define PG8_SCHED __builtin_amdgcn_sched_barrier(0)
; template <class Epi>
; __device__ __forceinline__ void gemm_phase(LAS unsigned char* lds, const Gemm g, const StaticOrder& S, const Epi& E, const int tid) {
;     ...
;             PG8_LDA(At, 1, 1); PG8_STAGE(PG8_SB(1, 0), b3, voffB); PG8_STAGE(PG8_SB(1, 1), b3 + hstep, voffB); PG8_STAGE(PG8_SA(1, 0), a3, voffA);
;             PG8_WAIT_V(8); PG8_WAIT_L(0); PG8_BAR; PG8_MMA(1, 0, At, B0); PG8_MMA(1, 1, At, B1); PG8_BAR; PG8_SCHED;
;         }
;         if (wr == 0) PG8_BAR;
	s_add_i32 s56, s91, s76
	v_lshl_add_u64 v[148:149], v[148:149], 0, s[8:9]
	s_mov_b32 m0, s56
	ds_read_b128 v[190:193], v153 offset:49152
	ds_read_b128 v[194:197], v153 offset:50176
	ds_read_b128 v[198:201], v153 offset:51200
	ds_read_b128 v[202:205], v153 offset:52224
	ds_read_b128 v[206:209], v153 offset:53248
	ds_read_b128 v[210:213], v153 offset:54272
	ds_read_b128 v[214:217], v153 offset:55296
	ds_read_b128 v[218:221], v153 offset:56320
	global_load_lds_dwordx4 v[148:149], off
	s_add_i32 m0, s56, 0x2000
	s_add_u32 s56, s60, 0x160080
	v_lshl_add_u64 v[148:149], v[222:223], 0, s[8:9]
	s_addc_u32 s57, s61, 0
	s_add_i32 s60, s92, s76
	global_load_lds_dwordx4 v[148:149], off
	v_lshl_add_u64 v[148:149], s[56:57], 0, v[128:129]
	s_mov_b32 m0, s60
	s_nop 0
	global_load_lds_dwordx4 v[148:149], off
	v_lshl_add_u64 v[148:149], s[56:57], 0, v[138:139]
	s_add_i32 m0, s60, 0x2000
	s_nop 0
	global_load_lds_dwordx4 v[148:149], off
	v_lshl_add_u64 v[148:149], v[226:227], 0, s[8:9]
	s_mov_b32 m0, s81
	s_nop 0
	global_load_lds_dwordx4 v[148:149], off
	v_lshl_add_u64 v[148:149], v[228:229], 0, s[8:9]
	s_mov_b32 m0, s82
	s_nop 0
	global_load_lds_dwordx4 v[148:149], off
	s_waitcnt vmcnt(8)
	s_waitcnt lgkmcnt(0)
	s_barrier
	s_setprio 1
	s_waitcnt lgkmcnt(0)
	v_mfma_f32_16x16x32_bf16 v[60:63], v[154:157], v[190:193], v[60:63]
	v_mfma_f32_16x16x32_bf16 v[56:59], v[166:169], v[190:193], v[56:59]
	v_mfma_f32_16x16x32_bf16 v[52:55], v[154:157], v[198:201], v[52:55]
	v_mfma_f32_16x16x32_bf16 v[44:47], v[166:169], v[198:201], v[44:47]
	v_mfma_f32_16x16x32_bf16 v[36:39], v[154:157], v[206:209], v[36:39]
	v_mfma_f32_16x16x32_bf16 v[28:31], v[166:169], v[206:209], v[28:31]
	v_mfma_f32_16x16x32_bf16 v[20:23], v[154:157], v[214:217], v[20:23]
	v_mfma_f32_16x16x32_bf16 v[12:15], v[166:169], v[214:217], v[12:15]
	v_mfma_f32_16x16x32_bf16 v[60:63], v[162:165], v[194:197], v[60:63]
	v_mfma_f32_16x16x32_bf16 v[56:59], v[170:173], v[194:197], v[56:59]
	v_mfma_f32_16x16x32_bf16 v[52:55], v[162:165], v[202:205], v[52:55]
	v_mfma_f32_16x16x32_bf16 v[44:47], v[170:173], v[202:205], v[44:47]
	v_mfma_f32_16x16x32_bf16 v[36:39], v[162:165], v[210:213], v[36:39]
	v_mfma_f32_16x16x32_bf16 v[28:31], v[170:173], v[210:213], v[28:31]
	v_mfma_f32_16x16x32_bf16 v[20:23], v[162:165], v[218:221], v[20:23]
	v_mfma_f32_16x16x32_bf16 v[12:15], v[170:173], v[218:221], v[12:15]
	v_mfma_f32_16x16x32_bf16 v[48:51], v[174:177], v[190:193], v[48:51]
	v_mfma_f32_16x16x32_bf16 v[40:43], v[182:185], v[190:193], v[40:43]
	v_mfma_f32_16x16x32_bf16 v[32:35], v[174:177], v[198:201], v[32:35]
	v_mfma_f32_16x16x32_bf16 v[24:27], v[182:185], v[198:201], v[24:27]
	v_mfma_f32_16x16x32_bf16 v[16:19], v[174:177], v[206:209], v[16:19]
	v_mfma_f32_16x16x32_bf16 v[8:11], v[182:185], v[206:209], v[8:11]
	v_mfma_f32_16x16x32_bf16 v[4:7], v[174:177], v[214:217], v[4:7]
	v_mfma_f32_16x16x32_bf16 v[0:3], v[182:185], v[214:217], v[0:3]
	v_mfma_f32_16x16x32_bf16 v[48:51], v[178:181], v[194:197], v[48:51]
	v_mfma_f32_16x16x32_bf16 v[40:43], v[186:189], v[194:197], v[40:43]
	v_mfma_f32_16x16x32_bf16 v[32:35], v[178:181], v[202:205], v[32:35]
	v_mfma_f32_16x16x32_bf16 v[24:27], v[186:189], v[202:205], v[24:27]
	v_mfma_f32_16x16x32_bf16 v[16:19], v[178:181], v[210:213], v[16:19]
	v_mfma_f32_16x16x32_bf16 v[8:11], v[186:189], v[210:213], v[8:11]
	v_mfma_f32_16x16x32_bf16 v[4:7], v[178:181], v[218:221], v[4:7]
	v_mfma_f32_16x16x32_bf16 v[0:3], v[186:189], v[218:221], v[0:3]
	s_setprio 0
	s_barrier
	s_add_i32 s90, s90, 2
	s_add_u32 s88, s88, 0x100
	s_addc_u32 s89, s89, 0
	s_cmpk_gt_u32 s90, 0x55
	s_mov_b64 s[56:57], s[58:59]
	s_cbranch_scc0 .LBB0_1804
	s_and_b64 vcc, exec, s[52:53]
	s_cbranch_vccz .LBB0_1807
	s_barrier
